# MFMA issue order within each 16-MFMA block: astat (one operand held for 4 consecutive MFMAs)
# baseline (speedup 1.0000x reference)
.LBB0_197:
	s_ashr_i32 s47, s46, 31
	ds_read_b128 v[18:21], v190
	ds_read_b128 v[22:25], v190 offset:1024
	ds_read_b128 v[26:29], v190 offset:2048
	ds_read_b128 v[30:33], v190 offset:3072
	ds_read_b128 v[2:5], v190 offset:16384
	ds_read_b128 v[6:9], v190 offset:17408
	ds_read_b128 v[10:13], v190 offset:18432
	ds_read_b128 v[14:17], v190 offset:19456
	s_lshl_b64 s[8:9], s[46:47], 20
	s_add_u32 s48, s22, s8
	s_addc_u32 s49, s23, s9
	s_and_b64 s[8:9], s[2:3], exec
	s_cselect_b32 s47, s49, s73
	s_cselect_b32 s70, s48, s72
	s_ashr_i32 s45, s44, 31
	s_lshl_b64 s[8:9], s[44:45], 20
	s_add_u32 s50, s27, s8
	s_addc_u32 s51, s68, s9
	s_and_b64 s[8:9], s[2:3], exec
	s_cselect_b32 s45, s51, s55
	s_cselect_b32 s71, s50, s54
	s_add_u32 s8, s72, 0x80080
	s_addc_u32 s9, s73, 0
	s_mov_b32 m0, s92
	v_lshl_add_u64 v[216:217], s[8:9], 0, v[164:165]
	ds_read_b128 v[180:183], v191
	ds_read_b128 v[184:187], v191 offset:1024
	ds_read_b128 v[192:195], v191 offset:2048
	ds_read_b128 v[196:199], v191 offset:3072
	ds_read_b128 v[200:203], v191 offset:4096
	ds_read_b128 v[204:207], v191 offset:5120
	ds_read_b128 v[208:211], v191 offset:6144
	ds_read_b128 v[212:215], v191 offset:7168
	global_load_lds_dwordx4 v[216:217], off
	v_lshl_add_u64 v[216:217], s[8:9], 0, v[168:169]
	s_mov_b32 m0, s93
	s_nop 0
	global_load_lds_dwordx4 v[216:217], off
	s_waitcnt vmcnt(8)
	s_waitcnt lgkmcnt(0)
	s_barrier
	s_setprio 1
	s_waitcnt lgkmcnt(0)
	v_mfma_scale_f32_16x16x128_f8f6f4 v[158:161], v[18:25], v[180:187], 0, v189, v189 op_sel_hi:[0,0,0]
	v_mfma_scale_f32_16x16x128_f8f6f4 v[154:157], v[26:33], v[180:187], 0, v189, v189 op_sel_hi:[0,0,0]
	v_mfma_scale_f32_16x16x128_f8f6f4 v[122:125], v[10:17], v[180:187], 0, v189, v189 op_sel_hi:[0,0,0]
	v_mfma_scale_f32_16x16x128_f8f6f4 v[126:129], v[2:9], v[180:187], 0, v189, v189 op_sel_hi:[0,0,0]
	v_mfma_scale_f32_16x16x128_f8f6f4 v[118:121], v[2:9], v[192:199], 0, v189, v189 op_sel_hi:[0,0,0]
	v_mfma_scale_f32_16x16x128_f8f6f4 v[114:117], v[10:17], v[192:199], 0, v189, v189 op_sel_hi:[0,0,0]
	v_mfma_scale_f32_16x16x128_f8f6f4 v[146:149], v[26:33], v[192:199], 0, v189, v189 op_sel_hi:[0,0,0]
	v_mfma_scale_f32_16x16x128_f8f6f4 v[150:153], v[18:25], v[192:199], 0, v189, v189 op_sel_hi:[0,0,0]
	s_setprio 0
	s_setprio 1
	v_mfma_scale_f32_16x16x128_f8f6f4 v[142:145], v[18:25], v[200:207], 0, v189, v189 op_sel_hi:[0,0,0]
	v_mfma_scale_f32_16x16x128_f8f6f4 v[138:141], v[26:33], v[200:207], 0, v189, v189 op_sel_hi:[0,0,0]
	v_mfma_scale_f32_16x16x128_f8f6f4 v[106:109], v[10:17], v[200:207], 0, v189, v189 op_sel_hi:[0,0,0]
	v_mfma_scale_f32_16x16x128_f8f6f4 v[110:113], v[2:9], v[200:207], 0, v189, v189 op_sel_hi:[0,0,0]
	v_mfma_scale_f32_16x16x128_f8f6f4 v[102:105], v[2:9], v[208:215], 0, v189, v189 op_sel_hi:[0,0,0]
	v_mfma_scale_f32_16x16x128_f8f6f4 v[98:101], v[10:17], v[208:215], 0, v189, v189 op_sel_hi:[0,0,0]
	v_mfma_scale_f32_16x16x128_f8f6f4 v[130:133], v[26:33], v[208:215], 0, v189, v189 op_sel_hi:[0,0,0]
	v_mfma_scale_f32_16x16x128_f8f6f4 v[134:137], v[18:25], v[208:215], 0, v189, v189 op_sel_hi:[0,0,0]
	s_setprio 0
	s_barrier
	v_lshl_add_u64 v[180:181], s[54:55], 0, v[166:167]
	s_mov_b32 m0, s77
	v_lshl_add_u64 v[182:183], v[180:181], 0, s[16:17]
	ds_read_b128 v[192:195], v191 offset:16384
	ds_read_b128 v[196:199], v191 offset:17408
	ds_read_b128 v[200:203], v191 offset:18432
	ds_read_b128 v[204:207], v191 offset:19456
	ds_read_b128 v[208:211], v191 offset:20480
	ds_read_b128 v[212:215], v191 offset:21504
	ds_read_b128 v[216:219], v191 offset:22528
	ds_read_b128 v[220:223], v191 offset:23552
	global_load_lds_dwordx4 v[182:183], off
	v_lshl_add_u64 v[182:183], s[54:55], 0, v[170:171]
	s_add_u32 s8, s54, 0x80100
	v_lshl_add_u64 v[184:185], v[182:183], 0, s[16:17]
	s_mov_b32 m0, s78
	s_addc_u32 s9, s55, 0
	global_load_lds_dwordx4 v[184:185], off
	v_lshl_add_u64 v[184:185], s[8:9], 0, v[166:167]
	s_mov_b32 m0, s79
	s_nop 0
	global_load_lds_dwordx4 v[184:185], off
	v_lshl_add_u64 v[184:185], s[8:9], 0, v[170:171]
	s_mov_b32 m0, s80
	s_nop 0
	global_load_lds_dwordx4 v[184:185], off
	v_lshl_add_u64 v[184:185], s[72:73], 0, v[164:165]
	v_lshl_add_u64 v[186:187], v[184:185], 0, s[16:17]
	s_mov_b32 m0, s53
	s_nop 0
	global_load_lds_dwordx4 v[186:187], off
	v_lshl_add_u64 v[186:187], s[72:73], 0, v[168:169]
	v_lshl_add_u64 v[224:225], v[186:187], 0, s[16:17]
	s_mov_b32 m0, s81
	s_nop 0
	global_load_lds_dwordx4 v[224:225], off
	s_waitcnt vmcnt(8)
	s_waitcnt lgkmcnt(0)
	s_barrier
	s_setprio 1
	s_waitcnt lgkmcnt(0)
	v_mfma_scale_f32_16x16x128_f8f6f4 v[94:97], v[18:25], v[192:199], 0, v189, v189 op_sel_hi:[0,0,0]
	v_mfma_scale_f32_16x16x128_f8f6f4 v[90:93], v[26:33], v[192:199], 0, v189, v189 op_sel_hi:[0,0,0]
	v_mfma_scale_f32_16x16x128_f8f6f4 v[58:61], v[10:17], v[192:199], 0, v189, v189 op_sel_hi:[0,0,0]
	v_mfma_scale_f32_16x16x128_f8f6f4 v[62:65], v[2:9], v[192:199], 0, v189, v189 op_sel_hi:[0,0,0]
	v_mfma_scale_f32_16x16x128_f8f6f4 v[54:57], v[2:9], v[200:207], 0, v189, v189 op_sel_hi:[0,0,0]
	v_mfma_scale_f32_16x16x128_f8f6f4 v[50:53], v[10:17], v[200:207], 0, v189, v189 op_sel_hi:[0,0,0]
	v_mfma_scale_f32_16x16x128_f8f6f4 v[82:85], v[26:33], v[200:207], 0, v189, v189 op_sel_hi:[0,0,0]
	v_mfma_scale_f32_16x16x128_f8f6f4 v[86:89], v[18:25], v[200:207], 0, v189, v189 op_sel_hi:[0,0,0]
	s_setprio 0
	s_setprio 1
	v_mfma_scale_f32_16x16x128_f8f6f4 v[78:81], v[18:25], v[208:215], 0, v189, v189 op_sel_hi:[0,0,0]
	v_mfma_scale_f32_16x16x128_f8f6f4 v[74:77], v[26:33], v[208:215], 0, v189, v189 op_sel_hi:[0,0,0]
	v_mfma_scale_f32_16x16x128_f8f6f4 v[42:45], v[10:17], v[208:215], 0, v189, v189 op_sel_hi:[0,0,0]
	v_mfma_scale_f32_16x16x128_f8f6f4 v[46:49], v[2:9], v[208:215], 0, v189, v189 op_sel_hi:[0,0,0]
	v_mfma_scale_f32_16x16x128_f8f6f4 v[38:41], v[2:9], v[216:223], 0, v189, v189 op_sel_hi:[0,0,0]
	v_mfma_scale_f32_16x16x128_f8f6f4 v[34:37], v[10:17], v[216:223], 0, v189, v189 op_sel_hi:[0,0,0]
	v_mfma_scale_f32_16x16x128_f8f6f4 v[66:69], v[26:33], v[216:223], 0, v189, v189 op_sel_hi:[0,0,0]
	v_mfma_scale_f32_16x16x128_f8f6f4 v[70:73], v[18:25], v[216:223], 0, v189, v189 op_sel_hi:[0,0,0]
	s_setprio 0
	s_barrier
	ds_read_b128 v[18:21], v190 offset:32768
	ds_read_b128 v[22:25], v190 offset:33792
	ds_read_b128 v[26:29], v190 offset:34816
	ds_read_b128 v[30:33], v190 offset:35840
	ds_read_b128 v[2:5], v190 offset:49152
	ds_read_b128 v[6:9], v190 offset:50176
	ds_read_b128 v[10:13], v190 offset:51200
	ds_read_b128 v[14:17], v190 offset:52224
	s_add_u32 s8, s72, 0x80100
	s_addc_u32 s9, s73, 0
	s_mov_b32 m0, s82
	v_lshl_add_u64 v[224:225], s[8:9], 0, v[164:165]
	ds_read_b128 v[192:195], v191 offset:32768
	ds_read_b128 v[196:199], v191 offset:33792
	ds_read_b128 v[200:203], v191 offset:34816
	ds_read_b128 v[204:207], v191 offset:35840
	ds_read_b128 v[208:211], v191 offset:36864
	ds_read_b128 v[212:215], v191 offset:37888
	ds_read_b128 v[216:219], v191 offset:38912
	ds_read_b128 v[220:223], v191 offset:39936
	global_load_lds_dwordx4 v[224:225], off
	v_lshl_add_u64 v[224:225], s[8:9], 0, v[168:169]
	s_mov_b32 m0, s83
	s_nop 0
	global_load_lds_dwordx4 v[224:225], off
	s_waitcnt vmcnt(8)
	s_waitcnt lgkmcnt(0)
	s_barrier
	s_setprio 1
	s_waitcnt lgkmcnt(0)
	v_mfma_scale_f32_16x16x128_f8f6f4 v[158:161], v[18:25], v[192:199], v[158:161], v189, v189 op_sel_hi:[0,0,0]
	v_mfma_scale_f32_16x16x128_f8f6f4 v[154:157], v[26:33], v[192:199], v[154:157], v189, v189 op_sel_hi:[0,0,0]
	v_mfma_scale_f32_16x16x128_f8f6f4 v[122:125], v[10:17], v[192:199], v[122:125], v189, v189 op_sel_hi:[0,0,0]
	v_mfma_scale_f32_16x16x128_f8f6f4 v[126:129], v[2:9], v[192:199], v[126:129], v189, v189 op_sel_hi:[0,0,0]
	v_mfma_scale_f32_16x16x128_f8f6f4 v[118:121], v[2:9], v[200:207], v[118:121], v189, v189 op_sel_hi:[0,0,0]
	v_mfma_scale_f32_16x16x128_f8f6f4 v[114:117], v[10:17], v[200:207], v[114:117], v189, v189 op_sel_hi:[0,0,0]
	v_mfma_scale_f32_16x16x128_f8f6f4 v[146:149], v[26:33], v[200:207], v[146:149], v189, v189 op_sel_hi:[0,0,0]
	v_mfma_scale_f32_16x16x128_f8f6f4 v[150:153], v[18:25], v[200:207], v[150:153], v189, v189 op_sel_hi:[0,0,0]
	s_setprio 0
	s_setprio 1
	v_mfma_scale_f32_16x16x128_f8f6f4 v[142:145], v[18:25], v[208:215], v[142:145], v189, v189 op_sel_hi:[0,0,0]
	v_mfma_scale_f32_16x16x128_f8f6f4 v[138:141], v[26:33], v[208:215], v[138:141], v189, v189 op_sel_hi:[0,0,0]
	v_mfma_scale_f32_16x16x128_f8f6f4 v[106:109], v[10:17], v[208:215], v[106:109], v189, v189 op_sel_hi:[0,0,0]
	v_mfma_scale_f32_16x16x128_f8f6f4 v[110:113], v[2:9], v[208:215], v[110:113], v189, v189 op_sel_hi:[0,0,0]
	v_mfma_scale_f32_16x16x128_f8f6f4 v[102:105], v[2:9], v[216:223], v[102:105], v189, v189 op_sel_hi:[0,0,0]
	v_mfma_scale_f32_16x16x128_f8f6f4 v[98:101], v[10:17], v[216:223], v[98:101], v189, v189 op_sel_hi:[0,0,0]
	v_mfma_scale_f32_16x16x128_f8f6f4 v[130:133], v[26:33], v[216:223], v[130:133], v189, v189 op_sel_hi:[0,0,0]
	v_mfma_scale_f32_16x16x128_f8f6f4 v[134:137], v[18:25], v[216:223], v[134:137], v189, v189 op_sel_hi:[0,0,0]
	s_setprio 0
	s_barrier
	s_mov_b32 m0, s86
	v_lshl_add_u64 v[180:181], v[180:181], 0, s[20:21]
	s_add_u32 s8, s54, 0x80180
	ds_read_b128 v[192:195], v191 offset:49152
	ds_read_b128 v[196:199], v191 offset:50176
	ds_read_b128 v[200:203], v191 offset:51200
	ds_read_b128 v[204:207], v191 offset:52224
	ds_read_b128 v[208:211], v191 offset:53248
	ds_read_b128 v[212:215], v191 offset:54272
	ds_read_b128 v[216:219], v191 offset:55296
	ds_read_b128 v[220:223], v191 offset:56320
	global_load_lds_dwordx4 v[180:181], off
	v_lshl_add_u64 v[180:181], v[182:183], 0, s[20:21]
	s_mov_b32 m0, s87
	s_addc_u32 s9, s55, 0
	global_load_lds_dwordx4 v[180:181], off
	v_lshl_add_u64 v[180:181], s[8:9], 0, v[166:167]
	s_mov_b32 m0, s90
	s_nop 0
	global_load_lds_dwordx4 v[180:181], off
	v_lshl_add_u64 v[180:181], s[8:9], 0, v[170:171]
	s_mov_b32 m0, s91
	s_nop 0
	global_load_lds_dwordx4 v[180:181], off
	v_lshl_add_u64 v[180:181], v[184:185], 0, s[20:21]
	s_mov_b32 m0, s88
	s_nop 0
	global_load_lds_dwordx4 v[180:181], off
	v_lshl_add_u64 v[180:181], v[186:187], 0, s[20:21]
	s_mov_b32 m0, s89
	s_nop 0
	global_load_lds_dwordx4 v[180:181], off
	s_waitcnt vmcnt(8)
	s_waitcnt lgkmcnt(0)
	s_barrier
	s_setprio 1
	s_waitcnt lgkmcnt(0)
	v_mfma_scale_f32_16x16x128_f8f6f4 v[94:97], v[18:25], v[192:199], v[94:97], v189, v189 op_sel_hi:[0,0,0]
	v_mfma_scale_f32_16x16x128_f8f6f4 v[90:93], v[26:33], v[192:199], v[90:93], v189, v189 op_sel_hi:[0,0,0]
	v_mfma_scale_f32_16x16x128_f8f6f4 v[58:61], v[10:17], v[192:199], v[58:61], v189, v189 op_sel_hi:[0,0,0]
	v_mfma_scale_f32_16x16x128_f8f6f4 v[62:65], v[2:9], v[192:199], v[62:65], v189, v189 op_sel_hi:[0,0,0]
	v_mfma_scale_f32_16x16x128_f8f6f4 v[54:57], v[2:9], v[200:207], v[54:57], v189, v189 op_sel_hi:[0,0,0]
	v_mfma_scale_f32_16x16x128_f8f6f4 v[50:53], v[10:17], v[200:207], v[50:53], v189, v189 op_sel_hi:[0,0,0]
	v_mfma_scale_f32_16x16x128_f8f6f4 v[82:85], v[26:33], v[200:207], v[82:85], v189, v189 op_sel_hi:[0,0,0]
	v_mfma_scale_f32_16x16x128_f8f6f4 v[86:89], v[18:25], v[200:207], v[86:89], v189, v189 op_sel_hi:[0,0,0]
	s_setprio 0
	s_setprio 1
	v_mfma_scale_f32_16x16x128_f8f6f4 v[78:81], v[18:25], v[208:215], v[78:81], v189, v189 op_sel_hi:[0,0,0]
	v_mfma_scale_f32_16x16x128_f8f6f4 v[74:77], v[26:33], v[208:215], v[74:77], v189, v189 op_sel_hi:[0,0,0]
	v_mfma_scale_f32_16x16x128_f8f6f4 v[42:45], v[10:17], v[208:215], v[42:45], v189, v189 op_sel_hi:[0,0,0]
	v_mfma_scale_f32_16x16x128_f8f6f4 v[46:49], v[2:9], v[208:215], v[46:49], v189, v189 op_sel_hi:[0,0,0]
	v_mfma_scale_f32_16x16x128_f8f6f4 v[38:41], v[2:9], v[216:223], v[38:41], v189, v189 op_sel_hi:[0,0,0]
	v_mfma_scale_f32_16x16x128_f8f6f4 v[34:37], v[10:17], v[216:223], v[34:37], v189, v189 op_sel_hi:[0,0,0]
	v_mfma_scale_f32_16x16x128_f8f6f4 v[66:69], v[26:33], v[216:223], v[66:69], v189, v189 op_sel_hi:[0,0,0]
	v_mfma_scale_f32_16x16x128_f8f6f4 v[70:73], v[18:25], v[216:223], v[70:73], v189, v189 op_sel_hi:[0,0,0]
	s_setprio 0
	s_barrier
	s_add_u32 s72, s72, 0x80180
	s_addc_u32 s73, s73, 0
	s_add_u32 s8, s54, 0x200
	s_addc_u32 s9, s55, 0
	s_mov_b32 s62, 0
.LBB0_198:
	ds_read_b128 v[2:5], v190
	ds_read_b128 v[6:9], v190 offset:1024
	ds_read_b128 v[18:21], v190 offset:2048
	ds_read_b128 v[22:25], v190 offset:3072
	ds_read_b128 v[26:29], v190 offset:16384
	ds_read_b128 v[30:33], v190 offset:17408
	ds_read_b128 v[180:183], v190 offset:18432
	ds_read_b128 v[184:187], v190 offset:19456
	s_add_u32 s54, s72, 0xfff80080
	s_addc_u32 s55, s73, -1
	s_cmp_eq_u32 s62, 28
	s_cselect_b32 s75, s47, s55
	s_cselect_b32 s74, s70, s54
	s_cselect_b32 s55, s45, s9
	s_cselect_b32 s54, s71, s8
	s_mov_b32 m0, s92
	v_lshl_add_u64 v[216:217], s[72:73], 0, v[172:173]
	ds_read_b128 v[10:13], v191
	ds_read_b128 v[14:17], v191 offset:1024
	ds_read_b128 v[192:195], v191 offset:2048
	ds_read_b128 v[196:199], v191 offset:3072
	ds_read_b128 v[200:203], v191 offset:4096
	ds_read_b128 v[204:207], v191 offset:5120
	ds_read_b128 v[208:211], v191 offset:6144
	ds_read_b128 v[212:215], v191 offset:7168
	global_load_lds_dwordx4 v[216:217], off
	v_lshl_add_u64 v[216:217], s[72:73], 0, v[174:175]
	s_mov_b32 m0, s93
	s_nop 0
	global_load_lds_dwordx4 v[216:217], off
	s_waitcnt vmcnt(8)
	s_waitcnt lgkmcnt(0)
	s_barrier
	s_setprio 1
	s_waitcnt lgkmcnt(0)
	v_mfma_scale_f32_16x16x128_f8f6f4 v[158:161], v[2:9], v[10:17], v[158:161], v189, v189 op_sel_hi:[0,0,0]
	v_mfma_scale_f32_16x16x128_f8f6f4 v[154:157], v[18:25], v[10:17], v[154:157], v189, v189 op_sel_hi:[0,0,0]
	v_mfma_scale_f32_16x16x128_f8f6f4 v[122:125], v[180:187], v[10:17], v[122:125], v189, v189 op_sel_hi:[0,0,0]
	v_mfma_scale_f32_16x16x128_f8f6f4 v[126:129], v[26:33], v[10:17], v[126:129], v189, v189 op_sel_hi:[0,0,0]
	v_mfma_scale_f32_16x16x128_f8f6f4 v[118:121], v[26:33], v[192:199], v[118:121], v189, v189 op_sel_hi:[0,0,0]
	v_mfma_scale_f32_16x16x128_f8f6f4 v[114:117], v[180:187], v[192:199], v[114:117], v189, v189 op_sel_hi:[0,0,0]
	v_mfma_scale_f32_16x16x128_f8f6f4 v[146:149], v[18:25], v[192:199], v[146:149], v189, v189 op_sel_hi:[0,0,0]
	v_mfma_scale_f32_16x16x128_f8f6f4 v[150:153], v[2:9], v[192:199], v[150:153], v189, v189 op_sel_hi:[0,0,0]
	s_setprio 0
	s_setprio 1
	v_mfma_scale_f32_16x16x128_f8f6f4 v[142:145], v[2:9], v[200:207], v[142:145], v189, v189 op_sel_hi:[0,0,0]
	v_mfma_scale_f32_16x16x128_f8f6f4 v[138:141], v[18:25], v[200:207], v[138:141], v189, v189 op_sel_hi:[0,0,0]
	v_mfma_scale_f32_16x16x128_f8f6f4 v[106:109], v[180:187], v[200:207], v[106:109], v189, v189 op_sel_hi:[0,0,0]
	v_mfma_scale_f32_16x16x128_f8f6f4 v[110:113], v[26:33], v[200:207], v[110:113], v189, v189 op_sel_hi:[0,0,0]
	v_mfma_scale_f32_16x16x128_f8f6f4 v[102:105], v[26:33], v[208:215], v[102:105], v189, v189 op_sel_hi:[0,0,0]
	v_mfma_scale_f32_16x16x128_f8f6f4 v[98:101], v[180:187], v[208:215], v[98:101], v189, v189 op_sel_hi:[0,0,0]
	v_mfma_scale_f32_16x16x128_f8f6f4 v[130:133], v[18:25], v[208:215], v[130:133], v189, v189 op_sel_hi:[0,0,0]
	v_mfma_scale_f32_16x16x128_f8f6f4 v[134:137], v[2:9], v[208:215], v[134:137], v189, v189 op_sel_hi:[0,0,0]
	s_setprio 0
	s_barrier
	s_mov_b32 m0, s77
	v_lshl_add_u64 v[10:11], s[54:55], 0, v[166:167]
	s_add_u32 vcc_lo, s54, 0x80000
	ds_read_b128 v[192:195], v191 offset:16384
	ds_read_b128 v[196:199], v191 offset:17408
	ds_read_b128 v[200:203], v191 offset:18432
	ds_read_b128 v[204:207], v191 offset:19456
	ds_read_b128 v[208:211], v191 offset:20480
	ds_read_b128 v[212:215], v191 offset:21504
	ds_read_b128 v[216:219], v191 offset:22528
	ds_read_b128 v[220:223], v191 offset:23552
	global_load_lds_dwordx4 v[10:11], off
	v_lshl_add_u64 v[12:13], s[54:55], 0, v[170:171]
	s_mov_b32 m0, s78
	s_addc_u32 vcc_hi, s55, 0
	global_load_lds_dwordx4 v[12:13], off
	v_lshl_add_u64 v[14:15], vcc, 0, v[166:167]
	s_mov_b32 m0, s79
	v_lshl_add_u64 v[16:17], s[74:75], 0, v[168:169]
	global_load_lds_dwordx4 v[14:15], off
	v_lshl_add_u64 v[14:15], vcc, 0, v[170:171]
	s_mov_b32 m0, s80
	s_nop 0
	global_load_lds_dwordx4 v[14:15], off
	v_lshl_add_u64 v[14:15], s[74:75], 0, v[164:165]
	s_mov_b32 m0, s53
	s_nop 0
	global_load_lds_dwordx4 v[14:15], off
	s_mov_b32 m0, s81
	s_nop 0
	global_load_lds_dwordx4 v[16:17], off
	s_waitcnt vmcnt(8)
	s_waitcnt lgkmcnt(0)
	s_barrier
	s_setprio 1
	s_waitcnt lgkmcnt(0)
	v_mfma_scale_f32_16x16x128_f8f6f4 v[94:97], v[2:9], v[192:199], v[94:97], v189, v189 op_sel_hi:[0,0,0]
	v_mfma_scale_f32_16x16x128_f8f6f4 v[90:93], v[18:25], v[192:199], v[90:93], v189, v189 op_sel_hi:[0,0,0]
	v_mfma_scale_f32_16x16x128_f8f6f4 v[58:61], v[180:187], v[192:199], v[58:61], v189, v189 op_sel_hi:[0,0,0]
	v_mfma_scale_f32_16x16x128_f8f6f4 v[62:65], v[26:33], v[192:199], v[62:65], v189, v189 op_sel_hi:[0,0,0]
	v_mfma_scale_f32_16x16x128_f8f6f4 v[54:57], v[26:33], v[200:207], v[54:57], v189, v189 op_sel_hi:[0,0,0]
	v_mfma_scale_f32_16x16x128_f8f6f4 v[50:53], v[180:187], v[200:207], v[50:53], v189, v189 op_sel_hi:[0,0,0]
	v_mfma_scale_f32_16x16x128_f8f6f4 v[82:85], v[18:25], v[200:207], v[82:85], v189, v189 op_sel_hi:[0,0,0]
	v_mfma_scale_f32_16x16x128_f8f6f4 v[86:89], v[2:9], v[200:207], v[86:89], v189, v189 op_sel_hi:[0,0,0]
	s_setprio 0
	s_setprio 1
	v_mfma_scale_f32_16x16x128_f8f6f4 v[78:81], v[2:9], v[208:215], v[78:81], v189, v189 op_sel_hi:[0,0,0]
	v_mfma_scale_f32_16x16x128_f8f6f4 v[74:77], v[18:25], v[208:215], v[74:77], v189, v189 op_sel_hi:[0,0,0]
	v_mfma_scale_f32_16x16x128_f8f6f4 v[42:45], v[180:187], v[208:215], v[42:45], v189, v189 op_sel_hi:[0,0,0]
	v_mfma_scale_f32_16x16x128_f8f6f4 v[46:49], v[26:33], v[208:215], v[46:49], v189, v189 op_sel_hi:[0,0,0]
	v_mfma_scale_f32_16x16x128_f8f6f4 v[38:41], v[26:33], v[216:223], v[38:41], v189, v189 op_sel_hi:[0,0,0]
	v_mfma_scale_f32_16x16x128_f8f6f4 v[34:37], v[180:187], v[216:223], v[34:37], v189, v189 op_sel_hi:[0,0,0]
	v_mfma_scale_f32_16x16x128_f8f6f4 v[66:69], v[18:25], v[216:223], v[66:69], v189, v189 op_sel_hi:[0,0,0]
	v_mfma_scale_f32_16x16x128_f8f6f4 v[70:73], v[2:9], v[216:223], v[70:73], v189, v189 op_sel_hi:[0,0,0]
	s_setprio 0
	s_barrier
	ds_read_b128 v[18:21], v190 offset:32768
	ds_read_b128 v[22:25], v190 offset:33792
	ds_read_b128 v[26:29], v190 offset:34816
	ds_read_b128 v[30:33], v190 offset:35840
	ds_read_b128 v[2:5], v190 offset:49152
	ds_read_b128 v[6:9], v190 offset:50176
	ds_read_b128 v[180:183], v190 offset:51200
	ds_read_b128 v[184:187], v190 offset:52224
	s_add_u32 s74, s74, 0x80000
	s_addc_u32 s75, s75, 0
	s_mov_b32 m0, s82
	v_lshl_add_u64 v[224:225], s[74:75], 0, v[164:165]
	ds_read_b128 v[192:195], v191 offset:32768
	ds_read_b128 v[196:199], v191 offset:33792
	ds_read_b128 v[200:203], v191 offset:34816
	ds_read_b128 v[204:207], v191 offset:35840
	ds_read_b128 v[208:211], v191 offset:36864
	ds_read_b128 v[212:215], v191 offset:37888
	ds_read_b128 v[216:219], v191 offset:38912
	ds_read_b128 v[220:223], v191 offset:39936
	global_load_lds_dwordx4 v[224:225], off
	v_lshl_add_u64 v[224:225], s[74:75], 0, v[168:169]
	s_mov_b32 m0, s83
	s_nop 0
	global_load_lds_dwordx4 v[224:225], off
	s_waitcnt vmcnt(8)
	s_waitcnt lgkmcnt(0)
	s_barrier
	s_setprio 1
	s_waitcnt lgkmcnt(0)
	v_mfma_scale_f32_16x16x128_f8f6f4 v[158:161], v[18:25], v[192:199], v[158:161], v189, v189 op_sel_hi:[0,0,0]
	v_mfma_scale_f32_16x16x128_f8f6f4 v[154:157], v[26:33], v[192:199], v[154:157], v189, v189 op_sel_hi:[0,0,0]
	v_mfma_scale_f32_16x16x128_f8f6f4 v[122:125], v[180:187], v[192:199], v[122:125], v189, v189 op_sel_hi:[0,0,0]
	v_mfma_scale_f32_16x16x128_f8f6f4 v[126:129], v[2:9], v[192:199], v[126:129], v189, v189 op_sel_hi:[0,0,0]
	v_mfma_scale_f32_16x16x128_f8f6f4 v[118:121], v[2:9], v[200:207], v[118:121], v189, v189 op_sel_hi:[0,0,0]
	v_mfma_scale_f32_16x16x128_f8f6f4 v[114:117], v[180:187], v[200:207], v[114:117], v189, v189 op_sel_hi:[0,0,0]
	v_mfma_scale_f32_16x16x128_f8f6f4 v[146:149], v[26:33], v[200:207], v[146:149], v189, v189 op_sel_hi:[0,0,0]
	v_mfma_scale_f32_16x16x128_f8f6f4 v[150:153], v[18:25], v[200:207], v[150:153], v189, v189 op_sel_hi:[0,0,0]
	s_setprio 0
	s_setprio 1
	v_mfma_scale_f32_16x16x128_f8f6f4 v[142:145], v[18:25], v[208:215], v[142:145], v189, v189 op_sel_hi:[0,0,0]
	v_mfma_scale_f32_16x16x128_f8f6f4 v[138:141], v[26:33], v[208:215], v[138:141], v189, v189 op_sel_hi:[0,0,0]
	v_mfma_scale_f32_16x16x128_f8f6f4 v[106:109], v[180:187], v[208:215], v[106:109], v189, v189 op_sel_hi:[0,0,0]
	v_mfma_scale_f32_16x16x128_f8f6f4 v[110:113], v[2:9], v[208:215], v[110:113], v189, v189 op_sel_hi:[0,0,0]
	v_mfma_scale_f32_16x16x128_f8f6f4 v[102:105], v[2:9], v[216:223], v[102:105], v189, v189 op_sel_hi:[0,0,0]
	v_mfma_scale_f32_16x16x128_f8f6f4 v[98:101], v[180:187], v[216:223], v[98:101], v189, v189 op_sel_hi:[0,0,0]
	v_mfma_scale_f32_16x16x128_f8f6f4 v[130:133], v[26:33], v[216:223], v[130:133], v189, v189 op_sel_hi:[0,0,0]
	v_mfma_scale_f32_16x16x128_f8f6f4 v[134:137], v[18:25], v[216:223], v[134:137], v189, v189 op_sel_hi:[0,0,0]
	s_setprio 0
	s_barrier
	s_mov_b32 m0, s86
	v_lshl_add_u64 v[10:11], v[10:11], 0, s[4:5]
	s_add_u32 s54, s54, 0x80080
	ds_read_b128 v[192:195], v191 offset:49152
	ds_read_b128 v[196:199], v191 offset:50176
	ds_read_b128 v[200:203], v191 offset:51200
	ds_read_b128 v[204:207], v191 offset:52224
	ds_read_b128 v[208:211], v191 offset:53248
	ds_read_b128 v[212:215], v191 offset:54272
	ds_read_b128 v[216:219], v191 offset:55296
	ds_read_b128 v[220:223], v191 offset:56320
	global_load_lds_dwordx4 v[10:11], off
	v_lshl_add_u64 v[10:11], v[12:13], 0, s[4:5]
	s_mov_b32 m0, s87
	s_addc_u32 s55, s55, 0
	global_load_lds_dwordx4 v[10:11], off
	v_lshl_add_u64 v[10:11], s[54:55], 0, v[166:167]
	s_mov_b32 m0, s90
	s_nop 0
	global_load_lds_dwordx4 v[10:11], off
	v_lshl_add_u64 v[10:11], s[54:55], 0, v[170:171]
	s_mov_b32 m0, s91
	s_nop 0
	global_load_lds_dwordx4 v[10:11], off
	v_lshl_add_u64 v[10:11], v[14:15], 0, s[4:5]
	s_mov_b32 m0, s88
	s_nop 0
	global_load_lds_dwordx4 v[10:11], off
	v_lshl_add_u64 v[10:11], v[16:17], 0, s[4:5]
	s_mov_b32 m0, s89
	s_nop 0
	global_load_lds_dwordx4 v[10:11], off
	s_waitcnt vmcnt(8)
	s_waitcnt lgkmcnt(0)
	s_barrier
	s_setprio 1
	s_waitcnt lgkmcnt(0)
	v_mfma_scale_f32_16x16x128_f8f6f4 v[94:97], v[18:25], v[192:199], v[94:97], v189, v189 op_sel_hi:[0,0,0]
	v_mfma_scale_f32_16x16x128_f8f6f4 v[90:93], v[26:33], v[192:199], v[90:93], v189, v189 op_sel_hi:[0,0,0]
	v_mfma_scale_f32_16x16x128_f8f6f4 v[58:61], v[180:187], v[192:199], v[58:61], v189, v189 op_sel_hi:[0,0,0]
	v_mfma_scale_f32_16x16x128_f8f6f4 v[62:65], v[2:9], v[192:199], v[62:65], v189, v189 op_sel_hi:[0,0,0]
	v_mfma_scale_f32_16x16x128_f8f6f4 v[54:57], v[2:9], v[200:207], v[54:57], v189, v189 op_sel_hi:[0,0,0]
	v_mfma_scale_f32_16x16x128_f8f6f4 v[50:53], v[180:187], v[200:207], v[50:53], v189, v189 op_sel_hi:[0,0,0]
	v_mfma_scale_f32_16x16x128_f8f6f4 v[82:85], v[26:33], v[200:207], v[82:85], v189, v189 op_sel_hi:[0,0,0]
	v_mfma_scale_f32_16x16x128_f8f6f4 v[86:89], v[18:25], v[200:207], v[86:89], v189, v189 op_sel_hi:[0,0,0]
	s_setprio 0
	s_setprio 1
	v_mfma_scale_f32_16x16x128_f8f6f4 v[78:81], v[18:25], v[208:215], v[78:81], v189, v189 op_sel_hi:[0,0,0]
	v_mfma_scale_f32_16x16x128_f8f6f4 v[74:77], v[26:33], v[208:215], v[74:77], v189, v189 op_sel_hi:[0,0,0]
	v_mfma_scale_f32_16x16x128_f8f6f4 v[42:45], v[180:187], v[208:215], v[42:45], v189, v189 op_sel_hi:[0,0,0]
	v_mfma_scale_f32_16x16x128_f8f6f4 v[46:49], v[2:9], v[208:215], v[46:49], v189, v189 op_sel_hi:[0,0,0]
	v_mfma_scale_f32_16x16x128_f8f6f4 v[38:41], v[2:9], v[216:223], v[38:41], v189, v189 op_sel_hi:[0,0,0]
	v_mfma_scale_f32_16x16x128_f8f6f4 v[34:37], v[180:187], v[216:223], v[34:37], v189, v189 op_sel_hi:[0,0,0]
	v_mfma_scale_f32_16x16x128_f8f6f4 v[66:69], v[26:33], v[216:223], v[66:69], v189, v189 op_sel_hi:[0,0,0]
	v_mfma_scale_f32_16x16x128_f8f6f4 v[70:73], v[18:25], v[216:223], v[70:73], v189, v189 op_sel_hi:[0,0,0]
	s_setprio 0
	s_barrier
	s_add_i32 s62, s62, 2
	s_add_u32 s72, s72, 0x100
	s_addc_u32 s73, s73, 0
	s_add_u32 s8, s8, 0x100
	s_addc_u32 s9, s9, 0
	s_cmp_gt_u32 s62, 29
	s_cbranch_scc0 .LBB0_198
	s_and_b64 vcc, exec, s[6:7]
	s_cbranch_vccz .LBB0_201
	s_barrier

.LBB0_282:
	ds_read_b128 v[2:5], v187
	ds_read_b128 v[6:9], v187 offset:1024
	ds_read_b128 v[174:177], v187 offset:2048
	ds_read_b128 v[178:181], v187 offset:3072
	ds_read_b128 v[190:193], v187 offset:16384
	ds_read_b128 v[194:197], v187 offset:17408
	ds_read_b128 v[198:201], v187 offset:18432
	ds_read_b128 v[202:205], v187 offset:19456
	s_add_u32 s49, s52, 0x100
	s_addc_u32 s71, s53, 0
	s_and_b64 s[62:63], s[54:55], exec
	s_cselect_b32 s73, s1, s71
	s_cselect_b32 s72, s0, s49
	s_add_u32 s49, s50, 0x100
	s_addc_u32 s62, s51, 0
	s_and_b64 s[54:55], s[54:55], exec
	s_cselect_b32 s55, s5, s62
	s_cselect_b32 s54, s4, s49
	s_add_u32 s62, s52, 0x158080
	s_addc_u32 s63, s53, 0
	s_add_i32 s49, s33, 0xc000
	v_lshl_add_u64 v[182:183], s[62:63], 0, v[154:155]
	s_mov_b32 m0, s49
	s_add_i32 s71, s33, 0xe000
	ds_read_b128 v[206:209], v188
	ds_read_b128 v[210:213], v188 offset:1024
	ds_read_b128 v[214:217], v188 offset:2048
	ds_read_b128 v[218:221], v188 offset:3072
	ds_read_b128 v[222:225], v188 offset:4096
	ds_read_b128 v[226:229], v188 offset:5120
	ds_read_b128 v[230:233], v188 offset:6144
	ds_read_b128 v[234:237], v188 offset:7168
	global_load_lds_dwordx4 v[182:183], off
	v_lshl_add_u64 v[182:183], s[62:63], 0, v[158:159]
	s_mov_b32 m0, s71
	s_nop 0
	global_load_lds_dwordx4 v[182:183], off
	s_waitcnt vmcnt(8)
	s_waitcnt lgkmcnt(0)
	s_barrier
	s_setprio 1
	s_waitcnt lgkmcnt(0)
	v_mfma_scale_f32_16x16x128_f8f6f4 v[134:137], v[2:9], v[206:213], 0, v186, v186 op_sel_hi:[0,0,0]
	v_mfma_scale_f32_16x16x128_f8f6f4 v[130:133], v[174:181], v[206:213], 0, v186, v186 op_sel_hi:[0,0,0]
	v_mfma_scale_f32_16x16x128_f8f6f4 v[98:101], v[198:205], v[206:213], 0, v186, v186 op_sel_hi:[0,0,0]
	v_mfma_scale_f32_16x16x128_f8f6f4 v[102:105], v[190:197], v[206:213], 0, v186, v186 op_sel_hi:[0,0,0]
	v_mfma_scale_f32_16x16x128_f8f6f4 v[94:97], v[190:197], v[214:221], 0, v186, v186 op_sel_hi:[0,0,0]
	v_mfma_scale_f32_16x16x128_f8f6f4 v[90:93], v[198:205], v[214:221], 0, v186, v186 op_sel_hi:[0,0,0]
	v_mfma_scale_f32_16x16x128_f8f6f4 v[122:125], v[174:181], v[214:221], 0, v186, v186 op_sel_hi:[0,0,0]
	v_mfma_scale_f32_16x16x128_f8f6f4 v[126:129], v[2:9], v[214:221], 0, v186, v186 op_sel_hi:[0,0,0]
	s_setprio 0
	s_setprio 1
	v_mfma_scale_f32_16x16x128_f8f6f4 v[118:121], v[2:9], v[222:229], 0, v186, v186 op_sel_hi:[0,0,0]
	v_mfma_scale_f32_16x16x128_f8f6f4 v[114:117], v[174:181], v[222:229], 0, v186, v186 op_sel_hi:[0,0,0]
	v_mfma_scale_f32_16x16x128_f8f6f4 v[82:85], v[198:205], v[222:229], 0, v186, v186 op_sel_hi:[0,0,0]
	v_mfma_scale_f32_16x16x128_f8f6f4 v[86:89], v[190:197], v[222:229], 0, v186, v186 op_sel_hi:[0,0,0]
	v_mfma_scale_f32_16x16x128_f8f6f4 v[78:81], v[190:197], v[230:237], 0, v186, v186 op_sel_hi:[0,0,0]
	v_mfma_scale_f32_16x16x128_f8f6f4 v[74:77], v[198:205], v[230:237], 0, v186, v186 op_sel_hi:[0,0,0]
	v_mfma_scale_f32_16x16x128_f8f6f4 v[106:109], v[174:181], v[230:237], 0, v186, v186 op_sel_hi:[0,0,0]
	v_mfma_scale_f32_16x16x128_f8f6f4 v[110:113], v[2:9], v[230:237], 0, v186, v186 op_sel_hi:[0,0,0]
	s_setprio 0
	s_barrier
	s_mov_b32 m0, s47
	v_lshl_add_u64 v[182:183], s[54:55], 0, v[156:157]
	s_add_u32 s62, s54, 0x158000
	ds_read_b128 v[206:209], v188 offset:16384
	ds_read_b128 v[210:213], v188 offset:17408
	ds_read_b128 v[214:217], v188 offset:18432
	ds_read_b128 v[218:221], v188 offset:19456
	ds_read_b128 v[222:225], v188 offset:20480
	ds_read_b128 v[226:229], v188 offset:21504
	ds_read_b128 v[230:233], v188 offset:22528
	ds_read_b128 v[234:237], v188 offset:23552
	global_load_lds_dwordx4 v[182:183], off
	v_lshl_add_u64 v[238:239], s[54:55], 0, v[160:161]
	s_mov_b32 m0, s68
	s_addc_u32 s63, s55, 0
	global_load_lds_dwordx4 v[238:239], off
	v_lshl_add_u64 v[242:243], s[62:63], 0, v[156:157]
	s_mov_b32 m0, s69
	v_lshl_add_u64 v[244:245], s[72:73], 0, v[158:159]
	global_load_lds_dwordx4 v[242:243], off
	v_lshl_add_u64 v[242:243], s[62:63], 0, v[160:161]
	s_mov_b32 m0, s74
	s_nop 0
	global_load_lds_dwordx4 v[242:243], off
	v_lshl_add_u64 v[242:243], s[72:73], 0, v[154:155]
	s_mov_b32 m0, s33
	s_nop 0
	global_load_lds_dwordx4 v[242:243], off
	s_mov_b32 m0, s75
	s_nop 0
	global_load_lds_dwordx4 v[244:245], off
	s_waitcnt vmcnt(8)
	s_waitcnt lgkmcnt(0)
	s_barrier
	s_setprio 1
	s_waitcnt lgkmcnt(0)
	v_mfma_scale_f32_16x16x128_f8f6f4 v[70:73], v[2:9], v[206:213], 0, v186, v186 op_sel_hi:[0,0,0]
	v_mfma_scale_f32_16x16x128_f8f6f4 v[66:69], v[174:181], v[206:213], 0, v186, v186 op_sel_hi:[0,0,0]
	v_mfma_scale_f32_16x16x128_f8f6f4 v[34:37], v[198:205], v[206:213], 0, v186, v186 op_sel_hi:[0,0,0]
	v_mfma_scale_f32_16x16x128_f8f6f4 v[38:41], v[190:197], v[206:213], 0, v186, v186 op_sel_hi:[0,0,0]
	v_mfma_scale_f32_16x16x128_f8f6f4 v[30:33], v[190:197], v[214:221], 0, v186, v186 op_sel_hi:[0,0,0]
	v_mfma_scale_f32_16x16x128_f8f6f4 v[26:29], v[198:205], v[214:221], 0, v186, v186 op_sel_hi:[0,0,0]
	v_mfma_scale_f32_16x16x128_f8f6f4 v[58:61], v[174:181], v[214:221], 0, v186, v186 op_sel_hi:[0,0,0]
	v_mfma_scale_f32_16x16x128_f8f6f4 v[62:65], v[2:9], v[214:221], 0, v186, v186 op_sel_hi:[0,0,0]
	s_setprio 0
	s_setprio 1
	v_mfma_scale_f32_16x16x128_f8f6f4 v[54:57], v[2:9], v[222:229], 0, v186, v186 op_sel_hi:[0,0,0]
	v_mfma_scale_f32_16x16x128_f8f6f4 v[50:53], v[174:181], v[222:229], 0, v186, v186 op_sel_hi:[0,0,0]
	v_mfma_scale_f32_16x16x128_f8f6f4 v[18:21], v[198:205], v[222:229], 0, v186, v186 op_sel_hi:[0,0,0]
	v_mfma_scale_f32_16x16x128_f8f6f4 v[22:25], v[190:197], v[222:229], 0, v186, v186 op_sel_hi:[0,0,0]
	v_mfma_scale_f32_16x16x128_f8f6f4 v[14:17], v[190:197], v[230:237], 0, v186, v186 op_sel_hi:[0,0,0]
	v_mfma_scale_f32_16x16x128_f8f6f4 v[10:13], v[198:205], v[230:237], 0, v186, v186 op_sel_hi:[0,0,0]
	v_mfma_scale_f32_16x16x128_f8f6f4 v[42:45], v[174:181], v[230:237], 0, v186, v186 op_sel_hi:[0,0,0]
	v_mfma_scale_f32_16x16x128_f8f6f4 v[46:49], v[2:9], v[230:237], 0, v186, v186 op_sel_hi:[0,0,0]
	s_setprio 0
	s_barrier
	ds_read_b128 v[2:5], v187 offset:32768
	ds_read_b128 v[6:9], v187 offset:33792
	ds_read_b128 v[174:177], v187 offset:34816
	ds_read_b128 v[178:181], v187 offset:35840
	ds_read_b128 v[190:193], v187 offset:49152
	ds_read_b128 v[194:197], v187 offset:50176
	ds_read_b128 v[198:201], v187 offset:51200
	ds_read_b128 v[202:205], v187 offset:52224
	s_add_u32 s62, s72, 0x158000
	s_addc_u32 s63, s73, 0
	s_mov_b32 m0, s76
	v_lshl_add_u64 v[246:247], s[62:63], 0, v[154:155]
	ds_read_b128 v[206:209], v188 offset:32768
	ds_read_b128 v[210:213], v188 offset:33792
	ds_read_b128 v[214:217], v188 offset:34816
	ds_read_b128 v[218:221], v188 offset:35840
	ds_read_b128 v[222:225], v188 offset:36864
	ds_read_b128 v[226:229], v188 offset:37888
	ds_read_b128 v[230:233], v188 offset:38912
	ds_read_b128 v[234:237], v188 offset:39936
	global_load_lds_dwordx4 v[246:247], off
	v_lshl_add_u64 v[246:247], s[62:63], 0, v[158:159]
	s_mov_b32 m0, s77
	s_nop 0
	global_load_lds_dwordx4 v[246:247], off
	s_waitcnt vmcnt(8)
	s_waitcnt lgkmcnt(0)
	s_barrier
	s_setprio 1
	s_waitcnt lgkmcnt(0)
	v_mfma_scale_f32_16x16x128_f8f6f4 v[134:137], v[2:9], v[206:213], v[134:137], v186, v186 op_sel_hi:[0,0,0]
	v_mfma_scale_f32_16x16x128_f8f6f4 v[130:133], v[174:181], v[206:213], v[130:133], v186, v186 op_sel_hi:[0,0,0]
	v_mfma_scale_f32_16x16x128_f8f6f4 v[98:101], v[198:205], v[206:213], v[98:101], v186, v186 op_sel_hi:[0,0,0]
	v_mfma_scale_f32_16x16x128_f8f6f4 v[102:105], v[190:197], v[206:213], v[102:105], v186, v186 op_sel_hi:[0,0,0]
	v_mfma_scale_f32_16x16x128_f8f6f4 v[94:97], v[190:197], v[214:221], v[94:97], v186, v186 op_sel_hi:[0,0,0]
	v_mfma_scale_f32_16x16x128_f8f6f4 v[90:93], v[198:205], v[214:221], v[90:93], v186, v186 op_sel_hi:[0,0,0]
	v_mfma_scale_f32_16x16x128_f8f6f4 v[122:125], v[174:181], v[214:221], v[122:125], v186, v186 op_sel_hi:[0,0,0]
	v_mfma_scale_f32_16x16x128_f8f6f4 v[126:129], v[2:9], v[214:221], v[126:129], v186, v186 op_sel_hi:[0,0,0]
	s_setprio 0
	s_setprio 1
	v_mfma_scale_f32_16x16x128_f8f6f4 v[118:121], v[2:9], v[222:229], v[118:121], v186, v186 op_sel_hi:[0,0,0]
	v_mfma_scale_f32_16x16x128_f8f6f4 v[114:117], v[174:181], v[222:229], v[114:117], v186, v186 op_sel_hi:[0,0,0]
	v_mfma_scale_f32_16x16x128_f8f6f4 v[82:85], v[198:205], v[222:229], v[82:85], v186, v186 op_sel_hi:[0,0,0]
	v_mfma_scale_f32_16x16x128_f8f6f4 v[86:89], v[190:197], v[222:229], v[86:89], v186, v186 op_sel_hi:[0,0,0]
	v_mfma_scale_f32_16x16x128_f8f6f4 v[78:81], v[190:197], v[230:237], v[78:81], v186, v186 op_sel_hi:[0,0,0]
	v_mfma_scale_f32_16x16x128_f8f6f4 v[74:77], v[198:205], v[230:237], v[74:77], v186, v186 op_sel_hi:[0,0,0]
	v_mfma_scale_f32_16x16x128_f8f6f4 v[106:109], v[174:181], v[230:237], v[106:109], v186, v186 op_sel_hi:[0,0,0]
	v_mfma_scale_f32_16x16x128_f8f6f4 v[110:113], v[2:9], v[230:237], v[110:113], v186, v186 op_sel_hi:[0,0,0]
	s_setprio 0
	s_barrier
	s_mov_b32 m0, s83
	v_lshl_add_u64 v[182:183], v[182:183], 0, s[26:27]
	s_add_u32 s54, s54, 0x158080
	ds_read_b128 v[206:209], v188 offset:49152
	ds_read_b128 v[210:213], v188 offset:50176
	ds_read_b128 v[214:217], v188 offset:51200
	ds_read_b128 v[218:221], v188 offset:52224
	ds_read_b128 v[222:225], v188 offset:53248
	ds_read_b128 v[226:229], v188 offset:54272
	ds_read_b128 v[230:233], v188 offset:55296
	ds_read_b128 v[234:237], v188 offset:56320
	global_load_lds_dwordx4 v[182:183], off
	v_lshl_add_u64 v[182:183], v[238:239], 0, s[26:27]
	s_mov_b32 m0, s84
	s_addc_u32 s55, s55, 0
	global_load_lds_dwordx4 v[182:183], off
	v_lshl_add_u64 v[182:183], s[54:55], 0, v[156:157]
	s_mov_b32 m0, s87
	s_nop 0
	global_load_lds_dwordx4 v[182:183], off
	v_lshl_add_u64 v[182:183], s[54:55], 0, v[160:161]
	s_mov_b32 m0, s88
	s_nop 0
	global_load_lds_dwordx4 v[182:183], off
	v_lshl_add_u64 v[182:183], v[242:243], 0, s[26:27]
	s_mov_b32 m0, s85
	s_nop 0
	global_load_lds_dwordx4 v[182:183], off
	v_lshl_add_u64 v[182:183], v[244:245], 0, s[26:27]
	s_mov_b32 m0, s86
	s_nop 0
	global_load_lds_dwordx4 v[182:183], off
	s_waitcnt vmcnt(8)
	s_waitcnt lgkmcnt(0)
	s_barrier
	s_setprio 1
	s_waitcnt lgkmcnt(0)
	v_mfma_scale_f32_16x16x128_f8f6f4 v[70:73], v[2:9], v[206:213], v[70:73], v186, v186 op_sel_hi:[0,0,0]
	v_mfma_scale_f32_16x16x128_f8f6f4 v[66:69], v[174:181], v[206:213], v[66:69], v186, v186 op_sel_hi:[0,0,0]
	v_mfma_scale_f32_16x16x128_f8f6f4 v[34:37], v[198:205], v[206:213], v[34:37], v186, v186 op_sel_hi:[0,0,0]
	v_mfma_scale_f32_16x16x128_f8f6f4 v[38:41], v[190:197], v[206:213], v[38:41], v186, v186 op_sel_hi:[0,0,0]
	v_mfma_scale_f32_16x16x128_f8f6f4 v[30:33], v[190:197], v[214:221], v[30:33], v186, v186 op_sel_hi:[0,0,0]
	v_mfma_scale_f32_16x16x128_f8f6f4 v[26:29], v[198:205], v[214:221], v[26:29], v186, v186 op_sel_hi:[0,0,0]
	v_mfma_scale_f32_16x16x128_f8f6f4 v[58:61], v[174:181], v[214:221], v[58:61], v186, v186 op_sel_hi:[0,0,0]
	v_mfma_scale_f32_16x16x128_f8f6f4 v[62:65], v[2:9], v[214:221], v[62:65], v186, v186 op_sel_hi:[0,0,0]
	s_setprio 0
	s_setprio 1
	v_mfma_scale_f32_16x16x128_f8f6f4 v[54:57], v[2:9], v[222:229], v[54:57], v186, v186 op_sel_hi:[0,0,0]
	v_mfma_scale_f32_16x16x128_f8f6f4 v[50:53], v[174:181], v[222:229], v[50:53], v186, v186 op_sel_hi:[0,0,0]
	v_mfma_scale_f32_16x16x128_f8f6f4 v[18:21], v[198:205], v[222:229], v[18:21], v186, v186 op_sel_hi:[0,0,0]
	v_mfma_scale_f32_16x16x128_f8f6f4 v[22:25], v[190:197], v[222:229], v[22:25], v186, v186 op_sel_hi:[0,0,0]
	v_mfma_scale_f32_16x16x128_f8f6f4 v[14:17], v[190:197], v[230:237], v[14:17], v186, v186 op_sel_hi:[0,0,0]
	v_mfma_scale_f32_16x16x128_f8f6f4 v[10:13], v[198:205], v[230:237], v[10:13], v186, v186 op_sel_hi:[0,0,0]
	v_mfma_scale_f32_16x16x128_f8f6f4 v[42:45], v[174:181], v[230:237], v[42:45], v186, v186 op_sel_hi:[0,0,0]
	v_mfma_scale_f32_16x16x128_f8f6f4 v[46:49], v[2:9], v[230:237], v[46:49], v186, v186 op_sel_hi:[0,0,0]
	s_setprio 0
	s_barrier
	s_cmp_lt_u32 s95, 3
	s_cbranch_scc1 .LBB0_287
	s_add_u32 s54, s79, s9
	s_addc_u32 s55, s80, s8
	s_add_u32 s52, s52, 0x158180
	s_addc_u32 s53, s53, 0
	s_add_u32 s8, s50, 0x200
	v_lshl_add_u64 v[174:175], v[172:173], 2, s[54:55]
	s_addc_u32 s9, s51, 0
	s_mov_b32 s72, 4
	s_cmp_eq_u32 s95, s72
	s_cselect_b64 s[50:51], -1, 0
	s_cmp_lg_u32 s95, s72
	s_cbranch_scc1 .LBB0_285

.LBB0_285:
	ds_read_b128 v[2:5], v187
	ds_read_b128 v[6:9], v187 offset:1024
	ds_read_b128 v[190:193], v187 offset:2048
	ds_read_b128 v[194:197], v187 offset:3072
	ds_read_b128 v[198:201], v187 offset:16384
	ds_read_b128 v[202:205], v187 offset:17408
	ds_read_b128 v[206:209], v187 offset:18432
	ds_read_b128 v[210:213], v187 offset:19456
	s_add_u32 s54, s52, 0xffea8080
	s_addc_u32 s55, s53, -1
	s_and_b64 s[50:51], s[50:51], exec
	s_cselect_b32 s50, s4, s8
	s_cselect_b32 s55, s1, s55
	s_cselect_b32 s54, s0, s54
	s_cselect_b32 s51, s5, s9
	s_mov_b32 m0, s49
	v_lshl_add_u64 v[238:239], s[52:53], 0, v[162:163]
	ds_read_b128 v[176:179], v188
	ds_read_b128 v[180:183], v188 offset:1024
	ds_read_b128 v[214:217], v188 offset:2048
	ds_read_b128 v[218:221], v188 offset:3072
	ds_read_b128 v[222:225], v188 offset:4096
	ds_read_b128 v[226:229], v188 offset:5120
	ds_read_b128 v[230:233], v188 offset:6144
	ds_read_b128 v[234:237], v188 offset:7168
	global_load_lds_dwordx4 v[238:239], off
	v_lshl_add_u64 v[238:239], s[52:53], 0, v[164:165]
	s_mov_b32 m0, s71
	s_nop 0
	global_load_lds_dwordx4 v[238:239], off
	s_waitcnt vmcnt(8)
	s_waitcnt lgkmcnt(0)
	s_barrier
	s_setprio 1
	s_waitcnt lgkmcnt(0)
	v_mfma_scale_f32_16x16x128_f8f6f4 v[134:137], v[2:9], v[176:183], v[134:137], v186, v186 op_sel_hi:[0,0,0]
	v_mfma_scale_f32_16x16x128_f8f6f4 v[130:133], v[190:197], v[176:183], v[130:133], v186, v186 op_sel_hi:[0,0,0]
	v_mfma_scale_f32_16x16x128_f8f6f4 v[98:101], v[206:213], v[176:183], v[98:101], v186, v186 op_sel_hi:[0,0,0]
	v_mfma_scale_f32_16x16x128_f8f6f4 v[102:105], v[198:205], v[176:183], v[102:105], v186, v186 op_sel_hi:[0,0,0]
	v_mfma_scale_f32_16x16x128_f8f6f4 v[94:97], v[198:205], v[214:221], v[94:97], v186, v186 op_sel_hi:[0,0,0]
	v_mfma_scale_f32_16x16x128_f8f6f4 v[90:93], v[206:213], v[214:221], v[90:93], v186, v186 op_sel_hi:[0,0,0]
	v_mfma_scale_f32_16x16x128_f8f6f4 v[122:125], v[190:197], v[214:221], v[122:125], v186, v186 op_sel_hi:[0,0,0]
	v_mfma_scale_f32_16x16x128_f8f6f4 v[126:129], v[2:9], v[214:221], v[126:129], v186, v186 op_sel_hi:[0,0,0]
	s_setprio 0
	s_setprio 1
	v_mfma_scale_f32_16x16x128_f8f6f4 v[118:121], v[2:9], v[222:229], v[118:121], v186, v186 op_sel_hi:[0,0,0]
	v_mfma_scale_f32_16x16x128_f8f6f4 v[114:117], v[190:197], v[222:229], v[114:117], v186, v186 op_sel_hi:[0,0,0]
	v_mfma_scale_f32_16x16x128_f8f6f4 v[82:85], v[206:213], v[222:229], v[82:85], v186, v186 op_sel_hi:[0,0,0]
	v_mfma_scale_f32_16x16x128_f8f6f4 v[86:89], v[198:205], v[222:229], v[86:89], v186, v186 op_sel_hi:[0,0,0]
	v_mfma_scale_f32_16x16x128_f8f6f4 v[78:81], v[198:205], v[230:237], v[78:81], v186, v186 op_sel_hi:[0,0,0]
	v_mfma_scale_f32_16x16x128_f8f6f4 v[74:77], v[206:213], v[230:237], v[74:77], v186, v186 op_sel_hi:[0,0,0]
	v_mfma_scale_f32_16x16x128_f8f6f4 v[106:109], v[190:197], v[230:237], v[106:109], v186, v186 op_sel_hi:[0,0,0]
	v_mfma_scale_f32_16x16x128_f8f6f4 v[110:113], v[2:9], v[230:237], v[110:113], v186, v186 op_sel_hi:[0,0,0]
	s_setprio 0
	s_barrier
	s_mov_b32 m0, s47
	v_lshl_add_u64 v[176:177], s[50:51], 0, v[156:157]
	s_add_u32 s62, s50, 0x158000
	ds_read_b128 v[214:217], v188 offset:16384
	ds_read_b128 v[218:221], v188 offset:17408
	ds_read_b128 v[222:225], v188 offset:18432
	ds_read_b128 v[226:229], v188 offset:19456
	ds_read_b128 v[230:233], v188 offset:20480
	ds_read_b128 v[234:237], v188 offset:21504
	ds_read_b128 v[242:245], v188 offset:22528
	ds_read_b128 v[246:249], v188 offset:23552
	global_load_lds_dwordx4 v[176:177], off
	v_lshl_add_u64 v[178:179], s[50:51], 0, v[160:161]
	s_mov_b32 m0, s68
	s_addc_u32 s63, s51, 0
	global_load_lds_dwordx4 v[178:179], off
	v_lshl_add_u64 v[180:181], s[62:63], 0, v[156:157]
	s_mov_b32 m0, s69
	v_lshl_add_u64 v[182:183], s[54:55], 0, v[158:159]
	global_load_lds_dwordx4 v[180:181], off
	v_lshl_add_u64 v[180:181], s[62:63], 0, v[160:161]
	s_mov_b32 m0, s74
	s_nop 0
	global_load_lds_dwordx4 v[180:181], off
	v_lshl_add_u64 v[180:181], s[54:55], 0, v[154:155]
	s_mov_b32 m0, s33
	s_nop 0
	global_load_lds_dwordx4 v[180:181], off
	s_mov_b32 m0, s75
	s_nop 0
	global_load_lds_dwordx4 v[182:183], off
	s_waitcnt vmcnt(8)
	s_waitcnt lgkmcnt(0)
	s_barrier
	s_setprio 1
	s_waitcnt lgkmcnt(0)
	v_mfma_scale_f32_16x16x128_f8f6f4 v[70:73], v[2:9], v[214:221], v[70:73], v186, v186 op_sel_hi:[0,0,0]
	v_mfma_scale_f32_16x16x128_f8f6f4 v[66:69], v[190:197], v[214:221], v[66:69], v186, v186 op_sel_hi:[0,0,0]
	v_mfma_scale_f32_16x16x128_f8f6f4 v[34:37], v[206:213], v[214:221], v[34:37], v186, v186 op_sel_hi:[0,0,0]
	v_mfma_scale_f32_16x16x128_f8f6f4 v[38:41], v[198:205], v[214:221], v[38:41], v186, v186 op_sel_hi:[0,0,0]
	v_mfma_scale_f32_16x16x128_f8f6f4 v[30:33], v[198:205], v[222:229], v[30:33], v186, v186 op_sel_hi:[0,0,0]
	v_mfma_scale_f32_16x16x128_f8f6f4 v[26:29], v[206:213], v[222:229], v[26:29], v186, v186 op_sel_hi:[0,0,0]
	v_mfma_scale_f32_16x16x128_f8f6f4 v[58:61], v[190:197], v[222:229], v[58:61], v186, v186 op_sel_hi:[0,0,0]
	v_mfma_scale_f32_16x16x128_f8f6f4 v[62:65], v[2:9], v[222:229], v[62:65], v186, v186 op_sel_hi:[0,0,0]
	s_setprio 0
	s_setprio 1
	v_mfma_scale_f32_16x16x128_f8f6f4 v[54:57], v[2:9], v[230:237], v[54:57], v186, v186 op_sel_hi:[0,0,0]
	v_mfma_scale_f32_16x16x128_f8f6f4 v[50:53], v[190:197], v[230:237], v[50:53], v186, v186 op_sel_hi:[0,0,0]
	v_mfma_scale_f32_16x16x128_f8f6f4 v[18:21], v[206:213], v[230:237], v[18:21], v186, v186 op_sel_hi:[0,0,0]
	v_mfma_scale_f32_16x16x128_f8f6f4 v[22:25], v[198:205], v[230:237], v[22:25], v186, v186 op_sel_hi:[0,0,0]
	v_mfma_scale_f32_16x16x128_f8f6f4 v[14:17], v[198:205], v[242:249], v[14:17], v186, v186 op_sel_hi:[0,0,0]
	v_mfma_scale_f32_16x16x128_f8f6f4 v[10:13], v[206:213], v[242:249], v[10:13], v186, v186 op_sel_hi:[0,0,0]
	v_mfma_scale_f32_16x16x128_f8f6f4 v[42:45], v[190:197], v[242:249], v[42:45], v186, v186 op_sel_hi:[0,0,0]
	v_mfma_scale_f32_16x16x128_f8f6f4 v[46:49], v[2:9], v[242:249], v[46:49], v186, v186 op_sel_hi:[0,0,0]
	s_setprio 0
	s_barrier
	ds_read_b128 v[190:193], v187 offset:32768
	ds_read_b128 v[194:197], v187 offset:33792
	ds_read_b128 v[198:201], v187 offset:34816
	ds_read_b128 v[202:205], v187 offset:35840
	ds_read_b128 v[2:5], v187 offset:49152
	ds_read_b128 v[6:9], v187 offset:50176
	ds_read_b128 v[206:209], v187 offset:51200
	ds_read_b128 v[210:213], v187 offset:52224
	s_add_u32 s54, s54, 0x158000
	s_addc_u32 s55, s55, 0
	s_mov_b32 m0, s76
	v_lshl_add_u64 v[238:239], s[54:55], 0, v[154:155]
	ds_read_b128 v[214:217], v188 offset:32768
	ds_read_b128 v[218:221], v188 offset:33792
	ds_read_b128 v[222:225], v188 offset:34816
	ds_read_b128 v[226:229], v188 offset:35840
	ds_read_b128 v[230:233], v188 offset:36864
	ds_read_b128 v[234:237], v188 offset:37888
	ds_read_b128 v[242:245], v188 offset:38912
	ds_read_b128 v[246:249], v188 offset:39936
	global_load_lds_dwordx4 v[238:239], off
	v_lshl_add_u64 v[238:239], s[54:55], 0, v[158:159]
	s_mov_b32 m0, s77
	s_nop 0
	global_load_lds_dwordx4 v[238:239], off
	s_waitcnt vmcnt(8)
	s_waitcnt lgkmcnt(0)
	s_barrier
	s_setprio 1
	s_waitcnt lgkmcnt(0)
	v_mfma_scale_f32_16x16x128_f8f6f4 v[134:137], v[190:197], v[214:221], v[134:137], v186, v186 op_sel_hi:[0,0,0]
	v_mfma_scale_f32_16x16x128_f8f6f4 v[130:133], v[198:205], v[214:221], v[130:133], v186, v186 op_sel_hi:[0,0,0]
	v_mfma_scale_f32_16x16x128_f8f6f4 v[98:101], v[206:213], v[214:221], v[98:101], v186, v186 op_sel_hi:[0,0,0]
	v_mfma_scale_f32_16x16x128_f8f6f4 v[102:105], v[2:9], v[214:221], v[102:105], v186, v186 op_sel_hi:[0,0,0]
	v_mfma_scale_f32_16x16x128_f8f6f4 v[94:97], v[2:9], v[222:229], v[94:97], v186, v186 op_sel_hi:[0,0,0]
	v_mfma_scale_f32_16x16x128_f8f6f4 v[90:93], v[206:213], v[222:229], v[90:93], v186, v186 op_sel_hi:[0,0,0]
	v_mfma_scale_f32_16x16x128_f8f6f4 v[122:125], v[198:205], v[222:229], v[122:125], v186, v186 op_sel_hi:[0,0,0]
	v_mfma_scale_f32_16x16x128_f8f6f4 v[126:129], v[190:197], v[222:229], v[126:129], v186, v186 op_sel_hi:[0,0,0]
	s_setprio 0
	s_setprio 1
	v_mfma_scale_f32_16x16x128_f8f6f4 v[118:121], v[190:197], v[230:237], v[118:121], v186, v186 op_sel_hi:[0,0,0]
	v_mfma_scale_f32_16x16x128_f8f6f4 v[114:117], v[198:205], v[230:237], v[114:117], v186, v186 op_sel_hi:[0,0,0]
	v_mfma_scale_f32_16x16x128_f8f6f4 v[82:85], v[206:213], v[230:237], v[82:85], v186, v186 op_sel_hi:[0,0,0]
	v_mfma_scale_f32_16x16x128_f8f6f4 v[86:89], v[2:9], v[230:237], v[86:89], v186, v186 op_sel_hi:[0,0,0]
	v_mfma_scale_f32_16x16x128_f8f6f4 v[78:81], v[2:9], v[242:249], v[78:81], v186, v186 op_sel_hi:[0,0,0]
	v_mfma_scale_f32_16x16x128_f8f6f4 v[74:77], v[206:213], v[242:249], v[74:77], v186, v186 op_sel_hi:[0,0,0]
	v_mfma_scale_f32_16x16x128_f8f6f4 v[106:109], v[198:205], v[242:249], v[106:109], v186, v186 op_sel_hi:[0,0,0]
	v_mfma_scale_f32_16x16x128_f8f6f4 v[110:113], v[190:197], v[242:249], v[110:113], v186, v186 op_sel_hi:[0,0,0]
	s_setprio 0
	s_barrier
	s_mov_b32 m0, s83
	v_lshl_add_u64 v[176:177], v[176:177], 0, s[26:27]
	s_add_u32 s50, s50, 0x158080
	ds_read_b128 v[214:217], v188 offset:49152
	ds_read_b128 v[218:221], v188 offset:50176
	ds_read_b128 v[222:225], v188 offset:51200
	ds_read_b128 v[226:229], v188 offset:52224
	ds_read_b128 v[230:233], v188 offset:53248
	ds_read_b128 v[234:237], v188 offset:54272
	ds_read_b128 v[242:245], v188 offset:55296
	ds_read_b128 v[246:249], v188 offset:56320
	global_load_lds_dwordx4 v[176:177], off
	v_lshl_add_u64 v[176:177], v[178:179], 0, s[26:27]
	s_mov_b32 m0, s84
	s_addc_u32 s51, s51, 0
	global_load_lds_dwordx4 v[176:177], off
	v_lshl_add_u64 v[176:177], s[50:51], 0, v[156:157]
	s_mov_b32 m0, s87
	s_nop 0
	global_load_lds_dwordx4 v[176:177], off
	v_lshl_add_u64 v[176:177], s[50:51], 0, v[160:161]
	s_mov_b32 m0, s88
	s_nop 0
	global_load_lds_dwordx4 v[176:177], off
	v_lshl_add_u64 v[176:177], v[180:181], 0, s[26:27]
	s_mov_b32 m0, s85
	s_nop 0
	global_load_lds_dwordx4 v[176:177], off
	v_lshl_add_u64 v[176:177], v[182:183], 0, s[26:27]
	s_mov_b32 m0, s86
	s_nop 0
	global_load_lds_dwordx4 v[176:177], off
	s_waitcnt vmcnt(8)
	s_waitcnt lgkmcnt(0)
	s_barrier
	s_setprio 1
	s_waitcnt lgkmcnt(0)
	v_mfma_scale_f32_16x16x128_f8f6f4 v[70:73], v[190:197], v[214:221], v[70:73], v186, v186 op_sel_hi:[0,0,0]
	v_mfma_scale_f32_16x16x128_f8f6f4 v[66:69], v[198:205], v[214:221], v[66:69], v186, v186 op_sel_hi:[0,0,0]
	v_mfma_scale_f32_16x16x128_f8f6f4 v[34:37], v[206:213], v[214:221], v[34:37], v186, v186 op_sel_hi:[0,0,0]
	v_mfma_scale_f32_16x16x128_f8f6f4 v[38:41], v[2:9], v[214:221], v[38:41], v186, v186 op_sel_hi:[0,0,0]
	v_mfma_scale_f32_16x16x128_f8f6f4 v[30:33], v[2:9], v[222:229], v[30:33], v186, v186 op_sel_hi:[0,0,0]
	v_mfma_scale_f32_16x16x128_f8f6f4 v[26:29], v[206:213], v[222:229], v[26:29], v186, v186 op_sel_hi:[0,0,0]
	v_mfma_scale_f32_16x16x128_f8f6f4 v[58:61], v[198:205], v[222:229], v[58:61], v186, v186 op_sel_hi:[0,0,0]
	v_mfma_scale_f32_16x16x128_f8f6f4 v[62:65], v[190:197], v[222:229], v[62:65], v186, v186 op_sel_hi:[0,0,0]
	s_setprio 0
	s_setprio 1
	v_mfma_scale_f32_16x16x128_f8f6f4 v[54:57], v[190:197], v[230:237], v[54:57], v186, v186 op_sel_hi:[0,0,0]
	v_mfma_scale_f32_16x16x128_f8f6f4 v[50:53], v[198:205], v[230:237], v[50:53], v186, v186 op_sel_hi:[0,0,0]
	v_mfma_scale_f32_16x16x128_f8f6f4 v[18:21], v[206:213], v[230:237], v[18:21], v186, v186 op_sel_hi:[0,0,0]
	v_mfma_scale_f32_16x16x128_f8f6f4 v[22:25], v[2:9], v[230:237], v[22:25], v186, v186 op_sel_hi:[0,0,0]
	v_mfma_scale_f32_16x16x128_f8f6f4 v[14:17], v[2:9], v[242:249], v[14:17], v186, v186 op_sel_hi:[0,0,0]
	v_mfma_scale_f32_16x16x128_f8f6f4 v[10:13], v[206:213], v[242:249], v[10:13], v186, v186 op_sel_hi:[0,0,0]
	v_mfma_scale_f32_16x16x128_f8f6f4 v[42:45], v[198:205], v[242:249], v[42:45], v186, v186 op_sel_hi:[0,0,0]
	v_mfma_scale_f32_16x16x128_f8f6f4 v[46:49], v[190:197], v[242:249], v[46:49], v186, v186 op_sel_hi:[0,0,0]
	s_setprio 0
	s_barrier
	s_add_i32 s50, s72, 2
	s_add_u32 s52, s52, 0x100
	s_addc_u32 s53, s53, 0
	s_add_u32 s8, s8, 0x100
	s_addc_u32 s9, s9, 0
	s_cmp_ge_i32 s72, s95
	s_cbranch_scc1 .LBB0_287
	s_mov_b32 s72, s50
	s_cmp_eq_u32 s95, s72
	s_cselect_b64 s[50:51], -1, 0
	s_cmp_lg_u32 s95, s72
	s_cbranch_scc0 .LBB0_284
	s_branch .LBB0_285

.LBB0_437:
	s_ashr_i32 s47, s46, 31
	ds_read_b128 v[18:21], v200
	ds_read_b128 v[22:25], v200 offset:1024
	ds_read_b128 v[26:29], v200 offset:2048
	ds_read_b128 v[30:33], v200 offset:3072
	ds_read_b128 v[2:5], v200 offset:16384
	ds_read_b128 v[6:9], v200 offset:17408
	ds_read_b128 v[10:13], v200 offset:18432
	ds_read_b128 v[14:17], v200 offset:19456
	s_lshl_b64 s[8:9], s[46:47], 20
	s_add_u32 s48, s12, s8
	s_addc_u32 s49, s13, s9
	s_and_b64 s[8:9], s[2:3], exec
	s_cselect_b32 s47, s49, s73
	s_cselect_b32 s71, s48, s72
	s_ashr_i32 s45, s44, 31
	s_lshl_b64 s[8:9], s[44:45], 20
	s_add_u32 s50, s39, s8
	s_addc_u32 s51, s76, s9
	s_and_b64 s[8:9], s[2:3], exec
	s_cselect_b32 s45, s51, s55
	s_cselect_b32 s94, s50, s54
	s_add_u32 s8, s72, 0x80080
	s_addc_u32 s9, s73, 0
	s_mov_b32 m0, s33
	v_lshl_add_u64 v[226:227], s[8:9], 0, v[162:163]
	ds_read_b128 v[180:183], v201
	ds_read_b128 v[184:187], v201 offset:1024
	ds_read_b128 v[202:205], v201 offset:2048
	ds_read_b128 v[206:209], v201 offset:3072
	ds_read_b128 v[210:213], v201 offset:4096
	ds_read_b128 v[214:217], v201 offset:5120
	ds_read_b128 v[218:221], v201 offset:6144
	ds_read_b128 v[222:225], v201 offset:7168
	global_load_lds_dwordx4 v[226:227], off
	v_lshl_add_u64 v[226:227], s[8:9], 0, v[166:167]
	s_mov_b32 m0, s93
	s_nop 0
	global_load_lds_dwordx4 v[226:227], off
	s_waitcnt vmcnt(8)
	s_waitcnt lgkmcnt(0)
	s_barrier
	s_setprio 1
	s_waitcnt lgkmcnt(0)
	v_mfma_scale_f32_16x16x128_f8f6f4 v[158:161], v[18:25], v[180:187], 0, v199, v199 op_sel_hi:[0,0,0]
	v_mfma_scale_f32_16x16x128_f8f6f4 v[154:157], v[26:33], v[180:187], 0, v199, v199 op_sel_hi:[0,0,0]
	v_mfma_scale_f32_16x16x128_f8f6f4 v[122:125], v[10:17], v[180:187], 0, v199, v199 op_sel_hi:[0,0,0]
	v_mfma_scale_f32_16x16x128_f8f6f4 v[126:129], v[2:9], v[180:187], 0, v199, v199 op_sel_hi:[0,0,0]
	v_mfma_scale_f32_16x16x128_f8f6f4 v[118:121], v[2:9], v[202:209], 0, v199, v199 op_sel_hi:[0,0,0]
	v_mfma_scale_f32_16x16x128_f8f6f4 v[114:117], v[10:17], v[202:209], 0, v199, v199 op_sel_hi:[0,0,0]
	v_mfma_scale_f32_16x16x128_f8f6f4 v[146:149], v[26:33], v[202:209], 0, v199, v199 op_sel_hi:[0,0,0]
	v_mfma_scale_f32_16x16x128_f8f6f4 v[150:153], v[18:25], v[202:209], 0, v199, v199 op_sel_hi:[0,0,0]
	s_setprio 0
	s_setprio 1
	v_mfma_scale_f32_16x16x128_f8f6f4 v[142:145], v[18:25], v[210:217], 0, v199, v199 op_sel_hi:[0,0,0]
	v_mfma_scale_f32_16x16x128_f8f6f4 v[138:141], v[26:33], v[210:217], 0, v199, v199 op_sel_hi:[0,0,0]
	v_mfma_scale_f32_16x16x128_f8f6f4 v[106:109], v[10:17], v[210:217], 0, v199, v199 op_sel_hi:[0,0,0]
	v_mfma_scale_f32_16x16x128_f8f6f4 v[110:113], v[2:9], v[210:217], 0, v199, v199 op_sel_hi:[0,0,0]
	v_mfma_scale_f32_16x16x128_f8f6f4 v[102:105], v[2:9], v[218:225], 0, v199, v199 op_sel_hi:[0,0,0]
	v_mfma_scale_f32_16x16x128_f8f6f4 v[98:101], v[10:17], v[218:225], 0, v199, v199 op_sel_hi:[0,0,0]
	v_mfma_scale_f32_16x16x128_f8f6f4 v[130:133], v[26:33], v[218:225], 0, v199, v199 op_sel_hi:[0,0,0]
	v_mfma_scale_f32_16x16x128_f8f6f4 v[134:137], v[18:25], v[218:225], 0, v199, v199 op_sel_hi:[0,0,0]
	s_setprio 0
	s_barrier
	v_lshl_add_u64 v[180:181], s[54:55], 0, v[164:165]
	s_mov_b32 m0, s78
	v_lshl_add_u64 v[182:183], v[180:181], 0, s[26:27]
	ds_read_b128 v[202:205], v201 offset:16384
	ds_read_b128 v[206:209], v201 offset:17408
	ds_read_b128 v[210:213], v201 offset:18432
	ds_read_b128 v[214:217], v201 offset:19456
	ds_read_b128 v[218:221], v201 offset:20480
	ds_read_b128 v[222:225], v201 offset:21504
	ds_read_b128 v[226:229], v201 offset:22528
	ds_read_b128 v[230:233], v201 offset:23552
	global_load_lds_dwordx4 v[182:183], off
	v_lshl_add_u64 v[182:183], s[54:55], 0, v[168:169]
	s_add_u32 s8, s54, 0x80100
	v_lshl_add_u64 v[184:185], v[182:183], 0, s[26:27]
	s_mov_b32 m0, s79
	s_addc_u32 s9, s55, 0
	global_load_lds_dwordx4 v[184:185], off
	v_lshl_add_u64 v[184:185], s[8:9], 0, v[164:165]
	s_mov_b32 m0, s80
	s_nop 0
	global_load_lds_dwordx4 v[184:185], off
	v_lshl_add_u64 v[184:185], s[8:9], 0, v[168:169]
	s_mov_b32 m0, s81
	s_nop 0
	global_load_lds_dwordx4 v[184:185], off
	v_lshl_add_u64 v[184:185], s[72:73], 0, v[162:163]
	v_lshl_add_u64 v[186:187], v[184:185], 0, s[26:27]
	s_mov_b32 m0, s53
	s_nop 0
	global_load_lds_dwordx4 v[186:187], off
	v_lshl_add_u64 v[186:187], s[72:73], 0, v[166:167]
	v_lshl_add_u64 v[234:235], v[186:187], 0, s[26:27]
	s_mov_b32 m0, s82
	s_nop 0
	global_load_lds_dwordx4 v[234:235], off
	s_waitcnt vmcnt(8)
	s_waitcnt lgkmcnt(0)
	s_barrier
	s_setprio 1
	s_waitcnt lgkmcnt(0)
	v_mfma_scale_f32_16x16x128_f8f6f4 v[94:97], v[18:25], v[202:209], 0, v199, v199 op_sel_hi:[0,0,0]
	v_mfma_scale_f32_16x16x128_f8f6f4 v[90:93], v[26:33], v[202:209], 0, v199, v199 op_sel_hi:[0,0,0]
	v_mfma_scale_f32_16x16x128_f8f6f4 v[58:61], v[10:17], v[202:209], 0, v199, v199 op_sel_hi:[0,0,0]
	v_mfma_scale_f32_16x16x128_f8f6f4 v[62:65], v[2:9], v[202:209], 0, v199, v199 op_sel_hi:[0,0,0]
	v_mfma_scale_f32_16x16x128_f8f6f4 v[54:57], v[2:9], v[210:217], 0, v199, v199 op_sel_hi:[0,0,0]
	v_mfma_scale_f32_16x16x128_f8f6f4 v[50:53], v[10:17], v[210:217], 0, v199, v199 op_sel_hi:[0,0,0]
	v_mfma_scale_f32_16x16x128_f8f6f4 v[82:85], v[26:33], v[210:217], 0, v199, v199 op_sel_hi:[0,0,0]
	v_mfma_scale_f32_16x16x128_f8f6f4 v[86:89], v[18:25], v[210:217], 0, v199, v199 op_sel_hi:[0,0,0]
	s_setprio 0
	s_setprio 1
	v_mfma_scale_f32_16x16x128_f8f6f4 v[78:81], v[18:25], v[218:225], 0, v199, v199 op_sel_hi:[0,0,0]
	v_mfma_scale_f32_16x16x128_f8f6f4 v[74:77], v[26:33], v[218:225], 0, v199, v199 op_sel_hi:[0,0,0]
	v_mfma_scale_f32_16x16x128_f8f6f4 v[42:45], v[10:17], v[218:225], 0, v199, v199 op_sel_hi:[0,0,0]
	v_mfma_scale_f32_16x16x128_f8f6f4 v[46:49], v[2:9], v[218:225], 0, v199, v199 op_sel_hi:[0,0,0]
	v_mfma_scale_f32_16x16x128_f8f6f4 v[38:41], v[2:9], v[226:233], 0, v199, v199 op_sel_hi:[0,0,0]
	v_mfma_scale_f32_16x16x128_f8f6f4 v[34:37], v[10:17], v[226:233], 0, v199, v199 op_sel_hi:[0,0,0]
	v_mfma_scale_f32_16x16x128_f8f6f4 v[66:69], v[26:33], v[226:233], 0, v199, v199 op_sel_hi:[0,0,0]
	v_mfma_scale_f32_16x16x128_f8f6f4 v[70:73], v[18:25], v[226:233], 0, v199, v199 op_sel_hi:[0,0,0]
	s_setprio 0
	s_barrier
	ds_read_b128 v[18:21], v200 offset:32768
	ds_read_b128 v[22:25], v200 offset:33792
	ds_read_b128 v[26:29], v200 offset:34816
	ds_read_b128 v[30:33], v200 offset:35840
	ds_read_b128 v[2:5], v200 offset:49152
	ds_read_b128 v[6:9], v200 offset:50176
	ds_read_b128 v[10:13], v200 offset:51200
	ds_read_b128 v[14:17], v200 offset:52224
	s_add_u32 s8, s72, 0x80100
	s_addc_u32 s9, s73, 0
	s_mov_b32 m0, s83
	v_lshl_add_u64 v[234:235], s[8:9], 0, v[162:163]
	ds_read_b128 v[202:205], v201 offset:32768
	ds_read_b128 v[206:209], v201 offset:33792
	ds_read_b128 v[210:213], v201 offset:34816
	ds_read_b128 v[214:217], v201 offset:35840
	ds_read_b128 v[218:221], v201 offset:36864
	ds_read_b128 v[222:225], v201 offset:37888
	ds_read_b128 v[226:229], v201 offset:38912
	ds_read_b128 v[230:233], v201 offset:39936
	global_load_lds_dwordx4 v[234:235], off
	v_lshl_add_u64 v[234:235], s[8:9], 0, v[166:167]
	s_mov_b32 m0, s84
	s_nop 0
	global_load_lds_dwordx4 v[234:235], off
	s_waitcnt vmcnt(8)
	s_waitcnt lgkmcnt(0)
	s_barrier
	s_setprio 1
	s_waitcnt lgkmcnt(0)
	v_mfma_scale_f32_16x16x128_f8f6f4 v[158:161], v[18:25], v[202:209], v[158:161], v199, v199 op_sel_hi:[0,0,0]
	v_mfma_scale_f32_16x16x128_f8f6f4 v[154:157], v[26:33], v[202:209], v[154:157], v199, v199 op_sel_hi:[0,0,0]
	v_mfma_scale_f32_16x16x128_f8f6f4 v[122:125], v[10:17], v[202:209], v[122:125], v199, v199 op_sel_hi:[0,0,0]
	v_mfma_scale_f32_16x16x128_f8f6f4 v[126:129], v[2:9], v[202:209], v[126:129], v199, v199 op_sel_hi:[0,0,0]
	v_mfma_scale_f32_16x16x128_f8f6f4 v[118:121], v[2:9], v[210:217], v[118:121], v199, v199 op_sel_hi:[0,0,0]
	v_mfma_scale_f32_16x16x128_f8f6f4 v[114:117], v[10:17], v[210:217], v[114:117], v199, v199 op_sel_hi:[0,0,0]
	v_mfma_scale_f32_16x16x128_f8f6f4 v[146:149], v[26:33], v[210:217], v[146:149], v199, v199 op_sel_hi:[0,0,0]
	v_mfma_scale_f32_16x16x128_f8f6f4 v[150:153], v[18:25], v[210:217], v[150:153], v199, v199 op_sel_hi:[0,0,0]
	s_setprio 0
	s_setprio 1
	v_mfma_scale_f32_16x16x128_f8f6f4 v[142:145], v[18:25], v[218:225], v[142:145], v199, v199 op_sel_hi:[0,0,0]
	v_mfma_scale_f32_16x16x128_f8f6f4 v[138:141], v[26:33], v[218:225], v[138:141], v199, v199 op_sel_hi:[0,0,0]
	v_mfma_scale_f32_16x16x128_f8f6f4 v[106:109], v[10:17], v[218:225], v[106:109], v199, v199 op_sel_hi:[0,0,0]
	v_mfma_scale_f32_16x16x128_f8f6f4 v[110:113], v[2:9], v[218:225], v[110:113], v199, v199 op_sel_hi:[0,0,0]
	v_mfma_scale_f32_16x16x128_f8f6f4 v[102:105], v[2:9], v[226:233], v[102:105], v199, v199 op_sel_hi:[0,0,0]
	v_mfma_scale_f32_16x16x128_f8f6f4 v[98:101], v[10:17], v[226:233], v[98:101], v199, v199 op_sel_hi:[0,0,0]
	v_mfma_scale_f32_16x16x128_f8f6f4 v[130:133], v[26:33], v[226:233], v[130:133], v199, v199 op_sel_hi:[0,0,0]
	v_mfma_scale_f32_16x16x128_f8f6f4 v[134:137], v[18:25], v[226:233], v[134:137], v199, v199 op_sel_hi:[0,0,0]
	s_setprio 0
	s_barrier
	s_mov_b32 m0, s87
	v_lshl_add_u64 v[180:181], v[180:181], 0, s[36:37]
	s_add_u32 s8, s54, 0x80180
	ds_read_b128 v[202:205], v201 offset:49152
	ds_read_b128 v[206:209], v201 offset:50176
	ds_read_b128 v[210:213], v201 offset:51200
	ds_read_b128 v[214:217], v201 offset:52224
	ds_read_b128 v[218:221], v201 offset:53248
	ds_read_b128 v[222:225], v201 offset:54272
	ds_read_b128 v[226:229], v201 offset:55296
	ds_read_b128 v[230:233], v201 offset:56320
	global_load_lds_dwordx4 v[180:181], off
	v_lshl_add_u64 v[180:181], v[182:183], 0, s[36:37]
	s_mov_b32 m0, s88
	s_addc_u32 s9, s55, 0
	global_load_lds_dwordx4 v[180:181], off
	v_lshl_add_u64 v[180:181], s[8:9], 0, v[164:165]
	s_mov_b32 m0, s91
	s_nop 0
	global_load_lds_dwordx4 v[180:181], off
	v_lshl_add_u64 v[180:181], s[8:9], 0, v[168:169]
	s_mov_b32 m0, s92
	s_nop 0
	global_load_lds_dwordx4 v[180:181], off
	v_lshl_add_u64 v[180:181], v[184:185], 0, s[36:37]
	s_mov_b32 m0, s89
	s_nop 0
	global_load_lds_dwordx4 v[180:181], off
	v_lshl_add_u64 v[180:181], v[186:187], 0, s[36:37]
	s_mov_b32 m0, s90
	s_nop 0
	global_load_lds_dwordx4 v[180:181], off
	s_waitcnt vmcnt(8)
	s_waitcnt lgkmcnt(0)
	s_barrier
	s_setprio 1
	s_waitcnt lgkmcnt(0)
	v_mfma_scale_f32_16x16x128_f8f6f4 v[94:97], v[18:25], v[202:209], v[94:97], v199, v199 op_sel_hi:[0,0,0]
	v_mfma_scale_f32_16x16x128_f8f6f4 v[90:93], v[26:33], v[202:209], v[90:93], v199, v199 op_sel_hi:[0,0,0]
	v_mfma_scale_f32_16x16x128_f8f6f4 v[58:61], v[10:17], v[202:209], v[58:61], v199, v199 op_sel_hi:[0,0,0]
	v_mfma_scale_f32_16x16x128_f8f6f4 v[62:65], v[2:9], v[202:209], v[62:65], v199, v199 op_sel_hi:[0,0,0]
	v_mfma_scale_f32_16x16x128_f8f6f4 v[54:57], v[2:9], v[210:217], v[54:57], v199, v199 op_sel_hi:[0,0,0]
	v_mfma_scale_f32_16x16x128_f8f6f4 v[50:53], v[10:17], v[210:217], v[50:53], v199, v199 op_sel_hi:[0,0,0]
	v_mfma_scale_f32_16x16x128_f8f6f4 v[82:85], v[26:33], v[210:217], v[82:85], v199, v199 op_sel_hi:[0,0,0]
	v_mfma_scale_f32_16x16x128_f8f6f4 v[86:89], v[18:25], v[210:217], v[86:89], v199, v199 op_sel_hi:[0,0,0]
	s_setprio 0
	s_setprio 1
	v_mfma_scale_f32_16x16x128_f8f6f4 v[78:81], v[18:25], v[218:225], v[78:81], v199, v199 op_sel_hi:[0,0,0]
	v_mfma_scale_f32_16x16x128_f8f6f4 v[74:77], v[26:33], v[218:225], v[74:77], v199, v199 op_sel_hi:[0,0,0]
	v_mfma_scale_f32_16x16x128_f8f6f4 v[42:45], v[10:17], v[218:225], v[42:45], v199, v199 op_sel_hi:[0,0,0]
	v_mfma_scale_f32_16x16x128_f8f6f4 v[46:49], v[2:9], v[218:225], v[46:49], v199, v199 op_sel_hi:[0,0,0]
	v_mfma_scale_f32_16x16x128_f8f6f4 v[38:41], v[2:9], v[226:233], v[38:41], v199, v199 op_sel_hi:[0,0,0]
	v_mfma_scale_f32_16x16x128_f8f6f4 v[34:37], v[10:17], v[226:233], v[34:37], v199, v199 op_sel_hi:[0,0,0]
	v_mfma_scale_f32_16x16x128_f8f6f4 v[66:69], v[26:33], v[226:233], v[66:69], v199, v199 op_sel_hi:[0,0,0]
	v_mfma_scale_f32_16x16x128_f8f6f4 v[70:73], v[18:25], v[226:233], v[70:73], v199, v199 op_sel_hi:[0,0,0]
	s_setprio 0
	s_barrier
	s_add_u32 s72, s72, 0x80180
	s_addc_u32 s73, s73, 0
	s_add_u32 s8, s54, 0x200
	s_addc_u32 s9, s55, 0
	s_mov_b32 s62, 0
.LBB0_438:
	ds_read_b128 v[2:5], v200
	ds_read_b128 v[6:9], v200 offset:1024
	ds_read_b128 v[18:21], v200 offset:2048
	ds_read_b128 v[22:25], v200 offset:3072
	ds_read_b128 v[26:29], v200 offset:16384
	ds_read_b128 v[30:33], v200 offset:17408
	ds_read_b128 v[180:183], v200 offset:18432
	ds_read_b128 v[184:187], v200 offset:19456
	s_add_u32 s54, s72, 0xfff80080
	s_addc_u32 s55, s73, -1
	s_cmp_eq_u32 s62, 28
	s_cselect_b32 s75, s47, s55
	s_cselect_b32 s74, s71, s54
	s_cselect_b32 s55, s45, s9
	s_cselect_b32 s54, s94, s8
	s_mov_b32 m0, s33
	v_lshl_add_u64 v[226:227], s[72:73], 0, v[170:171]
	ds_read_b128 v[10:13], v201
	ds_read_b128 v[14:17], v201 offset:1024
	ds_read_b128 v[202:205], v201 offset:2048
	ds_read_b128 v[206:209], v201 offset:3072
	ds_read_b128 v[210:213], v201 offset:4096
	ds_read_b128 v[214:217], v201 offset:5120
	ds_read_b128 v[218:221], v201 offset:6144
	ds_read_b128 v[222:225], v201 offset:7168
	global_load_lds_dwordx4 v[226:227], off
	v_lshl_add_u64 v[226:227], s[72:73], 0, v[172:173]
	s_mov_b32 m0, s93
	s_nop 0
	global_load_lds_dwordx4 v[226:227], off
	s_waitcnt vmcnt(8)
	s_waitcnt lgkmcnt(0)
	s_barrier
	s_setprio 1
	s_waitcnt lgkmcnt(0)
	v_mfma_scale_f32_16x16x128_f8f6f4 v[158:161], v[2:9], v[10:17], v[158:161], v199, v199 op_sel_hi:[0,0,0]
	v_mfma_scale_f32_16x16x128_f8f6f4 v[154:157], v[18:25], v[10:17], v[154:157], v199, v199 op_sel_hi:[0,0,0]
	v_mfma_scale_f32_16x16x128_f8f6f4 v[122:125], v[180:187], v[10:17], v[122:125], v199, v199 op_sel_hi:[0,0,0]
	v_mfma_scale_f32_16x16x128_f8f6f4 v[126:129], v[26:33], v[10:17], v[126:129], v199, v199 op_sel_hi:[0,0,0]
	v_mfma_scale_f32_16x16x128_f8f6f4 v[118:121], v[26:33], v[202:209], v[118:121], v199, v199 op_sel_hi:[0,0,0]
	v_mfma_scale_f32_16x16x128_f8f6f4 v[114:117], v[180:187], v[202:209], v[114:117], v199, v199 op_sel_hi:[0,0,0]
	v_mfma_scale_f32_16x16x128_f8f6f4 v[146:149], v[18:25], v[202:209], v[146:149], v199, v199 op_sel_hi:[0,0,0]
	v_mfma_scale_f32_16x16x128_f8f6f4 v[150:153], v[2:9], v[202:209], v[150:153], v199, v199 op_sel_hi:[0,0,0]
	s_setprio 0
	s_setprio 1
	v_mfma_scale_f32_16x16x128_f8f6f4 v[142:145], v[2:9], v[210:217], v[142:145], v199, v199 op_sel_hi:[0,0,0]
	v_mfma_scale_f32_16x16x128_f8f6f4 v[138:141], v[18:25], v[210:217], v[138:141], v199, v199 op_sel_hi:[0,0,0]
	v_mfma_scale_f32_16x16x128_f8f6f4 v[106:109], v[180:187], v[210:217], v[106:109], v199, v199 op_sel_hi:[0,0,0]
	v_mfma_scale_f32_16x16x128_f8f6f4 v[110:113], v[26:33], v[210:217], v[110:113], v199, v199 op_sel_hi:[0,0,0]
	v_mfma_scale_f32_16x16x128_f8f6f4 v[102:105], v[26:33], v[218:225], v[102:105], v199, v199 op_sel_hi:[0,0,0]
	v_mfma_scale_f32_16x16x128_f8f6f4 v[98:101], v[180:187], v[218:225], v[98:101], v199, v199 op_sel_hi:[0,0,0]
	v_mfma_scale_f32_16x16x128_f8f6f4 v[130:133], v[18:25], v[218:225], v[130:133], v199, v199 op_sel_hi:[0,0,0]
	v_mfma_scale_f32_16x16x128_f8f6f4 v[134:137], v[2:9], v[218:225], v[134:137], v199, v199 op_sel_hi:[0,0,0]
	s_setprio 0
	s_barrier
	s_mov_b32 m0, s78
	v_lshl_add_u64 v[10:11], s[54:55], 0, v[164:165]
	s_add_u32 s96, s54, 0x80000
	ds_read_b128 v[202:205], v201 offset:16384
	ds_read_b128 v[206:209], v201 offset:17408
	ds_read_b128 v[210:213], v201 offset:18432
	ds_read_b128 v[214:217], v201 offset:19456
	ds_read_b128 v[218:221], v201 offset:20480
	ds_read_b128 v[222:225], v201 offset:21504
	ds_read_b128 v[226:229], v201 offset:22528
	ds_read_b128 v[230:233], v201 offset:23552
	global_load_lds_dwordx4 v[10:11], off
	v_lshl_add_u64 v[12:13], s[54:55], 0, v[168:169]
	s_mov_b32 m0, s79
	s_addc_u32 s97, s55, 0
	global_load_lds_dwordx4 v[12:13], off
	v_lshl_add_u64 v[14:15], s[96:97], 0, v[164:165]
	s_mov_b32 m0, s80
	v_lshl_add_u64 v[16:17], s[74:75], 0, v[166:167]
	global_load_lds_dwordx4 v[14:15], off
	v_lshl_add_u64 v[14:15], s[96:97], 0, v[168:169]
	s_mov_b32 m0, s81
	s_nop 0
	global_load_lds_dwordx4 v[14:15], off
	v_lshl_add_u64 v[14:15], s[74:75], 0, v[162:163]
	s_mov_b32 m0, s53
	s_nop 0
	global_load_lds_dwordx4 v[14:15], off
	s_mov_b32 m0, s82
	s_nop 0
	global_load_lds_dwordx4 v[16:17], off
	s_waitcnt vmcnt(8)
	s_waitcnt lgkmcnt(0)
	s_barrier
	s_setprio 1
	s_waitcnt lgkmcnt(0)
	v_mfma_scale_f32_16x16x128_f8f6f4 v[94:97], v[2:9], v[202:209], v[94:97], v199, v199 op_sel_hi:[0,0,0]
	v_mfma_scale_f32_16x16x128_f8f6f4 v[90:93], v[18:25], v[202:209], v[90:93], v199, v199 op_sel_hi:[0,0,0]
	v_mfma_scale_f32_16x16x128_f8f6f4 v[58:61], v[180:187], v[202:209], v[58:61], v199, v199 op_sel_hi:[0,0,0]
	v_mfma_scale_f32_16x16x128_f8f6f4 v[62:65], v[26:33], v[202:209], v[62:65], v199, v199 op_sel_hi:[0,0,0]
	v_mfma_scale_f32_16x16x128_f8f6f4 v[54:57], v[26:33], v[210:217], v[54:57], v199, v199 op_sel_hi:[0,0,0]
	v_mfma_scale_f32_16x16x128_f8f6f4 v[50:53], v[180:187], v[210:217], v[50:53], v199, v199 op_sel_hi:[0,0,0]
	v_mfma_scale_f32_16x16x128_f8f6f4 v[82:85], v[18:25], v[210:217], v[82:85], v199, v199 op_sel_hi:[0,0,0]
	v_mfma_scale_f32_16x16x128_f8f6f4 v[86:89], v[2:9], v[210:217], v[86:89], v199, v199 op_sel_hi:[0,0,0]
	s_setprio 0
	s_setprio 1
	v_mfma_scale_f32_16x16x128_f8f6f4 v[78:81], v[2:9], v[218:225], v[78:81], v199, v199 op_sel_hi:[0,0,0]
	v_mfma_scale_f32_16x16x128_f8f6f4 v[74:77], v[18:25], v[218:225], v[74:77], v199, v199 op_sel_hi:[0,0,0]
	v_mfma_scale_f32_16x16x128_f8f6f4 v[42:45], v[180:187], v[218:225], v[42:45], v199, v199 op_sel_hi:[0,0,0]
	v_mfma_scale_f32_16x16x128_f8f6f4 v[46:49], v[26:33], v[218:225], v[46:49], v199, v199 op_sel_hi:[0,0,0]
	v_mfma_scale_f32_16x16x128_f8f6f4 v[38:41], v[26:33], v[226:233], v[38:41], v199, v199 op_sel_hi:[0,0,0]
	v_mfma_scale_f32_16x16x128_f8f6f4 v[34:37], v[180:187], v[226:233], v[34:37], v199, v199 op_sel_hi:[0,0,0]
	v_mfma_scale_f32_16x16x128_f8f6f4 v[66:69], v[18:25], v[226:233], v[66:69], v199, v199 op_sel_hi:[0,0,0]
	v_mfma_scale_f32_16x16x128_f8f6f4 v[70:73], v[2:9], v[226:233], v[70:73], v199, v199 op_sel_hi:[0,0,0]
	s_setprio 0
	s_barrier
	ds_read_b128 v[18:21], v200 offset:32768
	ds_read_b128 v[22:25], v200 offset:33792
	ds_read_b128 v[26:29], v200 offset:34816
	ds_read_b128 v[30:33], v200 offset:35840
	ds_read_b128 v[2:5], v200 offset:49152
	ds_read_b128 v[6:9], v200 offset:50176
	ds_read_b128 v[180:183], v200 offset:51200
	ds_read_b128 v[184:187], v200 offset:52224
	s_add_u32 s74, s74, 0x80000
	s_addc_u32 s75, s75, 0
	s_mov_b32 m0, s83
	v_lshl_add_u64 v[234:235], s[74:75], 0, v[162:163]
	ds_read_b128 v[202:205], v201 offset:32768
	ds_read_b128 v[206:209], v201 offset:33792
	ds_read_b128 v[210:213], v201 offset:34816
	ds_read_b128 v[214:217], v201 offset:35840
	ds_read_b128 v[218:221], v201 offset:36864
	ds_read_b128 v[222:225], v201 offset:37888
	ds_read_b128 v[226:229], v201 offset:38912
	ds_read_b128 v[230:233], v201 offset:39936
	global_load_lds_dwordx4 v[234:235], off
	v_lshl_add_u64 v[234:235], s[74:75], 0, v[166:167]
	s_mov_b32 m0, s84
	s_nop 0
	global_load_lds_dwordx4 v[234:235], off
	s_waitcnt vmcnt(8)
	s_waitcnt lgkmcnt(0)
	s_barrier
	s_setprio 1
	s_waitcnt lgkmcnt(0)
	v_mfma_scale_f32_16x16x128_f8f6f4 v[158:161], v[18:25], v[202:209], v[158:161], v199, v199 op_sel_hi:[0,0,0]
	v_mfma_scale_f32_16x16x128_f8f6f4 v[154:157], v[26:33], v[202:209], v[154:157], v199, v199 op_sel_hi:[0,0,0]
	v_mfma_scale_f32_16x16x128_f8f6f4 v[122:125], v[180:187], v[202:209], v[122:125], v199, v199 op_sel_hi:[0,0,0]
	v_mfma_scale_f32_16x16x128_f8f6f4 v[126:129], v[2:9], v[202:209], v[126:129], v199, v199 op_sel_hi:[0,0,0]
	v_mfma_scale_f32_16x16x128_f8f6f4 v[118:121], v[2:9], v[210:217], v[118:121], v199, v199 op_sel_hi:[0,0,0]
	v_mfma_scale_f32_16x16x128_f8f6f4 v[114:117], v[180:187], v[210:217], v[114:117], v199, v199 op_sel_hi:[0,0,0]
	v_mfma_scale_f32_16x16x128_f8f6f4 v[146:149], v[26:33], v[210:217], v[146:149], v199, v199 op_sel_hi:[0,0,0]
	v_mfma_scale_f32_16x16x128_f8f6f4 v[150:153], v[18:25], v[210:217], v[150:153], v199, v199 op_sel_hi:[0,0,0]
	s_setprio 0
	s_setprio 1
	v_mfma_scale_f32_16x16x128_f8f6f4 v[142:145], v[18:25], v[218:225], v[142:145], v199, v199 op_sel_hi:[0,0,0]
	v_mfma_scale_f32_16x16x128_f8f6f4 v[138:141], v[26:33], v[218:225], v[138:141], v199, v199 op_sel_hi:[0,0,0]
	v_mfma_scale_f32_16x16x128_f8f6f4 v[106:109], v[180:187], v[218:225], v[106:109], v199, v199 op_sel_hi:[0,0,0]
	v_mfma_scale_f32_16x16x128_f8f6f4 v[110:113], v[2:9], v[218:225], v[110:113], v199, v199 op_sel_hi:[0,0,0]
	v_mfma_scale_f32_16x16x128_f8f6f4 v[102:105], v[2:9], v[226:233], v[102:105], v199, v199 op_sel_hi:[0,0,0]
	v_mfma_scale_f32_16x16x128_f8f6f4 v[98:101], v[180:187], v[226:233], v[98:101], v199, v199 op_sel_hi:[0,0,0]
	v_mfma_scale_f32_16x16x128_f8f6f4 v[130:133], v[26:33], v[226:233], v[130:133], v199, v199 op_sel_hi:[0,0,0]
	v_mfma_scale_f32_16x16x128_f8f6f4 v[134:137], v[18:25], v[226:233], v[134:137], v199, v199 op_sel_hi:[0,0,0]
	s_setprio 0
	s_barrier
	s_mov_b32 m0, s87
	v_lshl_add_u64 v[10:11], v[10:11], 0, s[4:5]
	s_add_u32 s54, s54, 0x80080
	ds_read_b128 v[202:205], v201 offset:49152
	ds_read_b128 v[206:209], v201 offset:50176
	ds_read_b128 v[210:213], v201 offset:51200
	ds_read_b128 v[214:217], v201 offset:52224
	ds_read_b128 v[218:221], v201 offset:53248
	ds_read_b128 v[222:225], v201 offset:54272
	ds_read_b128 v[226:229], v201 offset:55296
	ds_read_b128 v[230:233], v201 offset:56320
	global_load_lds_dwordx4 v[10:11], off
	v_lshl_add_u64 v[10:11], v[12:13], 0, s[4:5]
	s_mov_b32 m0, s88
	s_addc_u32 s55, s55, 0
	global_load_lds_dwordx4 v[10:11], off
	v_lshl_add_u64 v[10:11], s[54:55], 0, v[164:165]
	s_mov_b32 m0, s91
	s_nop 0
	global_load_lds_dwordx4 v[10:11], off
	v_lshl_add_u64 v[10:11], s[54:55], 0, v[168:169]
	s_mov_b32 m0, s92
	s_nop 0
	global_load_lds_dwordx4 v[10:11], off
	v_lshl_add_u64 v[10:11], v[14:15], 0, s[4:5]
	s_mov_b32 m0, s89
	s_nop 0
	global_load_lds_dwordx4 v[10:11], off
	v_lshl_add_u64 v[10:11], v[16:17], 0, s[4:5]
	s_mov_b32 m0, s90
	s_nop 0
	global_load_lds_dwordx4 v[10:11], off
	s_waitcnt vmcnt(8)
	s_waitcnt lgkmcnt(0)
	s_barrier
	s_setprio 1
	s_waitcnt lgkmcnt(0)
	v_mfma_scale_f32_16x16x128_f8f6f4 v[94:97], v[18:25], v[202:209], v[94:97], v199, v199 op_sel_hi:[0,0,0]
	v_mfma_scale_f32_16x16x128_f8f6f4 v[90:93], v[26:33], v[202:209], v[90:93], v199, v199 op_sel_hi:[0,0,0]
	v_mfma_scale_f32_16x16x128_f8f6f4 v[58:61], v[180:187], v[202:209], v[58:61], v199, v199 op_sel_hi:[0,0,0]
	v_mfma_scale_f32_16x16x128_f8f6f4 v[62:65], v[2:9], v[202:209], v[62:65], v199, v199 op_sel_hi:[0,0,0]
	v_mfma_scale_f32_16x16x128_f8f6f4 v[54:57], v[2:9], v[210:217], v[54:57], v199, v199 op_sel_hi:[0,0,0]
	v_mfma_scale_f32_16x16x128_f8f6f4 v[50:53], v[180:187], v[210:217], v[50:53], v199, v199 op_sel_hi:[0,0,0]
	v_mfma_scale_f32_16x16x128_f8f6f4 v[82:85], v[26:33], v[210:217], v[82:85], v199, v199 op_sel_hi:[0,0,0]
	v_mfma_scale_f32_16x16x128_f8f6f4 v[86:89], v[18:25], v[210:217], v[86:89], v199, v199 op_sel_hi:[0,0,0]
	s_setprio 0
	s_setprio 1
	v_mfma_scale_f32_16x16x128_f8f6f4 v[78:81], v[18:25], v[218:225], v[78:81], v199, v199 op_sel_hi:[0,0,0]
	v_mfma_scale_f32_16x16x128_f8f6f4 v[74:77], v[26:33], v[218:225], v[74:77], v199, v199 op_sel_hi:[0,0,0]
	v_mfma_scale_f32_16x16x128_f8f6f4 v[42:45], v[180:187], v[218:225], v[42:45], v199, v199 op_sel_hi:[0,0,0]
	v_mfma_scale_f32_16x16x128_f8f6f4 v[46:49], v[2:9], v[218:225], v[46:49], v199, v199 op_sel_hi:[0,0,0]
	v_mfma_scale_f32_16x16x128_f8f6f4 v[38:41], v[2:9], v[226:233], v[38:41], v199, v199 op_sel_hi:[0,0,0]
	v_mfma_scale_f32_16x16x128_f8f6f4 v[34:37], v[180:187], v[226:233], v[34:37], v199, v199 op_sel_hi:[0,0,0]
	v_mfma_scale_f32_16x16x128_f8f6f4 v[66:69], v[26:33], v[226:233], v[66:69], v199, v199 op_sel_hi:[0,0,0]
	v_mfma_scale_f32_16x16x128_f8f6f4 v[70:73], v[18:25], v[226:233], v[70:73], v199, v199 op_sel_hi:[0,0,0]
	s_setprio 0
	s_barrier
	s_add_i32 s62, s62, 2
	s_add_u32 s72, s72, 0x100
	s_addc_u32 s73, s73, 0
	s_add_u32 s8, s8, 0x100
	s_addc_u32 s9, s9, 0
	s_cmp_gt_u32 s62, 29
	s_cbranch_scc0 .LBB0_438
	s_and_b64 vcc, exec, s[6:7]
	s_cbranch_vccz .LBB0_441
	s_barrier

.LBB0_600:
	s_ashr_i32 s55, s54, 31
	ds_read_b128 v[18:21], v200
	ds_read_b128 v[22:25], v200 offset:1024
	ds_read_b128 v[26:29], v200 offset:2048
	ds_read_b128 v[30:33], v200 offset:3072
	ds_read_b128 v[2:5], v200 offset:16384
	ds_read_b128 v[6:9], v200 offset:17408
	ds_read_b128 v[10:13], v200 offset:18432
	ds_read_b128 v[14:17], v200 offset:19456
	s_lshl_b64 s[4:5], s[54:55], 18
	s_add_u32 s72, s38, s4
	s_addc_u32 s73, s39, s5
	s_and_b64 s[4:5], s[2:3], exec
	s_cselect_b32 s4, s73, s81
	s_cselect_b32 s5, s72, s80
	s_ashr_i32 s53, s52, 31
	s_lshl_b64 s[8:9], s[52:53], 18
	s_add_u32 s74, s94, s8
	v_readlane_b32 s8, v254, 6
	s_addc_u32 s75, s8, s9
	s_and_b64 s[8:9], s[2:3], exec
	s_cselect_b32 s53, s75, s79
	s_cselect_b32 s55, s74, s78
	s_add_u32 s8, s80, 0x20080
	s_addc_u32 s9, s81, 0
	s_mov_b32 m0, s96
	v_lshl_add_u64 v[226:227], s[8:9], 0, v[162:163]
	ds_read_b128 v[182:185], v201
	ds_read_b128 v[186:189], v201 offset:1024
	ds_read_b128 v[202:205], v201 offset:2048
	ds_read_b128 v[206:209], v201 offset:3072
	ds_read_b128 v[210:213], v201 offset:4096
	ds_read_b128 v[214:217], v201 offset:5120
	ds_read_b128 v[218:221], v201 offset:6144
	ds_read_b128 v[222:225], v201 offset:7168
	global_load_lds_dwordx4 v[226:227], off
	v_lshl_add_u64 v[226:227], s[8:9], 0, v[166:167]
	s_mov_b32 m0, s61
	s_nop 0
	global_load_lds_dwordx4 v[226:227], off
	s_waitcnt vmcnt(8)
	s_waitcnt lgkmcnt(0)
	s_barrier
	s_setprio 1
	s_waitcnt lgkmcnt(0)
	v_mfma_scale_f32_16x16x128_f8f6f4 v[158:161], v[18:25], v[182:189], 0, v199, v199 op_sel_hi:[0,0,0]
	v_mfma_scale_f32_16x16x128_f8f6f4 v[154:157], v[26:33], v[182:189], 0, v199, v199 op_sel_hi:[0,0,0]
	v_mfma_scale_f32_16x16x128_f8f6f4 v[122:125], v[10:17], v[182:189], 0, v199, v199 op_sel_hi:[0,0,0]
	v_mfma_scale_f32_16x16x128_f8f6f4 v[126:129], v[2:9], v[182:189], 0, v199, v199 op_sel_hi:[0,0,0]
	v_mfma_scale_f32_16x16x128_f8f6f4 v[118:121], v[2:9], v[202:209], 0, v199, v199 op_sel_hi:[0,0,0]
	v_mfma_scale_f32_16x16x128_f8f6f4 v[114:117], v[10:17], v[202:209], 0, v199, v199 op_sel_hi:[0,0,0]
	v_mfma_scale_f32_16x16x128_f8f6f4 v[146:149], v[26:33], v[202:209], 0, v199, v199 op_sel_hi:[0,0,0]
	v_mfma_scale_f32_16x16x128_f8f6f4 v[150:153], v[18:25], v[202:209], 0, v199, v199 op_sel_hi:[0,0,0]
	s_setprio 0
	s_setprio 1
	v_mfma_scale_f32_16x16x128_f8f6f4 v[142:145], v[18:25], v[210:217], 0, v199, v199 op_sel_hi:[0,0,0]
	v_mfma_scale_f32_16x16x128_f8f6f4 v[138:141], v[26:33], v[210:217], 0, v199, v199 op_sel_hi:[0,0,0]
	v_mfma_scale_f32_16x16x128_f8f6f4 v[106:109], v[10:17], v[210:217], 0, v199, v199 op_sel_hi:[0,0,0]
	v_mfma_scale_f32_16x16x128_f8f6f4 v[110:113], v[2:9], v[210:217], 0, v199, v199 op_sel_hi:[0,0,0]
	v_mfma_scale_f32_16x16x128_f8f6f4 v[102:105], v[2:9], v[218:225], 0, v199, v199 op_sel_hi:[0,0,0]
	v_mfma_scale_f32_16x16x128_f8f6f4 v[98:101], v[10:17], v[218:225], 0, v199, v199 op_sel_hi:[0,0,0]
	v_mfma_scale_f32_16x16x128_f8f6f4 v[130:133], v[26:33], v[218:225], 0, v199, v199 op_sel_hi:[0,0,0]
	v_mfma_scale_f32_16x16x128_f8f6f4 v[134:137], v[18:25], v[218:225], 0, v199, v199 op_sel_hi:[0,0,0]
	s_setprio 0
	s_barrier
	v_lshl_add_u64 v[182:183], s[78:79], 0, v[164:165]
	s_mov_b32 m0, s68
	v_lshl_add_u64 v[184:185], v[182:183], 0, s[46:47]
	ds_read_b128 v[202:205], v201 offset:16384
	ds_read_b128 v[206:209], v201 offset:17408
	ds_read_b128 v[210:213], v201 offset:18432
	ds_read_b128 v[214:217], v201 offset:19456
	ds_read_b128 v[218:221], v201 offset:20480
	ds_read_b128 v[222:225], v201 offset:21504
	ds_read_b128 v[226:229], v201 offset:22528
	ds_read_b128 v[230:233], v201 offset:23552
	global_load_lds_dwordx4 v[184:185], off
	v_lshl_add_u64 v[184:185], s[78:79], 0, v[168:169]
	s_add_u32 s8, s78, 0x20100
	v_lshl_add_u64 v[186:187], v[184:185], 0, s[46:47]
	s_mov_b32 m0, s69
	s_addc_u32 s9, s79, 0
	global_load_lds_dwordx4 v[186:187], off
	v_lshl_add_u64 v[186:187], s[8:9], 0, v[164:165]
	s_mov_b32 m0, s77
	s_nop 0
	global_load_lds_dwordx4 v[186:187], off
	v_lshl_add_u64 v[186:187], s[8:9], 0, v[168:169]
	s_mov_b32 m0, s84
	s_nop 0
	global_load_lds_dwordx4 v[186:187], off
	v_lshl_add_u64 v[186:187], s[80:81], 0, v[162:163]
	v_lshl_add_u64 v[188:189], v[186:187], 0, s[46:47]
	s_mov_b32 m0, s33
	s_nop 0
	global_load_lds_dwordx4 v[188:189], off
	v_lshl_add_u64 v[188:189], s[80:81], 0, v[166:167]
	v_lshl_add_u64 v[234:235], v[188:189], 0, s[46:47]
	s_mov_b32 m0, s85
	s_nop 0
	global_load_lds_dwordx4 v[234:235], off
	s_waitcnt vmcnt(8)
	s_waitcnt lgkmcnt(0)
	s_barrier
	s_setprio 1
	s_waitcnt lgkmcnt(0)
	v_mfma_scale_f32_16x16x128_f8f6f4 v[94:97], v[18:25], v[202:209], 0, v199, v199 op_sel_hi:[0,0,0]
	v_mfma_scale_f32_16x16x128_f8f6f4 v[90:93], v[26:33], v[202:209], 0, v199, v199 op_sel_hi:[0,0,0]
	v_mfma_scale_f32_16x16x128_f8f6f4 v[58:61], v[10:17], v[202:209], 0, v199, v199 op_sel_hi:[0,0,0]
	v_mfma_scale_f32_16x16x128_f8f6f4 v[62:65], v[2:9], v[202:209], 0, v199, v199 op_sel_hi:[0,0,0]
	v_mfma_scale_f32_16x16x128_f8f6f4 v[54:57], v[2:9], v[210:217], 0, v199, v199 op_sel_hi:[0,0,0]
	v_mfma_scale_f32_16x16x128_f8f6f4 v[50:53], v[10:17], v[210:217], 0, v199, v199 op_sel_hi:[0,0,0]
	v_mfma_scale_f32_16x16x128_f8f6f4 v[82:85], v[26:33], v[210:217], 0, v199, v199 op_sel_hi:[0,0,0]
	v_mfma_scale_f32_16x16x128_f8f6f4 v[86:89], v[18:25], v[210:217], 0, v199, v199 op_sel_hi:[0,0,0]
	s_setprio 0
	s_setprio 1
	v_mfma_scale_f32_16x16x128_f8f6f4 v[78:81], v[18:25], v[218:225], 0, v199, v199 op_sel_hi:[0,0,0]
	v_mfma_scale_f32_16x16x128_f8f6f4 v[74:77], v[26:33], v[218:225], 0, v199, v199 op_sel_hi:[0,0,0]
	v_mfma_scale_f32_16x16x128_f8f6f4 v[42:45], v[10:17], v[218:225], 0, v199, v199 op_sel_hi:[0,0,0]
	v_mfma_scale_f32_16x16x128_f8f6f4 v[46:49], v[2:9], v[218:225], 0, v199, v199 op_sel_hi:[0,0,0]
	v_mfma_scale_f32_16x16x128_f8f6f4 v[38:41], v[2:9], v[226:233], 0, v199, v199 op_sel_hi:[0,0,0]
	v_mfma_scale_f32_16x16x128_f8f6f4 v[34:37], v[10:17], v[226:233], 0, v199, v199 op_sel_hi:[0,0,0]
	v_mfma_scale_f32_16x16x128_f8f6f4 v[66:69], v[26:33], v[226:233], 0, v199, v199 op_sel_hi:[0,0,0]
	v_mfma_scale_f32_16x16x128_f8f6f4 v[70:73], v[18:25], v[226:233], 0, v199, v199 op_sel_hi:[0,0,0]
	s_setprio 0
	s_barrier
	ds_read_b128 v[18:21], v200 offset:32768
	ds_read_b128 v[22:25], v200 offset:33792
	ds_read_b128 v[26:29], v200 offset:34816
	ds_read_b128 v[30:33], v200 offset:35840
	ds_read_b128 v[2:5], v200 offset:49152
	ds_read_b128 v[6:9], v200 offset:50176
	ds_read_b128 v[10:13], v200 offset:51200
	ds_read_b128 v[14:17], v200 offset:52224
	s_add_u32 s8, s80, 0x20100
	s_addc_u32 s9, s81, 0
	s_mov_b32 m0, s86
	v_lshl_add_u64 v[234:235], s[8:9], 0, v[162:163]
	ds_read_b128 v[202:205], v201 offset:32768
	ds_read_b128 v[206:209], v201 offset:33792
	ds_read_b128 v[210:213], v201 offset:34816
	ds_read_b128 v[214:217], v201 offset:35840
	ds_read_b128 v[218:221], v201 offset:36864
	ds_read_b128 v[222:225], v201 offset:37888
	ds_read_b128 v[226:229], v201 offset:38912
	ds_read_b128 v[230:233], v201 offset:39936
	global_load_lds_dwordx4 v[234:235], off
	v_lshl_add_u64 v[234:235], s[8:9], 0, v[166:167]
	s_mov_b32 m0, s87
	s_nop 0
	global_load_lds_dwordx4 v[234:235], off
	s_waitcnt vmcnt(8)
	s_waitcnt lgkmcnt(0)
	s_barrier
	s_setprio 1
	s_waitcnt lgkmcnt(0)
	v_mfma_scale_f32_16x16x128_f8f6f4 v[158:161], v[18:25], v[202:209], v[158:161], v199, v199 op_sel_hi:[0,0,0]
	v_mfma_scale_f32_16x16x128_f8f6f4 v[154:157], v[26:33], v[202:209], v[154:157], v199, v199 op_sel_hi:[0,0,0]
	v_mfma_scale_f32_16x16x128_f8f6f4 v[122:125], v[10:17], v[202:209], v[122:125], v199, v199 op_sel_hi:[0,0,0]
	v_mfma_scale_f32_16x16x128_f8f6f4 v[126:129], v[2:9], v[202:209], v[126:129], v199, v199 op_sel_hi:[0,0,0]
	v_mfma_scale_f32_16x16x128_f8f6f4 v[118:121], v[2:9], v[210:217], v[118:121], v199, v199 op_sel_hi:[0,0,0]
	v_mfma_scale_f32_16x16x128_f8f6f4 v[114:117], v[10:17], v[210:217], v[114:117], v199, v199 op_sel_hi:[0,0,0]
	v_mfma_scale_f32_16x16x128_f8f6f4 v[146:149], v[26:33], v[210:217], v[146:149], v199, v199 op_sel_hi:[0,0,0]
	v_mfma_scale_f32_16x16x128_f8f6f4 v[150:153], v[18:25], v[210:217], v[150:153], v199, v199 op_sel_hi:[0,0,0]
	s_setprio 0
	s_setprio 1
	v_mfma_scale_f32_16x16x128_f8f6f4 v[142:145], v[18:25], v[218:225], v[142:145], v199, v199 op_sel_hi:[0,0,0]
	v_mfma_scale_f32_16x16x128_f8f6f4 v[138:141], v[26:33], v[218:225], v[138:141], v199, v199 op_sel_hi:[0,0,0]
	v_mfma_scale_f32_16x16x128_f8f6f4 v[106:109], v[10:17], v[218:225], v[106:109], v199, v199 op_sel_hi:[0,0,0]
	v_mfma_scale_f32_16x16x128_f8f6f4 v[110:113], v[2:9], v[218:225], v[110:113], v199, v199 op_sel_hi:[0,0,0]
	v_mfma_scale_f32_16x16x128_f8f6f4 v[102:105], v[2:9], v[226:233], v[102:105], v199, v199 op_sel_hi:[0,0,0]
	v_mfma_scale_f32_16x16x128_f8f6f4 v[98:101], v[10:17], v[226:233], v[98:101], v199, v199 op_sel_hi:[0,0,0]
	v_mfma_scale_f32_16x16x128_f8f6f4 v[130:133], v[26:33], v[226:233], v[130:133], v199, v199 op_sel_hi:[0,0,0]
	v_mfma_scale_f32_16x16x128_f8f6f4 v[134:137], v[18:25], v[226:233], v[134:137], v199, v199 op_sel_hi:[0,0,0]
	s_setprio 0
	s_barrier
	s_mov_b32 m0, s89
	v_lshl_add_u64 v[182:183], v[182:183], 0, s[48:49]
	s_add_u32 s8, s78, 0x20180
	ds_read_b128 v[202:205], v201 offset:49152
	ds_read_b128 v[206:209], v201 offset:50176
	ds_read_b128 v[210:213], v201 offset:51200
	ds_read_b128 v[214:217], v201 offset:52224
	ds_read_b128 v[218:221], v201 offset:53248
	ds_read_b128 v[222:225], v201 offset:54272
	ds_read_b128 v[226:229], v201 offset:55296
	ds_read_b128 v[230:233], v201 offset:56320
	global_load_lds_dwordx4 v[182:183], off
	v_lshl_add_u64 v[182:183], v[184:185], 0, s[48:49]
	s_mov_b32 m0, s90
	s_addc_u32 s9, s79, 0
	global_load_lds_dwordx4 v[182:183], off
	v_lshl_add_u64 v[182:183], s[8:9], 0, v[164:165]
	s_mov_b32 m0, s93
	s_nop 0
	global_load_lds_dwordx4 v[182:183], off
	v_lshl_add_u64 v[182:183], s[8:9], 0, v[168:169]
	s_mov_b32 m0, s95
	s_nop 0
	global_load_lds_dwordx4 v[182:183], off
	v_lshl_add_u64 v[182:183], v[186:187], 0, s[48:49]
	s_mov_b32 m0, s91
	s_nop 0
	global_load_lds_dwordx4 v[182:183], off
	v_lshl_add_u64 v[182:183], v[188:189], 0, s[48:49]
	s_mov_b32 m0, s92
	s_nop 0
	global_load_lds_dwordx4 v[182:183], off
	s_waitcnt vmcnt(8)
	s_waitcnt lgkmcnt(0)
	s_barrier
	s_setprio 1
	s_waitcnt lgkmcnt(0)
	v_mfma_scale_f32_16x16x128_f8f6f4 v[94:97], v[18:25], v[202:209], v[94:97], v199, v199 op_sel_hi:[0,0,0]
	v_mfma_scale_f32_16x16x128_f8f6f4 v[90:93], v[26:33], v[202:209], v[90:93], v199, v199 op_sel_hi:[0,0,0]
	v_mfma_scale_f32_16x16x128_f8f6f4 v[58:61], v[10:17], v[202:209], v[58:61], v199, v199 op_sel_hi:[0,0,0]
	v_mfma_scale_f32_16x16x128_f8f6f4 v[62:65], v[2:9], v[202:209], v[62:65], v199, v199 op_sel_hi:[0,0,0]
	v_mfma_scale_f32_16x16x128_f8f6f4 v[54:57], v[2:9], v[210:217], v[54:57], v199, v199 op_sel_hi:[0,0,0]
	v_mfma_scale_f32_16x16x128_f8f6f4 v[50:53], v[10:17], v[210:217], v[50:53], v199, v199 op_sel_hi:[0,0,0]
	v_mfma_scale_f32_16x16x128_f8f6f4 v[82:85], v[26:33], v[210:217], v[82:85], v199, v199 op_sel_hi:[0,0,0]
	v_mfma_scale_f32_16x16x128_f8f6f4 v[86:89], v[18:25], v[210:217], v[86:89], v199, v199 op_sel_hi:[0,0,0]
	s_setprio 0
	s_setprio 1
	v_mfma_scale_f32_16x16x128_f8f6f4 v[78:81], v[18:25], v[218:225], v[78:81], v199, v199 op_sel_hi:[0,0,0]
	v_mfma_scale_f32_16x16x128_f8f6f4 v[74:77], v[26:33], v[218:225], v[74:77], v199, v199 op_sel_hi:[0,0,0]
	v_mfma_scale_f32_16x16x128_f8f6f4 v[42:45], v[10:17], v[218:225], v[42:45], v199, v199 op_sel_hi:[0,0,0]
	v_mfma_scale_f32_16x16x128_f8f6f4 v[46:49], v[2:9], v[218:225], v[46:49], v199, v199 op_sel_hi:[0,0,0]
	v_mfma_scale_f32_16x16x128_f8f6f4 v[38:41], v[2:9], v[226:233], v[38:41], v199, v199 op_sel_hi:[0,0,0]
	v_mfma_scale_f32_16x16x128_f8f6f4 v[34:37], v[10:17], v[226:233], v[34:37], v199, v199 op_sel_hi:[0,0,0]
	v_mfma_scale_f32_16x16x128_f8f6f4 v[66:69], v[26:33], v[226:233], v[66:69], v199, v199 op_sel_hi:[0,0,0]
	v_mfma_scale_f32_16x16x128_f8f6f4 v[70:73], v[18:25], v[226:233], v[70:73], v199, v199 op_sel_hi:[0,0,0]
	s_setprio 0
	s_barrier
	s_add_u32 s80, s80, 0x20180
	s_addc_u32 s81, s81, 0
	s_add_u32 s8, s78, 0x200
	s_addc_u32 s9, s79, 0
	s_mov_b32 s62, 0
.LBB0_601:
	ds_read_b128 v[2:5], v200
	ds_read_b128 v[6:9], v200 offset:1024
	ds_read_b128 v[18:21], v200 offset:2048
	ds_read_b128 v[22:25], v200 offset:3072
	ds_read_b128 v[26:29], v200 offset:16384
	ds_read_b128 v[30:33], v200 offset:17408
	ds_read_b128 v[182:185], v200 offset:18432
	ds_read_b128 v[186:189], v200 offset:19456
	s_add_u32 s63, s80, 0xfffe0080
	s_addc_u32 s71, s81, -1
	s_cmp_eq_u32 s62, 4
	s_cselect_b32 s83, s4, s71
	s_cselect_b32 s82, s5, s63
	s_cselect_b32 s79, s53, s9
	s_cselect_b32 s78, s55, s8
	s_mov_b32 m0, s96
	v_lshl_add_u64 v[226:227], s[80:81], 0, v[170:171]
	ds_read_b128 v[10:13], v201
	ds_read_b128 v[14:17], v201 offset:1024
	ds_read_b128 v[202:205], v201 offset:2048
	ds_read_b128 v[206:209], v201 offset:3072
	ds_read_b128 v[210:213], v201 offset:4096
	ds_read_b128 v[214:217], v201 offset:5120
	ds_read_b128 v[218:221], v201 offset:6144
	ds_read_b128 v[222:225], v201 offset:7168
	global_load_lds_dwordx4 v[226:227], off
	v_lshl_add_u64 v[226:227], s[80:81], 0, v[172:173]
	s_mov_b32 m0, s61
	s_nop 0
	global_load_lds_dwordx4 v[226:227], off
	s_waitcnt vmcnt(8)
	s_waitcnt lgkmcnt(0)
	s_barrier
	s_setprio 1
	s_waitcnt lgkmcnt(0)
	v_mfma_scale_f32_16x16x128_f8f6f4 v[158:161], v[2:9], v[10:17], v[158:161], v199, v199 op_sel_hi:[0,0,0]
	v_mfma_scale_f32_16x16x128_f8f6f4 v[154:157], v[18:25], v[10:17], v[154:157], v199, v199 op_sel_hi:[0,0,0]
	v_mfma_scale_f32_16x16x128_f8f6f4 v[122:125], v[182:189], v[10:17], v[122:125], v199, v199 op_sel_hi:[0,0,0]
	v_mfma_scale_f32_16x16x128_f8f6f4 v[126:129], v[26:33], v[10:17], v[126:129], v199, v199 op_sel_hi:[0,0,0]
	v_mfma_scale_f32_16x16x128_f8f6f4 v[118:121], v[26:33], v[202:209], v[118:121], v199, v199 op_sel_hi:[0,0,0]
	v_mfma_scale_f32_16x16x128_f8f6f4 v[114:117], v[182:189], v[202:209], v[114:117], v199, v199 op_sel_hi:[0,0,0]
	v_mfma_scale_f32_16x16x128_f8f6f4 v[146:149], v[18:25], v[202:209], v[146:149], v199, v199 op_sel_hi:[0,0,0]
	v_mfma_scale_f32_16x16x128_f8f6f4 v[150:153], v[2:9], v[202:209], v[150:153], v199, v199 op_sel_hi:[0,0,0]
	s_setprio 0
	s_setprio 1
	v_mfma_scale_f32_16x16x128_f8f6f4 v[142:145], v[2:9], v[210:217], v[142:145], v199, v199 op_sel_hi:[0,0,0]
	v_mfma_scale_f32_16x16x128_f8f6f4 v[138:141], v[18:25], v[210:217], v[138:141], v199, v199 op_sel_hi:[0,0,0]
	v_mfma_scale_f32_16x16x128_f8f6f4 v[106:109], v[182:189], v[210:217], v[106:109], v199, v199 op_sel_hi:[0,0,0]
	v_mfma_scale_f32_16x16x128_f8f6f4 v[110:113], v[26:33], v[210:217], v[110:113], v199, v199 op_sel_hi:[0,0,0]
	v_mfma_scale_f32_16x16x128_f8f6f4 v[102:105], v[26:33], v[218:225], v[102:105], v199, v199 op_sel_hi:[0,0,0]
	v_mfma_scale_f32_16x16x128_f8f6f4 v[98:101], v[182:189], v[218:225], v[98:101], v199, v199 op_sel_hi:[0,0,0]
	v_mfma_scale_f32_16x16x128_f8f6f4 v[130:133], v[18:25], v[218:225], v[130:133], v199, v199 op_sel_hi:[0,0,0]
	v_mfma_scale_f32_16x16x128_f8f6f4 v[134:137], v[2:9], v[218:225], v[134:137], v199, v199 op_sel_hi:[0,0,0]
	s_setprio 0
	s_barrier
	s_mov_b32 m0, s68
	v_lshl_add_u64 v[10:11], s[78:79], 0, v[164:165]
	s_add_u32 vcc_lo, s78, 0x20000
	ds_read_b128 v[202:205], v201 offset:16384
	ds_read_b128 v[206:209], v201 offset:17408
	ds_read_b128 v[210:213], v201 offset:18432
	ds_read_b128 v[214:217], v201 offset:19456
	ds_read_b128 v[218:221], v201 offset:20480
	ds_read_b128 v[222:225], v201 offset:21504
	ds_read_b128 v[226:229], v201 offset:22528
	ds_read_b128 v[230:233], v201 offset:23552
	global_load_lds_dwordx4 v[10:11], off
	v_lshl_add_u64 v[12:13], s[78:79], 0, v[168:169]
	s_mov_b32 m0, s69
	s_addc_u32 vcc_hi, s79, 0
	global_load_lds_dwordx4 v[12:13], off
	v_lshl_add_u64 v[14:15], vcc, 0, v[164:165]
	s_mov_b32 m0, s77
	v_lshl_add_u64 v[16:17], s[82:83], 0, v[166:167]
	global_load_lds_dwordx4 v[14:15], off
	v_lshl_add_u64 v[14:15], vcc, 0, v[168:169]
	s_mov_b32 m0, s84
	s_nop 0
	global_load_lds_dwordx4 v[14:15], off
	v_lshl_add_u64 v[14:15], s[82:83], 0, v[162:163]
	s_mov_b32 m0, s33
	s_nop 0
	global_load_lds_dwordx4 v[14:15], off
	s_mov_b32 m0, s85
	s_nop 0
	global_load_lds_dwordx4 v[16:17], off
	s_waitcnt vmcnt(8)
	s_waitcnt lgkmcnt(0)
	s_barrier
	s_setprio 1
	s_waitcnt lgkmcnt(0)
	v_mfma_scale_f32_16x16x128_f8f6f4 v[94:97], v[2:9], v[202:209], v[94:97], v199, v199 op_sel_hi:[0,0,0]
	v_mfma_scale_f32_16x16x128_f8f6f4 v[90:93], v[18:25], v[202:209], v[90:93], v199, v199 op_sel_hi:[0,0,0]
	v_mfma_scale_f32_16x16x128_f8f6f4 v[58:61], v[182:189], v[202:209], v[58:61], v199, v199 op_sel_hi:[0,0,0]
	v_mfma_scale_f32_16x16x128_f8f6f4 v[62:65], v[26:33], v[202:209], v[62:65], v199, v199 op_sel_hi:[0,0,0]
	v_mfma_scale_f32_16x16x128_f8f6f4 v[54:57], v[26:33], v[210:217], v[54:57], v199, v199 op_sel_hi:[0,0,0]
	v_mfma_scale_f32_16x16x128_f8f6f4 v[50:53], v[182:189], v[210:217], v[50:53], v199, v199 op_sel_hi:[0,0,0]
	v_mfma_scale_f32_16x16x128_f8f6f4 v[82:85], v[18:25], v[210:217], v[82:85], v199, v199 op_sel_hi:[0,0,0]
	v_mfma_scale_f32_16x16x128_f8f6f4 v[86:89], v[2:9], v[210:217], v[86:89], v199, v199 op_sel_hi:[0,0,0]
	s_setprio 0
	s_setprio 1
	v_mfma_scale_f32_16x16x128_f8f6f4 v[78:81], v[2:9], v[218:225], v[78:81], v199, v199 op_sel_hi:[0,0,0]
	v_mfma_scale_f32_16x16x128_f8f6f4 v[74:77], v[18:25], v[218:225], v[74:77], v199, v199 op_sel_hi:[0,0,0]
	v_mfma_scale_f32_16x16x128_f8f6f4 v[42:45], v[182:189], v[218:225], v[42:45], v199, v199 op_sel_hi:[0,0,0]
	v_mfma_scale_f32_16x16x128_f8f6f4 v[46:49], v[26:33], v[218:225], v[46:49], v199, v199 op_sel_hi:[0,0,0]
	v_mfma_scale_f32_16x16x128_f8f6f4 v[38:41], v[26:33], v[226:233], v[38:41], v199, v199 op_sel_hi:[0,0,0]
	v_mfma_scale_f32_16x16x128_f8f6f4 v[34:37], v[182:189], v[226:233], v[34:37], v199, v199 op_sel_hi:[0,0,0]
	v_mfma_scale_f32_16x16x128_f8f6f4 v[66:69], v[18:25], v[226:233], v[66:69], v199, v199 op_sel_hi:[0,0,0]
	v_mfma_scale_f32_16x16x128_f8f6f4 v[70:73], v[2:9], v[226:233], v[70:73], v199, v199 op_sel_hi:[0,0,0]
	s_setprio 0
	s_barrier
	ds_read_b128 v[18:21], v200 offset:32768
	ds_read_b128 v[22:25], v200 offset:33792
	ds_read_b128 v[26:29], v200 offset:34816
	ds_read_b128 v[30:33], v200 offset:35840
	ds_read_b128 v[2:5], v200 offset:49152
	ds_read_b128 v[6:9], v200 offset:50176
	ds_read_b128 v[182:185], v200 offset:51200
	ds_read_b128 v[186:189], v200 offset:52224
	s_add_u32 s82, s82, 0x20000
	s_addc_u32 s83, s83, 0
	s_mov_b32 m0, s86
	v_lshl_add_u64 v[234:235], s[82:83], 0, v[162:163]
	ds_read_b128 v[202:205], v201 offset:32768
	ds_read_b128 v[206:209], v201 offset:33792
	ds_read_b128 v[210:213], v201 offset:34816
	ds_read_b128 v[214:217], v201 offset:35840
	ds_read_b128 v[218:221], v201 offset:36864
	ds_read_b128 v[222:225], v201 offset:37888
	ds_read_b128 v[226:229], v201 offset:38912
	ds_read_b128 v[230:233], v201 offset:39936
	global_load_lds_dwordx4 v[234:235], off
	v_lshl_add_u64 v[234:235], s[82:83], 0, v[166:167]
	s_mov_b32 m0, s87
	s_nop 0
	global_load_lds_dwordx4 v[234:235], off
	s_waitcnt vmcnt(8)
	s_waitcnt lgkmcnt(0)
	s_barrier
	s_setprio 1
	s_waitcnt lgkmcnt(0)
	v_mfma_scale_f32_16x16x128_f8f6f4 v[158:161], v[18:25], v[202:209], v[158:161], v199, v199 op_sel_hi:[0,0,0]
	v_mfma_scale_f32_16x16x128_f8f6f4 v[154:157], v[26:33], v[202:209], v[154:157], v199, v199 op_sel_hi:[0,0,0]
	v_mfma_scale_f32_16x16x128_f8f6f4 v[122:125], v[182:189], v[202:209], v[122:125], v199, v199 op_sel_hi:[0,0,0]
	v_mfma_scale_f32_16x16x128_f8f6f4 v[126:129], v[2:9], v[202:209], v[126:129], v199, v199 op_sel_hi:[0,0,0]
	v_mfma_scale_f32_16x16x128_f8f6f4 v[118:121], v[2:9], v[210:217], v[118:121], v199, v199 op_sel_hi:[0,0,0]
	v_mfma_scale_f32_16x16x128_f8f6f4 v[114:117], v[182:189], v[210:217], v[114:117], v199, v199 op_sel_hi:[0,0,0]
	v_mfma_scale_f32_16x16x128_f8f6f4 v[146:149], v[26:33], v[210:217], v[146:149], v199, v199 op_sel_hi:[0,0,0]
	v_mfma_scale_f32_16x16x128_f8f6f4 v[150:153], v[18:25], v[210:217], v[150:153], v199, v199 op_sel_hi:[0,0,0]
	s_setprio 0
	s_setprio 1
	v_mfma_scale_f32_16x16x128_f8f6f4 v[142:145], v[18:25], v[218:225], v[142:145], v199, v199 op_sel_hi:[0,0,0]
	v_mfma_scale_f32_16x16x128_f8f6f4 v[138:141], v[26:33], v[218:225], v[138:141], v199, v199 op_sel_hi:[0,0,0]
	v_mfma_scale_f32_16x16x128_f8f6f4 v[106:109], v[182:189], v[218:225], v[106:109], v199, v199 op_sel_hi:[0,0,0]
	v_mfma_scale_f32_16x16x128_f8f6f4 v[110:113], v[2:9], v[218:225], v[110:113], v199, v199 op_sel_hi:[0,0,0]
	v_mfma_scale_f32_16x16x128_f8f6f4 v[102:105], v[2:9], v[226:233], v[102:105], v199, v199 op_sel_hi:[0,0,0]
	v_mfma_scale_f32_16x16x128_f8f6f4 v[98:101], v[182:189], v[226:233], v[98:101], v199, v199 op_sel_hi:[0,0,0]
	v_mfma_scale_f32_16x16x128_f8f6f4 v[130:133], v[26:33], v[226:233], v[130:133], v199, v199 op_sel_hi:[0,0,0]
	v_mfma_scale_f32_16x16x128_f8f6f4 v[134:137], v[18:25], v[226:233], v[134:137], v199, v199 op_sel_hi:[0,0,0]
	s_setprio 0
	s_barrier
	s_mov_b32 m0, s89
	v_lshl_add_u64 v[10:11], v[10:11], 0, s[42:43]
	s_add_u32 s78, s78, 0x20080
	ds_read_b128 v[202:205], v201 offset:49152
	ds_read_b128 v[206:209], v201 offset:50176
	ds_read_b128 v[210:213], v201 offset:51200
	ds_read_b128 v[214:217], v201 offset:52224
	ds_read_b128 v[218:221], v201 offset:53248
	ds_read_b128 v[222:225], v201 offset:54272
	ds_read_b128 v[226:229], v201 offset:55296
	ds_read_b128 v[230:233], v201 offset:56320
	global_load_lds_dwordx4 v[10:11], off
	v_lshl_add_u64 v[10:11], v[12:13], 0, s[42:43]
	s_mov_b32 m0, s90
	s_addc_u32 s79, s79, 0
	global_load_lds_dwordx4 v[10:11], off
	v_lshl_add_u64 v[10:11], s[78:79], 0, v[164:165]
	s_mov_b32 m0, s93
	s_nop 0
	global_load_lds_dwordx4 v[10:11], off
	v_lshl_add_u64 v[10:11], s[78:79], 0, v[168:169]
	s_mov_b32 m0, s95
	s_nop 0
	global_load_lds_dwordx4 v[10:11], off
	v_lshl_add_u64 v[10:11], v[14:15], 0, s[42:43]
	s_mov_b32 m0, s91
	s_nop 0
	global_load_lds_dwordx4 v[10:11], off
	v_lshl_add_u64 v[10:11], v[16:17], 0, s[42:43]
	s_mov_b32 m0, s92
	s_nop 0
	global_load_lds_dwordx4 v[10:11], off
	s_waitcnt vmcnt(8)
	s_waitcnt lgkmcnt(0)
	s_barrier
	s_setprio 1
	s_waitcnt lgkmcnt(0)
	v_mfma_scale_f32_16x16x128_f8f6f4 v[94:97], v[18:25], v[202:209], v[94:97], v199, v199 op_sel_hi:[0,0,0]
	v_mfma_scale_f32_16x16x128_f8f6f4 v[90:93], v[26:33], v[202:209], v[90:93], v199, v199 op_sel_hi:[0,0,0]
	v_mfma_scale_f32_16x16x128_f8f6f4 v[58:61], v[182:189], v[202:209], v[58:61], v199, v199 op_sel_hi:[0,0,0]
	v_mfma_scale_f32_16x16x128_f8f6f4 v[62:65], v[2:9], v[202:209], v[62:65], v199, v199 op_sel_hi:[0,0,0]
	v_mfma_scale_f32_16x16x128_f8f6f4 v[54:57], v[2:9], v[210:217], v[54:57], v199, v199 op_sel_hi:[0,0,0]
	v_mfma_scale_f32_16x16x128_f8f6f4 v[50:53], v[182:189], v[210:217], v[50:53], v199, v199 op_sel_hi:[0,0,0]
	v_mfma_scale_f32_16x16x128_f8f6f4 v[82:85], v[26:33], v[210:217], v[82:85], v199, v199 op_sel_hi:[0,0,0]
	v_mfma_scale_f32_16x16x128_f8f6f4 v[86:89], v[18:25], v[210:217], v[86:89], v199, v199 op_sel_hi:[0,0,0]
	s_setprio 0
	s_setprio 1
	v_mfma_scale_f32_16x16x128_f8f6f4 v[78:81], v[18:25], v[218:225], v[78:81], v199, v199 op_sel_hi:[0,0,0]
	v_mfma_scale_f32_16x16x128_f8f6f4 v[74:77], v[26:33], v[218:225], v[74:77], v199, v199 op_sel_hi:[0,0,0]
	v_mfma_scale_f32_16x16x128_f8f6f4 v[42:45], v[182:189], v[218:225], v[42:45], v199, v199 op_sel_hi:[0,0,0]
	v_mfma_scale_f32_16x16x128_f8f6f4 v[46:49], v[2:9], v[218:225], v[46:49], v199, v199 op_sel_hi:[0,0,0]
	v_mfma_scale_f32_16x16x128_f8f6f4 v[38:41], v[2:9], v[226:233], v[38:41], v199, v199 op_sel_hi:[0,0,0]
	v_mfma_scale_f32_16x16x128_f8f6f4 v[34:37], v[182:189], v[226:233], v[34:37], v199, v199 op_sel_hi:[0,0,0]
	v_mfma_scale_f32_16x16x128_f8f6f4 v[66:69], v[26:33], v[226:233], v[66:69], v199, v199 op_sel_hi:[0,0,0]
	v_mfma_scale_f32_16x16x128_f8f6f4 v[70:73], v[18:25], v[226:233], v[70:73], v199, v199 op_sel_hi:[0,0,0]
	s_setprio 0
	s_barrier
	s_add_i32 s62, s62, 2
	s_add_u32 s80, s80, 0x100
	s_addc_u32 s81, s81, 0
	s_add_u32 s8, s8, 0x100
	s_addc_u32 s9, s9, 0
	s_cmp_gt_u32 s62, 5
	s_cbranch_scc0 .LBB0_601
	s_and_b64 vcc, exec, s[44:45]
	s_cbranch_vccz .LBB0_604
	s_barrier

.LBB0_616:
	ds_read_b128 v[18:21], v188
	ds_read_b128 v[22:25], v188 offset:1024
	ds_read_b128 v[26:29], v188 offset:2048
	ds_read_b128 v[30:33], v188 offset:3072
	ds_read_b128 v[2:5], v188 offset:16384
	ds_read_b128 v[6:9], v188 offset:17408
	ds_read_b128 v[10:13], v188 offset:18432
	ds_read_b128 v[14:17], v188 offset:19456
	s_ashr_i32 s55, s54, 31
	s_lshl_b64 s[62:63], s[54:55], 17
	s_add_u32 s72, s36, s62
	s_addc_u32 s73, s37, s63
	s_and_b64 s[62:63], s[2:3], exec
	s_cselect_b32 s85, s73, s79
	s_cselect_b32 s84, s72, s78
	s_ashr_i32 s53, s52, 31
	s_lshl_b64 s[62:63], s[52:53], 17
	s_add_u32 s74, s94, s62
	v_readlane_b32 s5, v254, 8
	s_addc_u32 s75, s5, s63
	s_and_b64 s[62:63], s[2:3], exec
	s_cselect_b32 s83, s75, s81
	s_cselect_b32 s82, s74, s80
	s_add_u32 s62, s78, 0x10080
	s_addc_u32 s63, s79, 0
	s_mov_b32 m0, s96
	v_lshl_add_u64 v[174:175], s[62:63], 0, v[166:167]
	ds_read_b128 v[196:199], v189
	ds_read_b128 v[200:203], v189 offset:1024
	ds_read_b128 v[204:207], v189 offset:2048
	ds_read_b128 v[208:211], v189 offset:3072
	ds_read_b128 v[212:215], v189 offset:4096
	ds_read_b128 v[216:219], v189 offset:5120
	ds_read_b128 v[220:223], v189 offset:6144
	ds_read_b128 v[224:227], v189 offset:7168
	global_load_lds_dwordx4 v[174:175], off
	v_lshl_add_u64 v[174:175], s[62:63], 0, v[168:169]
	s_mov_b32 m0, s97
	s_nop 0
	global_load_lds_dwordx4 v[174:175], off
	s_waitcnt vmcnt(8)
	s_waitcnt lgkmcnt(0)
	s_barrier
	s_setprio 1
	s_waitcnt lgkmcnt(0)
	v_mfma_scale_f32_16x16x128_f8f6f4 v[158:161], v[18:25], v[196:203], 0, v195, v195 op_sel_hi:[0,0,0]
	v_mfma_scale_f32_16x16x128_f8f6f4 v[154:157], v[26:33], v[196:203], 0, v195, v195 op_sel_hi:[0,0,0]
	v_mfma_scale_f32_16x16x128_f8f6f4 v[122:125], v[10:17], v[196:203], 0, v195, v195 op_sel_hi:[0,0,0]
	v_mfma_scale_f32_16x16x128_f8f6f4 v[126:129], v[2:9], v[196:203], 0, v195, v195 op_sel_hi:[0,0,0]
	v_mfma_scale_f32_16x16x128_f8f6f4 v[118:121], v[2:9], v[204:211], 0, v195, v195 op_sel_hi:[0,0,0]
	v_mfma_scale_f32_16x16x128_f8f6f4 v[114:117], v[10:17], v[204:211], 0, v195, v195 op_sel_hi:[0,0,0]
	v_mfma_scale_f32_16x16x128_f8f6f4 v[146:149], v[26:33], v[204:211], 0, v195, v195 op_sel_hi:[0,0,0]
	v_mfma_scale_f32_16x16x128_f8f6f4 v[150:153], v[18:25], v[204:211], 0, v195, v195 op_sel_hi:[0,0,0]
	s_setprio 0
	s_setprio 1
	v_mfma_scale_f32_16x16x128_f8f6f4 v[142:145], v[18:25], v[212:219], 0, v195, v195 op_sel_hi:[0,0,0]
	v_mfma_scale_f32_16x16x128_f8f6f4 v[138:141], v[26:33], v[212:219], 0, v195, v195 op_sel_hi:[0,0,0]
	v_mfma_scale_f32_16x16x128_f8f6f4 v[106:109], v[10:17], v[212:219], 0, v195, v195 op_sel_hi:[0,0,0]
	v_mfma_scale_f32_16x16x128_f8f6f4 v[110:113], v[2:9], v[212:219], 0, v195, v195 op_sel_hi:[0,0,0]
	v_mfma_scale_f32_16x16x128_f8f6f4 v[102:105], v[2:9], v[220:227], 0, v195, v195 op_sel_hi:[0,0,0]
	v_mfma_scale_f32_16x16x128_f8f6f4 v[98:101], v[10:17], v[220:227], 0, v195, v195 op_sel_hi:[0,0,0]
	v_mfma_scale_f32_16x16x128_f8f6f4 v[130:133], v[26:33], v[220:227], 0, v195, v195 op_sel_hi:[0,0,0]
	v_mfma_scale_f32_16x16x128_f8f6f4 v[134:137], v[18:25], v[220:227], 0, v195, v195 op_sel_hi:[0,0,0]
	s_setprio 0
	s_barrier
	v_lshl_add_u64 v[174:175], s[80:81], 0, v[162:163]
	s_mov_b32 m0, s61
	v_lshl_add_u64 v[176:177], v[174:175], 0, s[46:47]
	ds_read_b128 v[196:199], v189 offset:16384
	ds_read_b128 v[200:203], v189 offset:17408
	ds_read_b128 v[204:207], v189 offset:18432
	ds_read_b128 v[208:211], v189 offset:19456
	ds_read_b128 v[212:215], v189 offset:20480
	ds_read_b128 v[216:219], v189 offset:21504
	ds_read_b128 v[220:223], v189 offset:22528
	ds_read_b128 v[224:227], v189 offset:23552
	global_load_lds_dwordx4 v[176:177], off
	v_lshl_add_u64 v[176:177], s[80:81], 0, v[164:165]
	s_add_u32 s62, s80, 0x10100
	v_lshl_add_u64 v[182:183], v[176:177], 0, s[46:47]
	s_mov_b32 m0, s68
	s_addc_u32 s63, s81, 0
	global_load_lds_dwordx4 v[182:183], off
	v_lshl_add_u64 v[182:183], s[62:63], 0, v[162:163]
	s_mov_b32 m0, s69
	s_nop 0
	global_load_lds_dwordx4 v[182:183], off
	v_lshl_add_u64 v[182:183], s[62:63], 0, v[164:165]
	s_mov_b32 m0, s77
	s_nop 0
	global_load_lds_dwordx4 v[182:183], off
	v_lshl_add_u64 v[182:183], s[78:79], 0, v[166:167]
	v_lshl_add_u64 v[184:185], v[182:183], 0, s[46:47]
	s_mov_b32 m0, s51
	s_nop 0
	global_load_lds_dwordx4 v[184:185], off
	v_lshl_add_u64 v[184:185], s[78:79], 0, v[168:169]
	v_lshl_add_u64 v[228:229], v[184:185], 0, s[46:47]
	s_mov_b32 m0, s86
	s_nop 0
	global_load_lds_dwordx4 v[228:229], off
	s_waitcnt vmcnt(8)
	s_waitcnt lgkmcnt(0)
	s_barrier
	s_setprio 1
	s_waitcnt lgkmcnt(0)
	v_mfma_scale_f32_16x16x128_f8f6f4 v[94:97], v[18:25], v[196:203], 0, v195, v195 op_sel_hi:[0,0,0]
	v_mfma_scale_f32_16x16x128_f8f6f4 v[90:93], v[26:33], v[196:203], 0, v195, v195 op_sel_hi:[0,0,0]
	v_mfma_scale_f32_16x16x128_f8f6f4 v[58:61], v[10:17], v[196:203], 0, v195, v195 op_sel_hi:[0,0,0]
	v_mfma_scale_f32_16x16x128_f8f6f4 v[62:65], v[2:9], v[196:203], 0, v195, v195 op_sel_hi:[0,0,0]
	v_mfma_scale_f32_16x16x128_f8f6f4 v[54:57], v[2:9], v[204:211], 0, v195, v195 op_sel_hi:[0,0,0]
	v_mfma_scale_f32_16x16x128_f8f6f4 v[50:53], v[10:17], v[204:211], 0, v195, v195 op_sel_hi:[0,0,0]
	v_mfma_scale_f32_16x16x128_f8f6f4 v[82:85], v[26:33], v[204:211], 0, v195, v195 op_sel_hi:[0,0,0]
	v_mfma_scale_f32_16x16x128_f8f6f4 v[86:89], v[18:25], v[204:211], 0, v195, v195 op_sel_hi:[0,0,0]
	s_setprio 0
	s_setprio 1
	v_mfma_scale_f32_16x16x128_f8f6f4 v[78:81], v[18:25], v[212:219], 0, v195, v195 op_sel_hi:[0,0,0]
	v_mfma_scale_f32_16x16x128_f8f6f4 v[74:77], v[26:33], v[212:219], 0, v195, v195 op_sel_hi:[0,0,0]
	v_mfma_scale_f32_16x16x128_f8f6f4 v[42:45], v[10:17], v[212:219], 0, v195, v195 op_sel_hi:[0,0,0]
	v_mfma_scale_f32_16x16x128_f8f6f4 v[46:49], v[2:9], v[212:219], 0, v195, v195 op_sel_hi:[0,0,0]
	v_mfma_scale_f32_16x16x128_f8f6f4 v[38:41], v[2:9], v[220:227], 0, v195, v195 op_sel_hi:[0,0,0]
	v_mfma_scale_f32_16x16x128_f8f6f4 v[34:37], v[10:17], v[220:227], 0, v195, v195 op_sel_hi:[0,0,0]
	v_mfma_scale_f32_16x16x128_f8f6f4 v[66:69], v[26:33], v[220:227], 0, v195, v195 op_sel_hi:[0,0,0]
	v_mfma_scale_f32_16x16x128_f8f6f4 v[70:73], v[18:25], v[220:227], 0, v195, v195 op_sel_hi:[0,0,0]
	s_setprio 0
	s_barrier
	ds_read_b128 v[2:5], v188 offset:32768
	ds_read_b128 v[6:9], v188 offset:33792
	ds_read_b128 v[10:13], v188 offset:34816
	ds_read_b128 v[14:17], v188 offset:35840
	ds_read_b128 v[18:21], v188 offset:49152
	ds_read_b128 v[22:25], v188 offset:50176
	ds_read_b128 v[26:29], v188 offset:51200
	ds_read_b128 v[30:33], v188 offset:52224
	s_add_u32 s62, s78, 0x10100
	s_addc_u32 s63, s79, 0
	s_mov_b32 m0, s87
	v_lshl_add_u64 v[228:229], s[62:63], 0, v[166:167]
	ds_read_b128 v[196:199], v189 offset:32768
	ds_read_b128 v[200:203], v189 offset:33792
	ds_read_b128 v[204:207], v189 offset:34816
	ds_read_b128 v[208:211], v189 offset:35840
	ds_read_b128 v[212:215], v189 offset:36864
	ds_read_b128 v[216:219], v189 offset:37888
	ds_read_b128 v[220:223], v189 offset:38912
	ds_read_b128 v[224:227], v189 offset:39936
	global_load_lds_dwordx4 v[228:229], off
	v_lshl_add_u64 v[228:229], s[62:63], 0, v[168:169]
	s_mov_b32 m0, s88
	s_nop 0
	global_load_lds_dwordx4 v[228:229], off
	s_waitcnt vmcnt(8)
	s_waitcnt lgkmcnt(0)
	s_barrier
	s_setprio 1
	s_waitcnt lgkmcnt(0)
	v_mfma_scale_f32_16x16x128_f8f6f4 v[158:161], v[2:9], v[196:203], v[158:161], v195, v195 op_sel_hi:[0,0,0]
	v_mfma_scale_f32_16x16x128_f8f6f4 v[154:157], v[10:17], v[196:203], v[154:157], v195, v195 op_sel_hi:[0,0,0]
	v_mfma_scale_f32_16x16x128_f8f6f4 v[122:125], v[26:33], v[196:203], v[122:125], v195, v195 op_sel_hi:[0,0,0]
	v_mfma_scale_f32_16x16x128_f8f6f4 v[126:129], v[18:25], v[196:203], v[126:129], v195, v195 op_sel_hi:[0,0,0]
	v_mfma_scale_f32_16x16x128_f8f6f4 v[118:121], v[18:25], v[204:211], v[118:121], v195, v195 op_sel_hi:[0,0,0]
	v_mfma_scale_f32_16x16x128_f8f6f4 v[114:117], v[26:33], v[204:211], v[114:117], v195, v195 op_sel_hi:[0,0,0]
	v_mfma_scale_f32_16x16x128_f8f6f4 v[146:149], v[10:17], v[204:211], v[146:149], v195, v195 op_sel_hi:[0,0,0]
	v_mfma_scale_f32_16x16x128_f8f6f4 v[150:153], v[2:9], v[204:211], v[150:153], v195, v195 op_sel_hi:[0,0,0]
	s_setprio 0
	s_setprio 1
	v_mfma_scale_f32_16x16x128_f8f6f4 v[142:145], v[2:9], v[212:219], v[142:145], v195, v195 op_sel_hi:[0,0,0]
	v_mfma_scale_f32_16x16x128_f8f6f4 v[138:141], v[10:17], v[212:219], v[138:141], v195, v195 op_sel_hi:[0,0,0]
	v_mfma_scale_f32_16x16x128_f8f6f4 v[106:109], v[26:33], v[212:219], v[106:109], v195, v195 op_sel_hi:[0,0,0]
	v_mfma_scale_f32_16x16x128_f8f6f4 v[110:113], v[18:25], v[212:219], v[110:113], v195, v195 op_sel_hi:[0,0,0]
	v_mfma_scale_f32_16x16x128_f8f6f4 v[102:105], v[18:25], v[220:227], v[102:105], v195, v195 op_sel_hi:[0,0,0]
	v_mfma_scale_f32_16x16x128_f8f6f4 v[98:101], v[26:33], v[220:227], v[98:101], v195, v195 op_sel_hi:[0,0,0]
	v_mfma_scale_f32_16x16x128_f8f6f4 v[130:133], v[10:17], v[220:227], v[130:133], v195, v195 op_sel_hi:[0,0,0]
	v_mfma_scale_f32_16x16x128_f8f6f4 v[134:137], v[2:9], v[220:227], v[134:137], v195, v195 op_sel_hi:[0,0,0]
	s_setprio 0
	s_barrier
	s_mov_b32 m0, s89
	v_lshl_add_u64 v[174:175], v[174:175], 0, s[48:49]
	s_add_u32 s62, s80, 0x10180
	ds_read_b128 v[196:199], v189 offset:49152
	ds_read_b128 v[200:203], v189 offset:50176
	ds_read_b128 v[204:207], v189 offset:51200
	ds_read_b128 v[208:211], v189 offset:52224
	ds_read_b128 v[212:215], v189 offset:53248
	ds_read_b128 v[216:219], v189 offset:54272
	ds_read_b128 v[220:223], v189 offset:55296
	ds_read_b128 v[224:227], v189 offset:56320
	global_load_lds_dwordx4 v[174:175], off
	v_lshl_add_u64 v[174:175], v[176:177], 0, s[48:49]
	s_mov_b32 m0, s90
	s_addc_u32 s63, s81, 0
	global_load_lds_dwordx4 v[174:175], off
	v_lshl_add_u64 v[174:175], s[62:63], 0, v[162:163]
	s_mov_b32 m0, s93
	s_nop 0
	global_load_lds_dwordx4 v[174:175], off
	v_lshl_add_u64 v[174:175], s[62:63], 0, v[164:165]
	s_mov_b32 m0, s95
	s_nop 0
	global_load_lds_dwordx4 v[174:175], off
	v_lshl_add_u64 v[174:175], v[182:183], 0, s[48:49]
	s_mov_b32 m0, s91
	s_nop 0
	global_load_lds_dwordx4 v[174:175], off
	v_lshl_add_u64 v[174:175], v[184:185], 0, s[48:49]
	s_mov_b32 m0, s92
	s_nop 0
	global_load_lds_dwordx4 v[174:175], off
	s_waitcnt vmcnt(8)
	s_waitcnt lgkmcnt(0)
	s_barrier
	s_setprio 1
	s_waitcnt lgkmcnt(0)
	v_mfma_scale_f32_16x16x128_f8f6f4 v[94:97], v[2:9], v[196:203], v[94:97], v195, v195 op_sel_hi:[0,0,0]
	v_mfma_scale_f32_16x16x128_f8f6f4 v[90:93], v[10:17], v[196:203], v[90:93], v195, v195 op_sel_hi:[0,0,0]
	v_mfma_scale_f32_16x16x128_f8f6f4 v[58:61], v[26:33], v[196:203], v[58:61], v195, v195 op_sel_hi:[0,0,0]
	v_mfma_scale_f32_16x16x128_f8f6f4 v[62:65], v[18:25], v[196:203], v[62:65], v195, v195 op_sel_hi:[0,0,0]
	v_mfma_scale_f32_16x16x128_f8f6f4 v[54:57], v[18:25], v[204:211], v[54:57], v195, v195 op_sel_hi:[0,0,0]
	v_mfma_scale_f32_16x16x128_f8f6f4 v[50:53], v[26:33], v[204:211], v[50:53], v195, v195 op_sel_hi:[0,0,0]
	v_mfma_scale_f32_16x16x128_f8f6f4 v[82:85], v[10:17], v[204:211], v[82:85], v195, v195 op_sel_hi:[0,0,0]
	v_mfma_scale_f32_16x16x128_f8f6f4 v[86:89], v[2:9], v[204:211], v[86:89], v195, v195 op_sel_hi:[0,0,0]
	s_setprio 0
	s_setprio 1
	v_mfma_scale_f32_16x16x128_f8f6f4 v[78:81], v[2:9], v[212:219], v[78:81], v195, v195 op_sel_hi:[0,0,0]
	v_mfma_scale_f32_16x16x128_f8f6f4 v[74:77], v[10:17], v[212:219], v[74:77], v195, v195 op_sel_hi:[0,0,0]
	v_mfma_scale_f32_16x16x128_f8f6f4 v[42:45], v[26:33], v[212:219], v[42:45], v195, v195 op_sel_hi:[0,0,0]
	v_mfma_scale_f32_16x16x128_f8f6f4 v[46:49], v[18:25], v[212:219], v[46:49], v195, v195 op_sel_hi:[0,0,0]
	v_mfma_scale_f32_16x16x128_f8f6f4 v[38:41], v[18:25], v[220:227], v[38:41], v195, v195 op_sel_hi:[0,0,0]
	v_mfma_scale_f32_16x16x128_f8f6f4 v[34:37], v[26:33], v[220:227], v[34:37], v195, v195 op_sel_hi:[0,0,0]
	v_mfma_scale_f32_16x16x128_f8f6f4 v[66:69], v[10:17], v[220:227], v[66:69], v195, v195 op_sel_hi:[0,0,0]
	v_mfma_scale_f32_16x16x128_f8f6f4 v[70:73], v[2:9], v[220:227], v[70:73], v195, v195 op_sel_hi:[0,0,0]
	s_setprio 0
	s_barrier
	ds_read_b128 v[2:5], v188
	ds_read_b128 v[6:9], v188 offset:1024
	ds_read_b128 v[10:13], v188 offset:2048
	ds_read_b128 v[14:17], v188 offset:3072
	ds_read_b128 v[18:21], v188 offset:16384
	ds_read_b128 v[22:25], v188 offset:17408
	ds_read_b128 v[26:29], v188 offset:18432
	ds_read_b128 v[30:33], v188 offset:19456
	s_add_u32 s62, s78, 0x10180
	s_addc_u32 s63, s79, 0
	s_mov_b32 m0, s96
	v_lshl_add_u64 v[174:175], s[62:63], 0, v[166:167]
	ds_read_b128 v[196:199], v189
	ds_read_b128 v[200:203], v189 offset:1024
	ds_read_b128 v[204:207], v189 offset:2048
	ds_read_b128 v[208:211], v189 offset:3072
	ds_read_b128 v[212:215], v189 offset:4096
	ds_read_b128 v[216:219], v189 offset:5120
	ds_read_b128 v[220:223], v189 offset:6144
	ds_read_b128 v[224:227], v189 offset:7168
	global_load_lds_dwordx4 v[174:175], off
	v_lshl_add_u64 v[174:175], s[62:63], 0, v[168:169]
	s_mov_b32 m0, s97
	s_nop 0
	global_load_lds_dwordx4 v[174:175], off
	s_waitcnt vmcnt(8)
	s_waitcnt lgkmcnt(0)
	s_barrier
	s_setprio 1
	s_waitcnt lgkmcnt(0)
	v_mfma_scale_f32_16x16x128_f8f6f4 v[158:161], v[2:9], v[196:203], v[158:161], v195, v195 op_sel_hi:[0,0,0]
	v_mfma_scale_f32_16x16x128_f8f6f4 v[154:157], v[10:17], v[196:203], v[154:157], v195, v195 op_sel_hi:[0,0,0]
	v_mfma_scale_f32_16x16x128_f8f6f4 v[122:125], v[26:33], v[196:203], v[122:125], v195, v195 op_sel_hi:[0,0,0]
	v_mfma_scale_f32_16x16x128_f8f6f4 v[126:129], v[18:25], v[196:203], v[126:129], v195, v195 op_sel_hi:[0,0,0]
	v_mfma_scale_f32_16x16x128_f8f6f4 v[118:121], v[18:25], v[204:211], v[118:121], v195, v195 op_sel_hi:[0,0,0]
	v_mfma_scale_f32_16x16x128_f8f6f4 v[114:117], v[26:33], v[204:211], v[114:117], v195, v195 op_sel_hi:[0,0,0]
	v_mfma_scale_f32_16x16x128_f8f6f4 v[146:149], v[10:17], v[204:211], v[146:149], v195, v195 op_sel_hi:[0,0,0]
	v_mfma_scale_f32_16x16x128_f8f6f4 v[150:153], v[2:9], v[204:211], v[150:153], v195, v195 op_sel_hi:[0,0,0]
	s_setprio 0
	s_setprio 1
	v_mfma_scale_f32_16x16x128_f8f6f4 v[142:145], v[2:9], v[212:219], v[142:145], v195, v195 op_sel_hi:[0,0,0]
	v_mfma_scale_f32_16x16x128_f8f6f4 v[138:141], v[10:17], v[212:219], v[138:141], v195, v195 op_sel_hi:[0,0,0]
	v_mfma_scale_f32_16x16x128_f8f6f4 v[106:109], v[26:33], v[212:219], v[106:109], v195, v195 op_sel_hi:[0,0,0]
	v_mfma_scale_f32_16x16x128_f8f6f4 v[110:113], v[18:25], v[212:219], v[110:113], v195, v195 op_sel_hi:[0,0,0]
	v_mfma_scale_f32_16x16x128_f8f6f4 v[102:105], v[18:25], v[220:227], v[102:105], v195, v195 op_sel_hi:[0,0,0]
	v_mfma_scale_f32_16x16x128_f8f6f4 v[98:101], v[26:33], v[220:227], v[98:101], v195, v195 op_sel_hi:[0,0,0]
	v_mfma_scale_f32_16x16x128_f8f6f4 v[130:133], v[10:17], v[220:227], v[130:133], v195, v195 op_sel_hi:[0,0,0]
	v_mfma_scale_f32_16x16x128_f8f6f4 v[134:137], v[2:9], v[220:227], v[134:137], v195, v195 op_sel_hi:[0,0,0]
	s_setprio 0
	s_barrier
	s_mov_b32 m0, s61
	v_lshl_add_u64 v[174:175], s[82:83], 0, v[162:163]
	s_add_u32 s62, s82, 0x10000
	ds_read_b128 v[196:199], v189 offset:16384
	ds_read_b128 v[200:203], v189 offset:17408
	ds_read_b128 v[204:207], v189 offset:18432
	ds_read_b128 v[208:211], v189 offset:19456
	ds_read_b128 v[212:215], v189 offset:20480
	ds_read_b128 v[216:219], v189 offset:21504
	ds_read_b128 v[220:223], v189 offset:22528
	ds_read_b128 v[224:227], v189 offset:23552
	global_load_lds_dwordx4 v[174:175], off
	v_lshl_add_u64 v[176:177], s[82:83], 0, v[164:165]
	s_mov_b32 m0, s68
	s_addc_u32 s63, s83, 0
	global_load_lds_dwordx4 v[176:177], off
	v_lshl_add_u64 v[182:183], s[62:63], 0, v[162:163]
	s_mov_b32 m0, s69
	v_lshl_add_u64 v[184:185], s[84:85], 0, v[168:169]
	global_load_lds_dwordx4 v[182:183], off
	v_lshl_add_u64 v[182:183], s[62:63], 0, v[164:165]
	s_mov_b32 m0, s77
	s_nop 0
	global_load_lds_dwordx4 v[182:183], off
	v_lshl_add_u64 v[182:183], s[84:85], 0, v[166:167]
	s_mov_b32 m0, s51
	s_nop 0
	global_load_lds_dwordx4 v[182:183], off
	s_mov_b32 m0, s86
	s_nop 0
	global_load_lds_dwordx4 v[184:185], off
	s_waitcnt vmcnt(8)
	s_waitcnt lgkmcnt(0)
	s_barrier
	s_setprio 1
	s_waitcnt lgkmcnt(0)
	v_mfma_scale_f32_16x16x128_f8f6f4 v[94:97], v[2:9], v[196:203], v[94:97], v195, v195 op_sel_hi:[0,0,0]
	v_mfma_scale_f32_16x16x128_f8f6f4 v[90:93], v[10:17], v[196:203], v[90:93], v195, v195 op_sel_hi:[0,0,0]
	v_mfma_scale_f32_16x16x128_f8f6f4 v[58:61], v[26:33], v[196:203], v[58:61], v195, v195 op_sel_hi:[0,0,0]
	v_mfma_scale_f32_16x16x128_f8f6f4 v[62:65], v[18:25], v[196:203], v[62:65], v195, v195 op_sel_hi:[0,0,0]
	v_mfma_scale_f32_16x16x128_f8f6f4 v[54:57], v[18:25], v[204:211], v[54:57], v195, v195 op_sel_hi:[0,0,0]
	v_mfma_scale_f32_16x16x128_f8f6f4 v[50:53], v[26:33], v[204:211], v[50:53], v195, v195 op_sel_hi:[0,0,0]
	v_mfma_scale_f32_16x16x128_f8f6f4 v[82:85], v[10:17], v[204:211], v[82:85], v195, v195 op_sel_hi:[0,0,0]
	v_mfma_scale_f32_16x16x128_f8f6f4 v[86:89], v[2:9], v[204:211], v[86:89], v195, v195 op_sel_hi:[0,0,0]
	s_setprio 0
	s_setprio 1
	v_mfma_scale_f32_16x16x128_f8f6f4 v[78:81], v[2:9], v[212:219], v[78:81], v195, v195 op_sel_hi:[0,0,0]
	v_mfma_scale_f32_16x16x128_f8f6f4 v[74:77], v[10:17], v[212:219], v[74:77], v195, v195 op_sel_hi:[0,0,0]
	v_mfma_scale_f32_16x16x128_f8f6f4 v[42:45], v[26:33], v[212:219], v[42:45], v195, v195 op_sel_hi:[0,0,0]
	v_mfma_scale_f32_16x16x128_f8f6f4 v[46:49], v[18:25], v[212:219], v[46:49], v195, v195 op_sel_hi:[0,0,0]
	v_mfma_scale_f32_16x16x128_f8f6f4 v[38:41], v[18:25], v[220:227], v[38:41], v195, v195 op_sel_hi:[0,0,0]
	v_mfma_scale_f32_16x16x128_f8f6f4 v[34:37], v[26:33], v[220:227], v[34:37], v195, v195 op_sel_hi:[0,0,0]
	v_mfma_scale_f32_16x16x128_f8f6f4 v[66:69], v[10:17], v[220:227], v[66:69], v195, v195 op_sel_hi:[0,0,0]
	v_mfma_scale_f32_16x16x128_f8f6f4 v[70:73], v[2:9], v[220:227], v[70:73], v195, v195 op_sel_hi:[0,0,0]
	s_setprio 0
	s_barrier
	ds_read_b128 v[2:5], v188 offset:32768
	ds_read_b128 v[6:9], v188 offset:33792
	ds_read_b128 v[10:13], v188 offset:34816
	ds_read_b128 v[14:17], v188 offset:35840
	ds_read_b128 v[18:21], v188 offset:49152
	ds_read_b128 v[22:25], v188 offset:50176
	ds_read_b128 v[26:29], v188 offset:51200
	ds_read_b128 v[30:33], v188 offset:52224
	s_add_u32 s62, s84, 0x10000
	s_addc_u32 s63, s85, 0
	s_mov_b32 m0, s87
	v_lshl_add_u64 v[228:229], s[62:63], 0, v[166:167]
	ds_read_b128 v[196:199], v189 offset:32768
	ds_read_b128 v[200:203], v189 offset:33792
	ds_read_b128 v[204:207], v189 offset:34816
	ds_read_b128 v[208:211], v189 offset:35840
	ds_read_b128 v[212:215], v189 offset:36864
	ds_read_b128 v[216:219], v189 offset:37888
	ds_read_b128 v[220:223], v189 offset:38912
	ds_read_b128 v[224:227], v189 offset:39936
	global_load_lds_dwordx4 v[228:229], off
	v_lshl_add_u64 v[228:229], s[62:63], 0, v[168:169]
	s_mov_b32 m0, s88
	s_nop 0
	global_load_lds_dwordx4 v[228:229], off
	s_waitcnt vmcnt(8)
	s_waitcnt lgkmcnt(0)
	s_barrier
	s_setprio 1
	s_waitcnt lgkmcnt(0)
	v_mfma_scale_f32_16x16x128_f8f6f4 v[158:161], v[2:9], v[196:203], v[158:161], v195, v195 op_sel_hi:[0,0,0]
	v_mfma_scale_f32_16x16x128_f8f6f4 v[154:157], v[10:17], v[196:203], v[154:157], v195, v195 op_sel_hi:[0,0,0]
	v_mfma_scale_f32_16x16x128_f8f6f4 v[122:125], v[26:33], v[196:203], v[122:125], v195, v195 op_sel_hi:[0,0,0]
	v_mfma_scale_f32_16x16x128_f8f6f4 v[126:129], v[18:25], v[196:203], v[126:129], v195, v195 op_sel_hi:[0,0,0]
	v_mfma_scale_f32_16x16x128_f8f6f4 v[118:121], v[18:25], v[204:211], v[118:121], v195, v195 op_sel_hi:[0,0,0]
	v_mfma_scale_f32_16x16x128_f8f6f4 v[114:117], v[26:33], v[204:211], v[114:117], v195, v195 op_sel_hi:[0,0,0]
	v_mfma_scale_f32_16x16x128_f8f6f4 v[146:149], v[10:17], v[204:211], v[146:149], v195, v195 op_sel_hi:[0,0,0]
	v_mfma_scale_f32_16x16x128_f8f6f4 v[150:153], v[2:9], v[204:211], v[150:153], v195, v195 op_sel_hi:[0,0,0]
	s_setprio 0
	s_setprio 1
	v_mfma_scale_f32_16x16x128_f8f6f4 v[142:145], v[2:9], v[212:219], v[142:145], v195, v195 op_sel_hi:[0,0,0]
	v_mfma_scale_f32_16x16x128_f8f6f4 v[138:141], v[10:17], v[212:219], v[138:141], v195, v195 op_sel_hi:[0,0,0]
	v_mfma_scale_f32_16x16x128_f8f6f4 v[106:109], v[26:33], v[212:219], v[106:109], v195, v195 op_sel_hi:[0,0,0]
	v_mfma_scale_f32_16x16x128_f8f6f4 v[110:113], v[18:25], v[212:219], v[110:113], v195, v195 op_sel_hi:[0,0,0]
	v_mfma_scale_f32_16x16x128_f8f6f4 v[102:105], v[18:25], v[220:227], v[102:105], v195, v195 op_sel_hi:[0,0,0]
	v_mfma_scale_f32_16x16x128_f8f6f4 v[98:101], v[26:33], v[220:227], v[98:101], v195, v195 op_sel_hi:[0,0,0]
	v_mfma_scale_f32_16x16x128_f8f6f4 v[130:133], v[10:17], v[220:227], v[130:133], v195, v195 op_sel_hi:[0,0,0]
	v_mfma_scale_f32_16x16x128_f8f6f4 v[134:137], v[2:9], v[220:227], v[134:137], v195, v195 op_sel_hi:[0,0,0]
	s_setprio 0
	s_barrier
	s_mov_b32 m0, s89
	v_lshl_add_u64 v[174:175], v[174:175], 0, s[40:41]
	s_add_u32 s62, s82, 0x10080
	ds_read_b128 v[196:199], v189 offset:49152
	ds_read_b128 v[200:203], v189 offset:50176
	ds_read_b128 v[204:207], v189 offset:51200
	ds_read_b128 v[208:211], v189 offset:52224
	ds_read_b128 v[212:215], v189 offset:53248
	ds_read_b128 v[216:219], v189 offset:54272
	ds_read_b128 v[220:223], v189 offset:55296
	ds_read_b128 v[224:227], v189 offset:56320
	global_load_lds_dwordx4 v[174:175], off
	v_lshl_add_u64 v[174:175], v[176:177], 0, s[40:41]
	s_mov_b32 m0, s90
	s_addc_u32 s63, s83, 0
	global_load_lds_dwordx4 v[174:175], off
	v_lshl_add_u64 v[174:175], s[62:63], 0, v[162:163]
	s_mov_b32 m0, s93
	s_nop 0
	global_load_lds_dwordx4 v[174:175], off
	v_lshl_add_u64 v[174:175], s[62:63], 0, v[164:165]
	s_mov_b32 m0, s95
	s_nop 0
	global_load_lds_dwordx4 v[174:175], off
	v_lshl_add_u64 v[174:175], v[182:183], 0, s[40:41]
	s_mov_b32 m0, s91
	s_nop 0
	global_load_lds_dwordx4 v[174:175], off
	v_lshl_add_u64 v[174:175], v[184:185], 0, s[40:41]
	s_mov_b32 m0, s92
	s_nop 0
	global_load_lds_dwordx4 v[174:175], off
	s_waitcnt vmcnt(8)
	s_waitcnt lgkmcnt(0)
	s_barrier
	s_setprio 1
	s_waitcnt lgkmcnt(0)
	v_mfma_scale_f32_16x16x128_f8f6f4 v[94:97], v[2:9], v[196:203], v[94:97], v195, v195 op_sel_hi:[0,0,0]
	v_mfma_scale_f32_16x16x128_f8f6f4 v[90:93], v[10:17], v[196:203], v[90:93], v195, v195 op_sel_hi:[0,0,0]
	v_mfma_scale_f32_16x16x128_f8f6f4 v[58:61], v[26:33], v[196:203], v[58:61], v195, v195 op_sel_hi:[0,0,0]
	v_mfma_scale_f32_16x16x128_f8f6f4 v[62:65], v[18:25], v[196:203], v[62:65], v195, v195 op_sel_hi:[0,0,0]
	v_mfma_scale_f32_16x16x128_f8f6f4 v[54:57], v[18:25], v[204:211], v[54:57], v195, v195 op_sel_hi:[0,0,0]
	v_mfma_scale_f32_16x16x128_f8f6f4 v[50:53], v[26:33], v[204:211], v[50:53], v195, v195 op_sel_hi:[0,0,0]
	v_mfma_scale_f32_16x16x128_f8f6f4 v[82:85], v[10:17], v[204:211], v[82:85], v195, v195 op_sel_hi:[0,0,0]
	v_mfma_scale_f32_16x16x128_f8f6f4 v[86:89], v[2:9], v[204:211], v[86:89], v195, v195 op_sel_hi:[0,0,0]
	s_setprio 0
	s_setprio 1
	v_mfma_scale_f32_16x16x128_f8f6f4 v[78:81], v[2:9], v[212:219], v[78:81], v195, v195 op_sel_hi:[0,0,0]
	v_mfma_scale_f32_16x16x128_f8f6f4 v[74:77], v[10:17], v[212:219], v[74:77], v195, v195 op_sel_hi:[0,0,0]
	v_mfma_scale_f32_16x16x128_f8f6f4 v[42:45], v[26:33], v[212:219], v[42:45], v195, v195 op_sel_hi:[0,0,0]
	v_mfma_scale_f32_16x16x128_f8f6f4 v[46:49], v[18:25], v[212:219], v[46:49], v195, v195 op_sel_hi:[0,0,0]
	v_mfma_scale_f32_16x16x128_f8f6f4 v[38:41], v[18:25], v[220:227], v[38:41], v195, v195 op_sel_hi:[0,0,0]
	v_mfma_scale_f32_16x16x128_f8f6f4 v[34:37], v[26:33], v[220:227], v[34:37], v195, v195 op_sel_hi:[0,0,0]
	v_mfma_scale_f32_16x16x128_f8f6f4 v[66:69], v[10:17], v[220:227], v[66:69], v195, v195 op_sel_hi:[0,0,0]
	v_mfma_scale_f32_16x16x128_f8f6f4 v[70:73], v[2:9], v[220:227], v[70:73], v195, v195 op_sel_hi:[0,0,0]
	s_setprio 0
	s_barrier
	s_andn2_b64 vcc, exec, s[42:43]
	s_cbranch_vccnz .LBB0_618
	s_barrier

.LBB0_630:
	s_ashr_i32 s54, s48, 1
	s_ashr_i32 s51, s50, 31
	s_ashr_i32 s55, s54, 31
	s_lshl_b64 s[52:53], s[50:51], 19
	s_lshl_b64 s[54:55], s[54:55], 9
	s_waitcnt vmcnt(0)
	ds_read_b128 v[18:21], v181
	ds_read_b128 v[22:25], v181 offset:1024
	ds_read_b128 v[26:29], v181 offset:2048
	ds_read_b128 v[30:33], v181 offset:3072
	ds_read_b128 v[2:5], v181 offset:16384
	ds_read_b128 v[6:9], v181 offset:17408
	ds_read_b128 v[10:13], v181 offset:18432
	ds_read_b128 v[14:17], v181 offset:19456
	s_add_u32 s5, s26, s52
	s_addc_u32 s33, s27, s53
	s_add_u32 s52, s5, s54
	s_addc_u32 s53, s33, s55
	s_and_b64 s[54:55], s[2:3], exec
	s_cselect_b32 s81, s53, s75
	s_cselect_b32 s80, s52, s74
	s_ashr_i32 s49, s48, 31
	s_lshl_b64 s[54:55], s[48:49], 17
	v_readlane_b32 s5, v254, 9
	s_add_u32 s54, s5, s54
	v_readlane_b32 s5, v254, 10
	s_addc_u32 s55, s5, s55
	s_and_b64 s[62:63], s[2:3], exec
	s_cselect_b32 s79, s55, s77
	s_cselect_b32 s78, s54, s76
	s_add_u32 s62, s74, 0x40080
	s_addc_u32 s63, s75, 0
	s_add_i32 s33, s8, 0xc000
	v_lshl_add_u64 v[174:175], s[62:63], 0, v[166:167]
	s_mov_b32 m0, s33
	s_add_i32 s5, s8, 0xe000
	ds_read_b128 v[190:193], v187
	ds_read_b128 v[194:197], v187 offset:1024
	ds_read_b128 v[198:201], v187 offset:2048
	ds_read_b128 v[202:205], v187 offset:3072
	ds_read_b128 v[206:209], v187 offset:4096
	ds_read_b128 v[210:213], v187 offset:5120
	ds_read_b128 v[214:217], v187 offset:6144
	ds_read_b128 v[218:221], v187 offset:7168
	global_load_lds_dwordx4 v[174:175], off
	v_lshl_add_u64 v[174:175], s[62:63], 0, v[168:169]
	s_mov_b32 m0, s5
	s_nop 0
	global_load_lds_dwordx4 v[174:175], off
	s_waitcnt vmcnt(8)
	s_waitcnt lgkmcnt(0)
	s_barrier
	s_setprio 1
	s_waitcnt lgkmcnt(0)
	v_mfma_scale_f32_16x16x128_f8f6f4 v[158:161], v[18:25], v[190:197], 0, v188, v188 op_sel_hi:[0,0,0]
	v_mfma_scale_f32_16x16x128_f8f6f4 v[154:157], v[26:33], v[190:197], 0, v188, v188 op_sel_hi:[0,0,0]
	v_mfma_scale_f32_16x16x128_f8f6f4 v[122:125], v[10:17], v[190:197], 0, v188, v188 op_sel_hi:[0,0,0]
	v_mfma_scale_f32_16x16x128_f8f6f4 v[126:129], v[2:9], v[190:197], 0, v188, v188 op_sel_hi:[0,0,0]
	v_mfma_scale_f32_16x16x128_f8f6f4 v[118:121], v[2:9], v[198:205], 0, v188, v188 op_sel_hi:[0,0,0]
	v_mfma_scale_f32_16x16x128_f8f6f4 v[114:117], v[10:17], v[198:205], 0, v188, v188 op_sel_hi:[0,0,0]
	v_mfma_scale_f32_16x16x128_f8f6f4 v[146:149], v[26:33], v[198:205], 0, v188, v188 op_sel_hi:[0,0,0]
	v_mfma_scale_f32_16x16x128_f8f6f4 v[150:153], v[18:25], v[198:205], 0, v188, v188 op_sel_hi:[0,0,0]
	s_setprio 0
	s_setprio 1
	v_mfma_scale_f32_16x16x128_f8f6f4 v[142:145], v[18:25], v[206:213], 0, v188, v188 op_sel_hi:[0,0,0]
	v_mfma_scale_f32_16x16x128_f8f6f4 v[138:141], v[26:33], v[206:213], 0, v188, v188 op_sel_hi:[0,0,0]
	v_mfma_scale_f32_16x16x128_f8f6f4 v[106:109], v[10:17], v[206:213], 0, v188, v188 op_sel_hi:[0,0,0]
	v_mfma_scale_f32_16x16x128_f8f6f4 v[110:113], v[2:9], v[206:213], 0, v188, v188 op_sel_hi:[0,0,0]
	v_mfma_scale_f32_16x16x128_f8f6f4 v[102:105], v[2:9], v[214:221], 0, v188, v188 op_sel_hi:[0,0,0]
	v_mfma_scale_f32_16x16x128_f8f6f4 v[98:101], v[10:17], v[214:221], 0, v188, v188 op_sel_hi:[0,0,0]
	v_mfma_scale_f32_16x16x128_f8f6f4 v[130:133], v[26:33], v[214:221], 0, v188, v188 op_sel_hi:[0,0,0]
	v_mfma_scale_f32_16x16x128_f8f6f4 v[134:137], v[18:25], v[214:221], 0, v188, v188 op_sel_hi:[0,0,0]
	s_setprio 0
	s_barrier
	v_lshl_add_u64 v[174:175], s[76:77], 0, v[162:163]
	s_mov_b32 m0, s9
	v_lshl_add_u64 v[176:177], v[174:175], 0, s[44:45]
	ds_read_b128 v[190:193], v187 offset:16384
	ds_read_b128 v[194:197], v187 offset:17408
	ds_read_b128 v[198:201], v187 offset:18432
	ds_read_b128 v[202:205], v187 offset:19456
	ds_read_b128 v[206:209], v187 offset:20480
	ds_read_b128 v[210:213], v187 offset:21504
	ds_read_b128 v[214:217], v187 offset:22528
	ds_read_b128 v[218:221], v187 offset:23552
	global_load_lds_dwordx4 v[176:177], off
	v_lshl_add_u64 v[176:177], s[76:77], 0, v[164:165]
	s_add_u32 s62, s76, 0x10100
	v_lshl_add_u64 v[182:183], v[176:177], 0, s[44:45]
	s_mov_b32 m0, s61
	s_addc_u32 s63, s77, 0
	global_load_lds_dwordx4 v[182:183], off
	v_lshl_add_u64 v[182:183], s[62:63], 0, v[162:163]
	s_mov_b32 m0, s68
	s_nop 0
	global_load_lds_dwordx4 v[182:183], off
	v_lshl_add_u64 v[182:183], s[62:63], 0, v[164:165]
	s_mov_b32 m0, s69
	s_nop 0
	global_load_lds_dwordx4 v[182:183], off
	v_lshl_add_u64 v[182:183], s[74:75], 0, v[166:167]
	v_lshl_add_u64 v[184:185], v[182:183], 0, s[44:45]
	s_mov_b32 m0, s8
	s_nop 0
	global_load_lds_dwordx4 v[184:185], off
	v_lshl_add_u64 v[184:185], s[74:75], 0, v[168:169]
	v_lshl_add_u64 v[222:223], v[184:185], 0, s[44:45]
	s_mov_b32 m0, s71
	s_nop 0
	global_load_lds_dwordx4 v[222:223], off
	s_waitcnt vmcnt(8)
	s_waitcnt lgkmcnt(0)
	s_barrier
	s_setprio 1
	s_waitcnt lgkmcnt(0)
	v_mfma_scale_f32_16x16x128_f8f6f4 v[94:97], v[18:25], v[190:197], 0, v188, v188 op_sel_hi:[0,0,0]
	v_mfma_scale_f32_16x16x128_f8f6f4 v[90:93], v[26:33], v[190:197], 0, v188, v188 op_sel_hi:[0,0,0]
	v_mfma_scale_f32_16x16x128_f8f6f4 v[58:61], v[10:17], v[190:197], 0, v188, v188 op_sel_hi:[0,0,0]
	v_mfma_scale_f32_16x16x128_f8f6f4 v[62:65], v[2:9], v[190:197], 0, v188, v188 op_sel_hi:[0,0,0]
	v_mfma_scale_f32_16x16x128_f8f6f4 v[54:57], v[2:9], v[198:205], 0, v188, v188 op_sel_hi:[0,0,0]
	v_mfma_scale_f32_16x16x128_f8f6f4 v[50:53], v[10:17], v[198:205], 0, v188, v188 op_sel_hi:[0,0,0]
	v_mfma_scale_f32_16x16x128_f8f6f4 v[82:85], v[26:33], v[198:205], 0, v188, v188 op_sel_hi:[0,0,0]
	v_mfma_scale_f32_16x16x128_f8f6f4 v[86:89], v[18:25], v[198:205], 0, v188, v188 op_sel_hi:[0,0,0]
	s_setprio 0
	s_setprio 1
	v_mfma_scale_f32_16x16x128_f8f6f4 v[78:81], v[18:25], v[206:213], 0, v188, v188 op_sel_hi:[0,0,0]
	v_mfma_scale_f32_16x16x128_f8f6f4 v[74:77], v[26:33], v[206:213], 0, v188, v188 op_sel_hi:[0,0,0]
	v_mfma_scale_f32_16x16x128_f8f6f4 v[42:45], v[10:17], v[206:213], 0, v188, v188 op_sel_hi:[0,0,0]
	v_mfma_scale_f32_16x16x128_f8f6f4 v[46:49], v[2:9], v[206:213], 0, v188, v188 op_sel_hi:[0,0,0]
	v_mfma_scale_f32_16x16x128_f8f6f4 v[38:41], v[2:9], v[214:221], 0, v188, v188 op_sel_hi:[0,0,0]
	v_mfma_scale_f32_16x16x128_f8f6f4 v[34:37], v[10:17], v[214:221], 0, v188, v188 op_sel_hi:[0,0,0]
	v_mfma_scale_f32_16x16x128_f8f6f4 v[66:69], v[26:33], v[214:221], 0, v188, v188 op_sel_hi:[0,0,0]
	v_mfma_scale_f32_16x16x128_f8f6f4 v[70:73], v[18:25], v[214:221], 0, v188, v188 op_sel_hi:[0,0,0]
	s_setprio 0
	s_barrier
	ds_read_b128 v[2:5], v181 offset:32768
	ds_read_b128 v[6:9], v181 offset:33792
	ds_read_b128 v[10:13], v181 offset:34816
	ds_read_b128 v[14:17], v181 offset:35840
	ds_read_b128 v[18:21], v181 offset:49152
	ds_read_b128 v[22:25], v181 offset:50176
	ds_read_b128 v[26:29], v181 offset:51200
	ds_read_b128 v[30:33], v181 offset:52224
	s_add_u32 s62, s74, 0x40100
	s_addc_u32 s63, s75, 0
	s_mov_b32 m0, s73
	v_lshl_add_u64 v[222:223], s[62:63], 0, v[166:167]
	ds_read_b128 v[190:193], v187 offset:32768
	ds_read_b128 v[194:197], v187 offset:33792
	ds_read_b128 v[198:201], v187 offset:34816
	ds_read_b128 v[202:205], v187 offset:35840
	ds_read_b128 v[206:209], v187 offset:36864
	ds_read_b128 v[210:213], v187 offset:37888
	ds_read_b128 v[214:217], v187 offset:38912
	ds_read_b128 v[218:221], v187 offset:39936
	global_load_lds_dwordx4 v[222:223], off
	v_lshl_add_u64 v[222:223], s[62:63], 0, v[168:169]
	s_mov_b32 m0, s82
	s_nop 0
	global_load_lds_dwordx4 v[222:223], off
	s_waitcnt vmcnt(8)
	s_waitcnt lgkmcnt(0)
	s_barrier
	s_setprio 1
	s_waitcnt lgkmcnt(0)
	v_mfma_scale_f32_16x16x128_f8f6f4 v[158:161], v[2:9], v[190:197], v[158:161], v188, v188 op_sel_hi:[0,0,0]
	v_mfma_scale_f32_16x16x128_f8f6f4 v[154:157], v[10:17], v[190:197], v[154:157], v188, v188 op_sel_hi:[0,0,0]
	v_mfma_scale_f32_16x16x128_f8f6f4 v[122:125], v[26:33], v[190:197], v[122:125], v188, v188 op_sel_hi:[0,0,0]
	v_mfma_scale_f32_16x16x128_f8f6f4 v[126:129], v[18:25], v[190:197], v[126:129], v188, v188 op_sel_hi:[0,0,0]
	v_mfma_scale_f32_16x16x128_f8f6f4 v[118:121], v[18:25], v[198:205], v[118:121], v188, v188 op_sel_hi:[0,0,0]
	v_mfma_scale_f32_16x16x128_f8f6f4 v[114:117], v[26:33], v[198:205], v[114:117], v188, v188 op_sel_hi:[0,0,0]
	v_mfma_scale_f32_16x16x128_f8f6f4 v[146:149], v[10:17], v[198:205], v[146:149], v188, v188 op_sel_hi:[0,0,0]
	v_mfma_scale_f32_16x16x128_f8f6f4 v[150:153], v[2:9], v[198:205], v[150:153], v188, v188 op_sel_hi:[0,0,0]
	s_setprio 0
	s_setprio 1
	v_mfma_scale_f32_16x16x128_f8f6f4 v[142:145], v[2:9], v[206:213], v[142:145], v188, v188 op_sel_hi:[0,0,0]
	v_mfma_scale_f32_16x16x128_f8f6f4 v[138:141], v[10:17], v[206:213], v[138:141], v188, v188 op_sel_hi:[0,0,0]
	v_mfma_scale_f32_16x16x128_f8f6f4 v[106:109], v[26:33], v[206:213], v[106:109], v188, v188 op_sel_hi:[0,0,0]
	v_mfma_scale_f32_16x16x128_f8f6f4 v[110:113], v[18:25], v[206:213], v[110:113], v188, v188 op_sel_hi:[0,0,0]
	v_mfma_scale_f32_16x16x128_f8f6f4 v[102:105], v[18:25], v[214:221], v[102:105], v188, v188 op_sel_hi:[0,0,0]
	v_mfma_scale_f32_16x16x128_f8f6f4 v[98:101], v[26:33], v[214:221], v[98:101], v188, v188 op_sel_hi:[0,0,0]
	v_mfma_scale_f32_16x16x128_f8f6f4 v[130:133], v[10:17], v[214:221], v[130:133], v188, v188 op_sel_hi:[0,0,0]
	v_mfma_scale_f32_16x16x128_f8f6f4 v[134:137], v[2:9], v[214:221], v[134:137], v188, v188 op_sel_hi:[0,0,0]
	s_setprio 0
	s_barrier
	s_mov_b32 m0, s83
	v_lshl_add_u64 v[174:175], v[174:175], 0, s[46:47]
	s_add_u32 s62, s76, 0x10180
	ds_read_b128 v[190:193], v187 offset:49152
	ds_read_b128 v[194:197], v187 offset:50176
	ds_read_b128 v[198:201], v187 offset:51200
	ds_read_b128 v[202:205], v187 offset:52224
	ds_read_b128 v[206:209], v187 offset:53248
	ds_read_b128 v[210:213], v187 offset:54272
	ds_read_b128 v[214:217], v187 offset:55296
	ds_read_b128 v[218:221], v187 offset:56320
	global_load_lds_dwordx4 v[174:175], off
	v_lshl_add_u64 v[174:175], v[176:177], 0, s[46:47]
	s_mov_b32 m0, s84
	s_addc_u32 s63, s77, 0
	global_load_lds_dwordx4 v[174:175], off
	v_lshl_add_u64 v[174:175], s[62:63], 0, v[162:163]
	s_mov_b32 m0, s87
	s_nop 0
	global_load_lds_dwordx4 v[174:175], off
	v_lshl_add_u64 v[174:175], s[62:63], 0, v[164:165]
	s_mov_b32 m0, s88
	s_nop 0
	global_load_lds_dwordx4 v[174:175], off
	v_lshl_add_u64 v[174:175], v[182:183], 0, s[46:47]
	s_mov_b32 m0, s85
	s_nop 0
	global_load_lds_dwordx4 v[174:175], off
	v_lshl_add_u64 v[174:175], v[184:185], 0, s[46:47]
	s_mov_b32 m0, s86
	s_nop 0
	global_load_lds_dwordx4 v[174:175], off
	s_waitcnt vmcnt(8)
	s_waitcnt lgkmcnt(0)
	s_barrier
	s_setprio 1
	s_waitcnt lgkmcnt(0)
	v_mfma_scale_f32_16x16x128_f8f6f4 v[94:97], v[2:9], v[190:197], v[94:97], v188, v188 op_sel_hi:[0,0,0]
	v_mfma_scale_f32_16x16x128_f8f6f4 v[90:93], v[10:17], v[190:197], v[90:93], v188, v188 op_sel_hi:[0,0,0]
	v_mfma_scale_f32_16x16x128_f8f6f4 v[58:61], v[26:33], v[190:197], v[58:61], v188, v188 op_sel_hi:[0,0,0]
	v_mfma_scale_f32_16x16x128_f8f6f4 v[62:65], v[18:25], v[190:197], v[62:65], v188, v188 op_sel_hi:[0,0,0]
	v_mfma_scale_f32_16x16x128_f8f6f4 v[54:57], v[18:25], v[198:205], v[54:57], v188, v188 op_sel_hi:[0,0,0]
	v_mfma_scale_f32_16x16x128_f8f6f4 v[50:53], v[26:33], v[198:205], v[50:53], v188, v188 op_sel_hi:[0,0,0]
	v_mfma_scale_f32_16x16x128_f8f6f4 v[82:85], v[10:17], v[198:205], v[82:85], v188, v188 op_sel_hi:[0,0,0]
	v_mfma_scale_f32_16x16x128_f8f6f4 v[86:89], v[2:9], v[198:205], v[86:89], v188, v188 op_sel_hi:[0,0,0]
	s_setprio 0
	s_setprio 1
	v_mfma_scale_f32_16x16x128_f8f6f4 v[78:81], v[2:9], v[206:213], v[78:81], v188, v188 op_sel_hi:[0,0,0]
	v_mfma_scale_f32_16x16x128_f8f6f4 v[74:77], v[10:17], v[206:213], v[74:77], v188, v188 op_sel_hi:[0,0,0]
	v_mfma_scale_f32_16x16x128_f8f6f4 v[42:45], v[26:33], v[206:213], v[42:45], v188, v188 op_sel_hi:[0,0,0]
	v_mfma_scale_f32_16x16x128_f8f6f4 v[46:49], v[18:25], v[206:213], v[46:49], v188, v188 op_sel_hi:[0,0,0]
	v_mfma_scale_f32_16x16x128_f8f6f4 v[38:41], v[18:25], v[214:221], v[38:41], v188, v188 op_sel_hi:[0,0,0]
	v_mfma_scale_f32_16x16x128_f8f6f4 v[34:37], v[26:33], v[214:221], v[34:37], v188, v188 op_sel_hi:[0,0,0]
	v_mfma_scale_f32_16x16x128_f8f6f4 v[66:69], v[10:17], v[214:221], v[66:69], v188, v188 op_sel_hi:[0,0,0]
	v_mfma_scale_f32_16x16x128_f8f6f4 v[70:73], v[2:9], v[214:221], v[70:73], v188, v188 op_sel_hi:[0,0,0]
	s_setprio 0
	s_barrier
	ds_read_b128 v[2:5], v181
	ds_read_b128 v[6:9], v181 offset:1024
	ds_read_b128 v[10:13], v181 offset:2048
	ds_read_b128 v[14:17], v181 offset:3072
	ds_read_b128 v[18:21], v181 offset:16384
	ds_read_b128 v[22:25], v181 offset:17408
	ds_read_b128 v[26:29], v181 offset:18432
	ds_read_b128 v[30:33], v181 offset:19456
	s_add_u32 s62, s74, 0x40180
	s_addc_u32 s63, s75, 0
	s_mov_b32 m0, s33
	v_lshl_add_u64 v[174:175], s[62:63], 0, v[166:167]
	ds_read_b128 v[190:193], v187
	ds_read_b128 v[194:197], v187 offset:1024
	ds_read_b128 v[198:201], v187 offset:2048
	ds_read_b128 v[202:205], v187 offset:3072
	ds_read_b128 v[206:209], v187 offset:4096
	ds_read_b128 v[210:213], v187 offset:5120
	ds_read_b128 v[214:217], v187 offset:6144
	ds_read_b128 v[218:221], v187 offset:7168
	global_load_lds_dwordx4 v[174:175], off
	v_lshl_add_u64 v[174:175], s[62:63], 0, v[168:169]
	s_mov_b32 m0, s5
	s_nop 0
	global_load_lds_dwordx4 v[174:175], off
	s_waitcnt vmcnt(8)
	s_waitcnt lgkmcnt(0)
	s_barrier
	s_setprio 1
	s_waitcnt lgkmcnt(0)
	v_mfma_scale_f32_16x16x128_f8f6f4 v[158:161], v[2:9], v[190:197], v[158:161], v188, v188 op_sel_hi:[0,0,0]
	v_mfma_scale_f32_16x16x128_f8f6f4 v[154:157], v[10:17], v[190:197], v[154:157], v188, v188 op_sel_hi:[0,0,0]
	v_mfma_scale_f32_16x16x128_f8f6f4 v[122:125], v[26:33], v[190:197], v[122:125], v188, v188 op_sel_hi:[0,0,0]
	v_mfma_scale_f32_16x16x128_f8f6f4 v[126:129], v[18:25], v[190:197], v[126:129], v188, v188 op_sel_hi:[0,0,0]
	v_mfma_scale_f32_16x16x128_f8f6f4 v[118:121], v[18:25], v[198:205], v[118:121], v188, v188 op_sel_hi:[0,0,0]
	v_mfma_scale_f32_16x16x128_f8f6f4 v[114:117], v[26:33], v[198:205], v[114:117], v188, v188 op_sel_hi:[0,0,0]
	v_mfma_scale_f32_16x16x128_f8f6f4 v[146:149], v[10:17], v[198:205], v[146:149], v188, v188 op_sel_hi:[0,0,0]
	v_mfma_scale_f32_16x16x128_f8f6f4 v[150:153], v[2:9], v[198:205], v[150:153], v188, v188 op_sel_hi:[0,0,0]
	s_setprio 0
	s_setprio 1
	v_mfma_scale_f32_16x16x128_f8f6f4 v[142:145], v[2:9], v[206:213], v[142:145], v188, v188 op_sel_hi:[0,0,0]
	v_mfma_scale_f32_16x16x128_f8f6f4 v[138:141], v[10:17], v[206:213], v[138:141], v188, v188 op_sel_hi:[0,0,0]
	v_mfma_scale_f32_16x16x128_f8f6f4 v[106:109], v[26:33], v[206:213], v[106:109], v188, v188 op_sel_hi:[0,0,0]
	v_mfma_scale_f32_16x16x128_f8f6f4 v[110:113], v[18:25], v[206:213], v[110:113], v188, v188 op_sel_hi:[0,0,0]
	v_mfma_scale_f32_16x16x128_f8f6f4 v[102:105], v[18:25], v[214:221], v[102:105], v188, v188 op_sel_hi:[0,0,0]
	v_mfma_scale_f32_16x16x128_f8f6f4 v[98:101], v[26:33], v[214:221], v[98:101], v188, v188 op_sel_hi:[0,0,0]
	v_mfma_scale_f32_16x16x128_f8f6f4 v[130:133], v[10:17], v[214:221], v[130:133], v188, v188 op_sel_hi:[0,0,0]
	v_mfma_scale_f32_16x16x128_f8f6f4 v[134:137], v[2:9], v[214:221], v[134:137], v188, v188 op_sel_hi:[0,0,0]
	s_setprio 0
	s_barrier
	s_mov_b32 m0, s9
	v_lshl_add_u64 v[174:175], s[78:79], 0, v[162:163]
	s_add_u32 s62, s78, 0x10000
	ds_read_b128 v[190:193], v187 offset:16384
	ds_read_b128 v[194:197], v187 offset:17408
	ds_read_b128 v[198:201], v187 offset:18432
	ds_read_b128 v[202:205], v187 offset:19456
	ds_read_b128 v[206:209], v187 offset:20480
	ds_read_b128 v[210:213], v187 offset:21504
	ds_read_b128 v[214:217], v187 offset:22528
	ds_read_b128 v[218:221], v187 offset:23552
	global_load_lds_dwordx4 v[174:175], off
	v_lshl_add_u64 v[176:177], s[78:79], 0, v[164:165]
	s_mov_b32 m0, s61
	s_addc_u32 s63, s79, 0
	global_load_lds_dwordx4 v[176:177], off
	v_lshl_add_u64 v[182:183], s[62:63], 0, v[162:163]
	s_mov_b32 m0, s68
	v_lshl_add_u64 v[184:185], s[80:81], 0, v[168:169]
	global_load_lds_dwordx4 v[182:183], off
	v_lshl_add_u64 v[182:183], s[62:63], 0, v[164:165]
	s_mov_b32 m0, s69
	s_nop 0
	global_load_lds_dwordx4 v[182:183], off
	v_lshl_add_u64 v[182:183], s[80:81], 0, v[166:167]
	s_mov_b32 m0, s8
	s_nop 0
	global_load_lds_dwordx4 v[182:183], off
	s_mov_b32 m0, s71
	s_nop 0
	global_load_lds_dwordx4 v[184:185], off
	s_waitcnt vmcnt(8)
	s_waitcnt lgkmcnt(0)
	s_barrier
	s_setprio 1
	s_waitcnt lgkmcnt(0)
	v_mfma_scale_f32_16x16x128_f8f6f4 v[94:97], v[2:9], v[190:197], v[94:97], v188, v188 op_sel_hi:[0,0,0]
	v_mfma_scale_f32_16x16x128_f8f6f4 v[90:93], v[10:17], v[190:197], v[90:93], v188, v188 op_sel_hi:[0,0,0]
	v_mfma_scale_f32_16x16x128_f8f6f4 v[58:61], v[26:33], v[190:197], v[58:61], v188, v188 op_sel_hi:[0,0,0]
	v_mfma_scale_f32_16x16x128_f8f6f4 v[62:65], v[18:25], v[190:197], v[62:65], v188, v188 op_sel_hi:[0,0,0]
	v_mfma_scale_f32_16x16x128_f8f6f4 v[54:57], v[18:25], v[198:205], v[54:57], v188, v188 op_sel_hi:[0,0,0]
	v_mfma_scale_f32_16x16x128_f8f6f4 v[50:53], v[26:33], v[198:205], v[50:53], v188, v188 op_sel_hi:[0,0,0]
	v_mfma_scale_f32_16x16x128_f8f6f4 v[82:85], v[10:17], v[198:205], v[82:85], v188, v188 op_sel_hi:[0,0,0]
	v_mfma_scale_f32_16x16x128_f8f6f4 v[86:89], v[2:9], v[198:205], v[86:89], v188, v188 op_sel_hi:[0,0,0]
	s_setprio 0
	s_setprio 1
	v_mfma_scale_f32_16x16x128_f8f6f4 v[78:81], v[2:9], v[206:213], v[78:81], v188, v188 op_sel_hi:[0,0,0]
	v_mfma_scale_f32_16x16x128_f8f6f4 v[74:77], v[10:17], v[206:213], v[74:77], v188, v188 op_sel_hi:[0,0,0]
	v_mfma_scale_f32_16x16x128_f8f6f4 v[42:45], v[26:33], v[206:213], v[42:45], v188, v188 op_sel_hi:[0,0,0]
	v_mfma_scale_f32_16x16x128_f8f6f4 v[46:49], v[18:25], v[206:213], v[46:49], v188, v188 op_sel_hi:[0,0,0]
	v_mfma_scale_f32_16x16x128_f8f6f4 v[38:41], v[18:25], v[214:221], v[38:41], v188, v188 op_sel_hi:[0,0,0]
	v_mfma_scale_f32_16x16x128_f8f6f4 v[34:37], v[26:33], v[214:221], v[34:37], v188, v188 op_sel_hi:[0,0,0]
	v_mfma_scale_f32_16x16x128_f8f6f4 v[66:69], v[10:17], v[214:221], v[66:69], v188, v188 op_sel_hi:[0,0,0]
	v_mfma_scale_f32_16x16x128_f8f6f4 v[70:73], v[2:9], v[214:221], v[70:73], v188, v188 op_sel_hi:[0,0,0]
	s_setprio 0
	s_barrier
	ds_read_b128 v[2:5], v181 offset:32768
	ds_read_b128 v[6:9], v181 offset:33792
	ds_read_b128 v[10:13], v181 offset:34816
	ds_read_b128 v[14:17], v181 offset:35840
	ds_read_b128 v[18:21], v181 offset:49152
	ds_read_b128 v[22:25], v181 offset:50176
	ds_read_b128 v[26:29], v181 offset:51200
	ds_read_b128 v[30:33], v181 offset:52224
	s_add_u32 s62, s80, 0x40000
	s_addc_u32 s63, s81, 0
	s_mov_b32 m0, s73
	v_lshl_add_u64 v[222:223], s[62:63], 0, v[166:167]
	ds_read_b128 v[190:193], v187 offset:32768
	ds_read_b128 v[194:197], v187 offset:33792
	ds_read_b128 v[198:201], v187 offset:34816
	ds_read_b128 v[202:205], v187 offset:35840
	ds_read_b128 v[206:209], v187 offset:36864
	ds_read_b128 v[210:213], v187 offset:37888
	ds_read_b128 v[214:217], v187 offset:38912
	ds_read_b128 v[218:221], v187 offset:39936
	global_load_lds_dwordx4 v[222:223], off
	v_lshl_add_u64 v[222:223], s[62:63], 0, v[168:169]
	s_mov_b32 m0, s82
	s_nop 0
	global_load_lds_dwordx4 v[222:223], off
	s_waitcnt vmcnt(8)
	s_waitcnt lgkmcnt(0)
	s_barrier
	s_setprio 1
	s_waitcnt lgkmcnt(0)
	v_mfma_scale_f32_16x16x128_f8f6f4 v[158:161], v[2:9], v[190:197], v[158:161], v188, v188 op_sel_hi:[0,0,0]
	v_mfma_scale_f32_16x16x128_f8f6f4 v[154:157], v[10:17], v[190:197], v[154:157], v188, v188 op_sel_hi:[0,0,0]
	v_mfma_scale_f32_16x16x128_f8f6f4 v[122:125], v[26:33], v[190:197], v[122:125], v188, v188 op_sel_hi:[0,0,0]
	v_mfma_scale_f32_16x16x128_f8f6f4 v[126:129], v[18:25], v[190:197], v[126:129], v188, v188 op_sel_hi:[0,0,0]
	v_mfma_scale_f32_16x16x128_f8f6f4 v[118:121], v[18:25], v[198:205], v[118:121], v188, v188 op_sel_hi:[0,0,0]
	v_mfma_scale_f32_16x16x128_f8f6f4 v[114:117], v[26:33], v[198:205], v[114:117], v188, v188 op_sel_hi:[0,0,0]
	v_mfma_scale_f32_16x16x128_f8f6f4 v[146:149], v[10:17], v[198:205], v[146:149], v188, v188 op_sel_hi:[0,0,0]
	v_mfma_scale_f32_16x16x128_f8f6f4 v[150:153], v[2:9], v[198:205], v[150:153], v188, v188 op_sel_hi:[0,0,0]
	s_setprio 0
	s_setprio 1
	v_mfma_scale_f32_16x16x128_f8f6f4 v[142:145], v[2:9], v[206:213], v[142:145], v188, v188 op_sel_hi:[0,0,0]
	v_mfma_scale_f32_16x16x128_f8f6f4 v[138:141], v[10:17], v[206:213], v[138:141], v188, v188 op_sel_hi:[0,0,0]
	v_mfma_scale_f32_16x16x128_f8f6f4 v[106:109], v[26:33], v[206:213], v[106:109], v188, v188 op_sel_hi:[0,0,0]
	v_mfma_scale_f32_16x16x128_f8f6f4 v[110:113], v[18:25], v[206:213], v[110:113], v188, v188 op_sel_hi:[0,0,0]
	v_mfma_scale_f32_16x16x128_f8f6f4 v[102:105], v[18:25], v[214:221], v[102:105], v188, v188 op_sel_hi:[0,0,0]
	v_mfma_scale_f32_16x16x128_f8f6f4 v[98:101], v[26:33], v[214:221], v[98:101], v188, v188 op_sel_hi:[0,0,0]
	v_mfma_scale_f32_16x16x128_f8f6f4 v[130:133], v[10:17], v[214:221], v[130:133], v188, v188 op_sel_hi:[0,0,0]
	v_mfma_scale_f32_16x16x128_f8f6f4 v[134:137], v[2:9], v[214:221], v[134:137], v188, v188 op_sel_hi:[0,0,0]
	s_setprio 0
	s_barrier
	s_mov_b32 m0, s83
	v_lshl_add_u64 v[174:175], v[174:175], 0, s[38:39]
	s_add_u32 s62, s78, 0x10080
	ds_read_b128 v[190:193], v187 offset:49152
	ds_read_b128 v[194:197], v187 offset:50176
	ds_read_b128 v[198:201], v187 offset:51200
	ds_read_b128 v[202:205], v187 offset:52224
	ds_read_b128 v[206:209], v187 offset:53248
	ds_read_b128 v[210:213], v187 offset:54272
	ds_read_b128 v[214:217], v187 offset:55296
	ds_read_b128 v[218:221], v187 offset:56320
	global_load_lds_dwordx4 v[174:175], off
	v_lshl_add_u64 v[174:175], v[176:177], 0, s[38:39]
	s_mov_b32 m0, s84
	s_addc_u32 s63, s79, 0
	global_load_lds_dwordx4 v[174:175], off
	v_lshl_add_u64 v[174:175], s[62:63], 0, v[162:163]
	s_mov_b32 m0, s87
	s_nop 0
	global_load_lds_dwordx4 v[174:175], off
	v_lshl_add_u64 v[174:175], s[62:63], 0, v[164:165]
	s_mov_b32 m0, s88
	s_nop 0
	global_load_lds_dwordx4 v[174:175], off
	v_lshl_add_u64 v[174:175], v[182:183], 0, s[38:39]
	s_mov_b32 m0, s85
	s_nop 0
	global_load_lds_dwordx4 v[174:175], off
	v_lshl_add_u64 v[174:175], v[184:185], 0, s[38:39]
	s_mov_b32 m0, s86
	s_nop 0
	global_load_lds_dwordx4 v[174:175], off
	s_waitcnt vmcnt(8)
	s_waitcnt lgkmcnt(0)
	s_barrier
	s_setprio 1
	s_waitcnt lgkmcnt(0)
	v_mfma_scale_f32_16x16x128_f8f6f4 v[94:97], v[2:9], v[190:197], v[94:97], v188, v188 op_sel_hi:[0,0,0]
	v_mfma_scale_f32_16x16x128_f8f6f4 v[90:93], v[10:17], v[190:197], v[90:93], v188, v188 op_sel_hi:[0,0,0]
	v_mfma_scale_f32_16x16x128_f8f6f4 v[58:61], v[26:33], v[190:197], v[58:61], v188, v188 op_sel_hi:[0,0,0]
	v_mfma_scale_f32_16x16x128_f8f6f4 v[62:65], v[18:25], v[190:197], v[62:65], v188, v188 op_sel_hi:[0,0,0]
	v_mfma_scale_f32_16x16x128_f8f6f4 v[54:57], v[18:25], v[198:205], v[54:57], v188, v188 op_sel_hi:[0,0,0]
	v_mfma_scale_f32_16x16x128_f8f6f4 v[50:53], v[26:33], v[198:205], v[50:53], v188, v188 op_sel_hi:[0,0,0]
	v_mfma_scale_f32_16x16x128_f8f6f4 v[82:85], v[10:17], v[198:205], v[82:85], v188, v188 op_sel_hi:[0,0,0]
	v_mfma_scale_f32_16x16x128_f8f6f4 v[86:89], v[2:9], v[198:205], v[86:89], v188, v188 op_sel_hi:[0,0,0]
	s_setprio 0
	s_setprio 1
	v_mfma_scale_f32_16x16x128_f8f6f4 v[78:81], v[2:9], v[206:213], v[78:81], v188, v188 op_sel_hi:[0,0,0]
	v_mfma_scale_f32_16x16x128_f8f6f4 v[74:77], v[10:17], v[206:213], v[74:77], v188, v188 op_sel_hi:[0,0,0]
	v_mfma_scale_f32_16x16x128_f8f6f4 v[42:45], v[26:33], v[206:213], v[42:45], v188, v188 op_sel_hi:[0,0,0]
	v_mfma_scale_f32_16x16x128_f8f6f4 v[46:49], v[18:25], v[206:213], v[46:49], v188, v188 op_sel_hi:[0,0,0]
	v_mfma_scale_f32_16x16x128_f8f6f4 v[38:41], v[18:25], v[214:221], v[38:41], v188, v188 op_sel_hi:[0,0,0]
	v_mfma_scale_f32_16x16x128_f8f6f4 v[34:37], v[26:33], v[214:221], v[34:37], v188, v188 op_sel_hi:[0,0,0]
	v_mfma_scale_f32_16x16x128_f8f6f4 v[66:69], v[10:17], v[214:221], v[66:69], v188, v188 op_sel_hi:[0,0,0]
	v_mfma_scale_f32_16x16x128_f8f6f4 v[70:73], v[2:9], v[214:221], v[70:73], v188, v188 op_sel_hi:[0,0,0]
	s_setprio 0
	s_barrier
	s_andn2_b64 vcc, exec, s[40:41]
	s_cbranch_vccnz .LBB0_632
	s_barrier

.LBB0_791:
	ds_read_b128 v[2:5], v189
	ds_read_b128 v[6:9], v189 offset:1024
	ds_read_b128 v[192:195], v189 offset:2048
	ds_read_b128 v[196:199], v189 offset:3072
	ds_read_b128 v[200:203], v189 offset:16384
	ds_read_b128 v[204:207], v189 offset:17408
	ds_read_b128 v[208:211], v189 offset:18432
	ds_read_b128 v[212:215], v189 offset:19456
	s_add_u32 s37, s46, 0x100
	s_addc_u32 s39, s47, 0
	s_and_b64 s[50:51], s[48:49], exec
	s_cselect_b32 s51, s1, s39
	s_cselect_b32 s50, s0, s37
	s_add_u32 s37, s44, 0x100
	s_addc_u32 s39, s45, 0
	s_and_b64 s[48:49], s[48:49], exec
	s_cselect_b32 s49, s5, s39
	s_cselect_b32 s48, s4, s37
	s_add_u32 s88, s46, 0x80080
	s_addc_u32 s89, s47, 0
	s_add_i32 s37, s8, 0xc000
	v_lshl_add_u64 v[174:175], s[88:89], 0, v[154:155]
	s_mov_b32 m0, s37
	s_add_i32 s39, s8, 0xe000
	ds_read_b128 v[216:219], v190
	ds_read_b128 v[220:223], v190 offset:1024
	ds_read_b128 v[224:227], v190 offset:2048
	ds_read_b128 v[228:231], v190 offset:3072
	ds_read_b128 v[242:245], v190 offset:4096
	ds_read_b128 v[246:249], v190 offset:5120
	ds_read_b128 v[232:235], v190 offset:6144
	ds_read_b128 v[236:239], v190 offset:7168
	global_load_lds_dwordx4 v[174:175], off
	v_lshl_add_u64 v[174:175], s[88:89], 0, v[158:159]
	s_mov_b32 m0, s39
	s_nop 0
	global_load_lds_dwordx4 v[174:175], off
	s_waitcnt vmcnt(8)
	s_waitcnt lgkmcnt(0)
	s_barrier
	s_setprio 1
	s_waitcnt lgkmcnt(0)
	v_mfma_scale_f32_16x16x128_f8f6f4 v[134:137], v[2:9], v[216:223], 0, v188, v188 op_sel_hi:[0,0,0]
	v_mfma_scale_f32_16x16x128_f8f6f4 v[130:133], v[192:199], v[216:223], 0, v188, v188 op_sel_hi:[0,0,0]
	v_mfma_scale_f32_16x16x128_f8f6f4 v[98:101], v[208:215], v[216:223], 0, v188, v188 op_sel_hi:[0,0,0]
	v_mfma_scale_f32_16x16x128_f8f6f4 v[102:105], v[200:207], v[216:223], 0, v188, v188 op_sel_hi:[0,0,0]
	v_mfma_scale_f32_16x16x128_f8f6f4 v[94:97], v[200:207], v[224:231], 0, v188, v188 op_sel_hi:[0,0,0]
	v_mfma_scale_f32_16x16x128_f8f6f4 v[90:93], v[208:215], v[224:231], 0, v188, v188 op_sel_hi:[0,0,0]
	v_mfma_scale_f32_16x16x128_f8f6f4 v[122:125], v[192:199], v[224:231], 0, v188, v188 op_sel_hi:[0,0,0]
	v_mfma_scale_f32_16x16x128_f8f6f4 v[126:129], v[2:9], v[224:231], 0, v188, v188 op_sel_hi:[0,0,0]
	s_setprio 0
	s_setprio 1
	v_mfma_scale_f32_16x16x128_f8f6f4 v[118:121], v[2:9], v[242:249], 0, v188, v188 op_sel_hi:[0,0,0]
	v_mfma_scale_f32_16x16x128_f8f6f4 v[114:117], v[192:199], v[242:249], 0, v188, v188 op_sel_hi:[0,0,0]
	v_mfma_scale_f32_16x16x128_f8f6f4 v[82:85], v[208:215], v[242:249], 0, v188, v188 op_sel_hi:[0,0,0]
	v_mfma_scale_f32_16x16x128_f8f6f4 v[86:89], v[200:207], v[242:249], 0, v188, v188 op_sel_hi:[0,0,0]
	v_mfma_scale_f32_16x16x128_f8f6f4 v[78:81], v[200:207], v[232:239], 0, v188, v188 op_sel_hi:[0,0,0]
	v_mfma_scale_f32_16x16x128_f8f6f4 v[74:77], v[208:215], v[232:239], 0, v188, v188 op_sel_hi:[0,0,0]
	v_mfma_scale_f32_16x16x128_f8f6f4 v[106:109], v[192:199], v[232:239], 0, v188, v188 op_sel_hi:[0,0,0]
	v_mfma_scale_f32_16x16x128_f8f6f4 v[110:113], v[2:9], v[232:239], 0, v188, v188 op_sel_hi:[0,0,0]
	s_setprio 0
	s_barrier
	s_mov_b32 m0, s9
	v_lshl_add_u64 v[174:175], s[48:49], 0, v[156:157]
	s_add_u32 s88, s48, 0x80000
	ds_read_b128 v[216:219], v190 offset:16384
	ds_read_b128 v[220:223], v190 offset:17408
	ds_read_b128 v[224:227], v190 offset:18432
	ds_read_b128 v[228:231], v190 offset:19456
	ds_read_b128 v[232:235], v190 offset:20480
	ds_read_b128 v[236:239], v190 offset:21504
	ds_read_b128 v[242:245], v190 offset:22528
	ds_read_b128 v[246:249], v190 offset:23552
	global_load_lds_dwordx4 v[174:175], off
	v_lshl_add_u64 v[176:177], s[48:49], 0, v[160:161]
	s_mov_b32 m0, s27
	s_addc_u32 s89, s49, 0
	global_load_lds_dwordx4 v[176:177], off
	v_lshl_add_u64 v[182:183], s[88:89], 0, v[156:157]
	s_mov_b32 m0, s33
	v_lshl_add_u64 v[184:185], s[50:51], 0, v[158:159]
	global_load_lds_dwordx4 v[182:183], off
	v_lshl_add_u64 v[182:183], s[88:89], 0, v[160:161]
	s_mov_b32 m0, s35
	s_nop 0
	global_load_lds_dwordx4 v[182:183], off
	v_lshl_add_u64 v[182:183], s[50:51], 0, v[154:155]
	s_mov_b32 m0, s8
	s_nop 0
	global_load_lds_dwordx4 v[182:183], off
	s_mov_b32 m0, s43
	s_nop 0
	global_load_lds_dwordx4 v[184:185], off
	s_waitcnt vmcnt(8)
	s_waitcnt lgkmcnt(0)
	s_barrier
	s_setprio 1
	s_waitcnt lgkmcnt(0)
	v_mfma_scale_f32_16x16x128_f8f6f4 v[70:73], v[2:9], v[216:223], 0, v188, v188 op_sel_hi:[0,0,0]
	v_mfma_scale_f32_16x16x128_f8f6f4 v[66:69], v[192:199], v[216:223], 0, v188, v188 op_sel_hi:[0,0,0]
	v_mfma_scale_f32_16x16x128_f8f6f4 v[34:37], v[208:215], v[216:223], 0, v188, v188 op_sel_hi:[0,0,0]
	v_mfma_scale_f32_16x16x128_f8f6f4 v[38:41], v[200:207], v[216:223], 0, v188, v188 op_sel_hi:[0,0,0]
	v_mfma_scale_f32_16x16x128_f8f6f4 v[30:33], v[200:207], v[224:231], 0, v188, v188 op_sel_hi:[0,0,0]
	v_mfma_scale_f32_16x16x128_f8f6f4 v[26:29], v[208:215], v[224:231], 0, v188, v188 op_sel_hi:[0,0,0]
	v_mfma_scale_f32_16x16x128_f8f6f4 v[58:61], v[192:199], v[224:231], 0, v188, v188 op_sel_hi:[0,0,0]
	v_mfma_scale_f32_16x16x128_f8f6f4 v[62:65], v[2:9], v[224:231], 0, v188, v188 op_sel_hi:[0,0,0]
	s_setprio 0
	s_setprio 1
	v_mfma_scale_f32_16x16x128_f8f6f4 v[54:57], v[2:9], v[232:239], 0, v188, v188 op_sel_hi:[0,0,0]
	v_mfma_scale_f32_16x16x128_f8f6f4 v[50:53], v[192:199], v[232:239], 0, v188, v188 op_sel_hi:[0,0,0]
	v_mfma_scale_f32_16x16x128_f8f6f4 v[18:21], v[208:215], v[232:239], 0, v188, v188 op_sel_hi:[0,0,0]
	v_mfma_scale_f32_16x16x128_f8f6f4 v[22:25], v[200:207], v[232:239], 0, v188, v188 op_sel_hi:[0,0,0]
	v_mfma_scale_f32_16x16x128_f8f6f4 v[14:17], v[200:207], v[242:249], 0, v188, v188 op_sel_hi:[0,0,0]
	v_mfma_scale_f32_16x16x128_f8f6f4 v[10:13], v[208:215], v[242:249], 0, v188, v188 op_sel_hi:[0,0,0]
	v_mfma_scale_f32_16x16x128_f8f6f4 v[42:45], v[192:199], v[242:249], 0, v188, v188 op_sel_hi:[0,0,0]
	v_mfma_scale_f32_16x16x128_f8f6f4 v[46:49], v[2:9], v[242:249], 0, v188, v188 op_sel_hi:[0,0,0]
	s_setprio 0
	s_barrier
	ds_read_b128 v[2:5], v189 offset:32768
	ds_read_b128 v[6:9], v189 offset:33792
	ds_read_b128 v[192:195], v189 offset:34816
	ds_read_b128 v[196:199], v189 offset:35840
	ds_read_b128 v[200:203], v189 offset:49152
	ds_read_b128 v[204:207], v189 offset:50176
	ds_read_b128 v[208:211], v189 offset:51200
	ds_read_b128 v[212:215], v189 offset:52224
	s_add_u32 s50, s50, 0x80000
	s_addc_u32 s51, s51, 0
	s_mov_b32 m0, s52
	v_lshl_add_u64 v[186:187], s[50:51], 0, v[154:155]
	ds_read_b128 v[216:219], v190 offset:32768
	ds_read_b128 v[220:223], v190 offset:33792
	ds_read_b128 v[224:227], v190 offset:34816
	ds_read_b128 v[228:231], v190 offset:35840
	ds_read_b128 v[232:235], v190 offset:36864
	ds_read_b128 v[236:239], v190 offset:37888
	ds_read_b128 v[242:245], v190 offset:38912
	ds_read_b128 v[246:249], v190 offset:39936
	global_load_lds_dwordx4 v[186:187], off
	v_lshl_add_u64 v[186:187], s[50:51], 0, v[158:159]
	s_mov_b32 m0, s53
	s_nop 0
	global_load_lds_dwordx4 v[186:187], off
	s_waitcnt vmcnt(8)
	s_waitcnt lgkmcnt(0)
	s_barrier
	s_setprio 1
	s_waitcnt lgkmcnt(0)
	v_mfma_scale_f32_16x16x128_f8f6f4 v[134:137], v[2:9], v[216:223], v[134:137], v188, v188 op_sel_hi:[0,0,0]
	v_mfma_scale_f32_16x16x128_f8f6f4 v[130:133], v[192:199], v[216:223], v[130:133], v188, v188 op_sel_hi:[0,0,0]
	v_mfma_scale_f32_16x16x128_f8f6f4 v[98:101], v[208:215], v[216:223], v[98:101], v188, v188 op_sel_hi:[0,0,0]
	v_mfma_scale_f32_16x16x128_f8f6f4 v[102:105], v[200:207], v[216:223], v[102:105], v188, v188 op_sel_hi:[0,0,0]
	v_mfma_scale_f32_16x16x128_f8f6f4 v[94:97], v[200:207], v[224:231], v[94:97], v188, v188 op_sel_hi:[0,0,0]
	v_mfma_scale_f32_16x16x128_f8f6f4 v[90:93], v[208:215], v[224:231], v[90:93], v188, v188 op_sel_hi:[0,0,0]
	v_mfma_scale_f32_16x16x128_f8f6f4 v[122:125], v[192:199], v[224:231], v[122:125], v188, v188 op_sel_hi:[0,0,0]
	v_mfma_scale_f32_16x16x128_f8f6f4 v[126:129], v[2:9], v[224:231], v[126:129], v188, v188 op_sel_hi:[0,0,0]
	s_setprio 0
	s_setprio 1
	v_mfma_scale_f32_16x16x128_f8f6f4 v[118:121], v[2:9], v[232:239], v[118:121], v188, v188 op_sel_hi:[0,0,0]
	v_mfma_scale_f32_16x16x128_f8f6f4 v[114:117], v[192:199], v[232:239], v[114:117], v188, v188 op_sel_hi:[0,0,0]
	v_mfma_scale_f32_16x16x128_f8f6f4 v[82:85], v[208:215], v[232:239], v[82:85], v188, v188 op_sel_hi:[0,0,0]
	v_mfma_scale_f32_16x16x128_f8f6f4 v[86:89], v[200:207], v[232:239], v[86:89], v188, v188 op_sel_hi:[0,0,0]
	v_mfma_scale_f32_16x16x128_f8f6f4 v[78:81], v[200:207], v[242:249], v[78:81], v188, v188 op_sel_hi:[0,0,0]
	v_mfma_scale_f32_16x16x128_f8f6f4 v[74:77], v[208:215], v[242:249], v[74:77], v188, v188 op_sel_hi:[0,0,0]
	v_mfma_scale_f32_16x16x128_f8f6f4 v[106:109], v[192:199], v[242:249], v[106:109], v188, v188 op_sel_hi:[0,0,0]
	v_mfma_scale_f32_16x16x128_f8f6f4 v[110:113], v[2:9], v[242:249], v[110:113], v188, v188 op_sel_hi:[0,0,0]
	s_setprio 0
	s_barrier
	s_mov_b32 m0, s70
	v_lshl_add_u64 v[174:175], v[174:175], 0, s[18:19]
	s_add_u32 s48, s48, 0x80080
	ds_read_b128 v[216:219], v190 offset:49152
	ds_read_b128 v[220:223], v190 offset:50176
	ds_read_b128 v[224:227], v190 offset:51200
	ds_read_b128 v[228:231], v190 offset:52224
	ds_read_b128 v[232:235], v190 offset:53248
	ds_read_b128 v[236:239], v190 offset:54272
	ds_read_b128 v[242:245], v190 offset:55296
	ds_read_b128 v[246:249], v190 offset:56320
	global_load_lds_dwordx4 v[174:175], off
	v_lshl_add_u64 v[174:175], v[176:177], 0, s[18:19]
	s_mov_b32 m0, s71
	s_addc_u32 s49, s49, 0
	global_load_lds_dwordx4 v[174:175], off
	v_lshl_add_u64 v[174:175], s[48:49], 0, v[156:157]
	s_mov_b32 m0, s74
	s_nop 0
	global_load_lds_dwordx4 v[174:175], off
	v_lshl_add_u64 v[174:175], s[48:49], 0, v[160:161]
	s_mov_b32 m0, s75
	s_nop 0
	global_load_lds_dwordx4 v[174:175], off
	v_lshl_add_u64 v[174:175], v[182:183], 0, s[18:19]
	s_mov_b32 m0, s72
	s_nop 0
	global_load_lds_dwordx4 v[174:175], off
	v_lshl_add_u64 v[174:175], v[184:185], 0, s[18:19]
	s_mov_b32 m0, s73
	s_nop 0
	global_load_lds_dwordx4 v[174:175], off
	s_waitcnt vmcnt(8)
	s_waitcnt lgkmcnt(0)
	s_barrier
	s_setprio 1
	s_waitcnt lgkmcnt(0)
	v_mfma_scale_f32_16x16x128_f8f6f4 v[70:73], v[2:9], v[216:223], v[70:73], v188, v188 op_sel_hi:[0,0,0]
	v_mfma_scale_f32_16x16x128_f8f6f4 v[66:69], v[192:199], v[216:223], v[66:69], v188, v188 op_sel_hi:[0,0,0]
	v_mfma_scale_f32_16x16x128_f8f6f4 v[34:37], v[208:215], v[216:223], v[34:37], v188, v188 op_sel_hi:[0,0,0]
	v_mfma_scale_f32_16x16x128_f8f6f4 v[38:41], v[200:207], v[216:223], v[38:41], v188, v188 op_sel_hi:[0,0,0]
	v_mfma_scale_f32_16x16x128_f8f6f4 v[30:33], v[200:207], v[224:231], v[30:33], v188, v188 op_sel_hi:[0,0,0]
	v_mfma_scale_f32_16x16x128_f8f6f4 v[26:29], v[208:215], v[224:231], v[26:29], v188, v188 op_sel_hi:[0,0,0]
	v_mfma_scale_f32_16x16x128_f8f6f4 v[58:61], v[192:199], v[224:231], v[58:61], v188, v188 op_sel_hi:[0,0,0]
	v_mfma_scale_f32_16x16x128_f8f6f4 v[62:65], v[2:9], v[224:231], v[62:65], v188, v188 op_sel_hi:[0,0,0]
	s_setprio 0
	s_setprio 1
	v_mfma_scale_f32_16x16x128_f8f6f4 v[54:57], v[2:9], v[232:239], v[54:57], v188, v188 op_sel_hi:[0,0,0]
	v_mfma_scale_f32_16x16x128_f8f6f4 v[50:53], v[192:199], v[232:239], v[50:53], v188, v188 op_sel_hi:[0,0,0]
	v_mfma_scale_f32_16x16x128_f8f6f4 v[18:21], v[208:215], v[232:239], v[18:21], v188, v188 op_sel_hi:[0,0,0]
	v_mfma_scale_f32_16x16x128_f8f6f4 v[22:25], v[200:207], v[232:239], v[22:25], v188, v188 op_sel_hi:[0,0,0]
	v_mfma_scale_f32_16x16x128_f8f6f4 v[14:17], v[200:207], v[242:249], v[14:17], v188, v188 op_sel_hi:[0,0,0]
	v_mfma_scale_f32_16x16x128_f8f6f4 v[10:13], v[208:215], v[242:249], v[10:13], v188, v188 op_sel_hi:[0,0,0]
	v_mfma_scale_f32_16x16x128_f8f6f4 v[42:45], v[192:199], v[242:249], v[42:45], v188, v188 op_sel_hi:[0,0,0]
	v_mfma_scale_f32_16x16x128_f8f6f4 v[46:49], v[2:9], v[242:249], v[46:49], v188, v188 op_sel_hi:[0,0,0]
	s_setprio 0
	s_barrier
	s_cmp_lt_u32 s86, 3
	s_cbranch_scc1 .LBB0_796
	s_add_u32 s48, s55, s62
	s_addc_u32 s49, s61, s41
	s_add_u32 s46, s46, 0x80180
	s_addc_u32 s47, s47, 0
	s_add_u32 s41, s44, 0x200
	v_lshl_add_u64 v[174:175], v[172:173], 2, s[48:49]
	s_addc_u32 s50, s45, 0
	s_mov_b32 s51, 4
	s_cmp_eq_u32 s86, s51
	s_cselect_b64 s[44:45], -1, 0
	s_cmp_lg_u32 s86, s51
	s_cbranch_scc1 .LBB0_794

.LBB0_794:
	ds_read_b128 v[2:5], v189
	ds_read_b128 v[6:9], v189 offset:1024
	ds_read_b128 v[192:195], v189 offset:2048
	ds_read_b128 v[196:199], v189 offset:3072
	ds_read_b128 v[200:203], v189 offset:16384
	ds_read_b128 v[204:207], v189 offset:17408
	ds_read_b128 v[208:211], v189 offset:18432
	ds_read_b128 v[212:215], v189 offset:19456
	s_add_u32 s48, s46, 0xfff80080
	s_addc_u32 s49, s47, -1
	s_and_b64 s[44:45], s[44:45], exec
	s_cselect_b32 s44, s4, s41
	s_cselect_b32 s49, s1, s49
	s_cselect_b32 s48, s0, s48
	s_cselect_b32 s45, s5, s50
	s_mov_b32 m0, s37
	v_lshl_add_u64 v[176:177], s[46:47], 0, v[162:163]
	ds_read_b128 v[216:219], v190
	ds_read_b128 v[220:223], v190 offset:1024
	ds_read_b128 v[224:227], v190 offset:2048
	ds_read_b128 v[228:231], v190 offset:3072
	ds_read_b128 v[232:235], v190 offset:4096
	ds_read_b128 v[236:239], v190 offset:5120
	ds_read_b128 v[242:245], v190 offset:6144
	ds_read_b128 v[246:249], v190 offset:7168
	global_load_lds_dwordx4 v[176:177], off
	v_lshl_add_u64 v[176:177], s[46:47], 0, v[164:165]
	s_mov_b32 m0, s39
	s_nop 0
	global_load_lds_dwordx4 v[176:177], off
	s_waitcnt vmcnt(8)
	s_waitcnt lgkmcnt(0)
	s_barrier
	s_setprio 1
	s_waitcnt lgkmcnt(0)
	v_mfma_scale_f32_16x16x128_f8f6f4 v[134:137], v[2:9], v[216:223], v[134:137], v188, v188 op_sel_hi:[0,0,0]
	v_mfma_scale_f32_16x16x128_f8f6f4 v[130:133], v[192:199], v[216:223], v[130:133], v188, v188 op_sel_hi:[0,0,0]
	v_mfma_scale_f32_16x16x128_f8f6f4 v[98:101], v[208:215], v[216:223], v[98:101], v188, v188 op_sel_hi:[0,0,0]
	v_mfma_scale_f32_16x16x128_f8f6f4 v[102:105], v[200:207], v[216:223], v[102:105], v188, v188 op_sel_hi:[0,0,0]
	v_mfma_scale_f32_16x16x128_f8f6f4 v[94:97], v[200:207], v[224:231], v[94:97], v188, v188 op_sel_hi:[0,0,0]
	v_mfma_scale_f32_16x16x128_f8f6f4 v[90:93], v[208:215], v[224:231], v[90:93], v188, v188 op_sel_hi:[0,0,0]
	v_mfma_scale_f32_16x16x128_f8f6f4 v[122:125], v[192:199], v[224:231], v[122:125], v188, v188 op_sel_hi:[0,0,0]
	v_mfma_scale_f32_16x16x128_f8f6f4 v[126:129], v[2:9], v[224:231], v[126:129], v188, v188 op_sel_hi:[0,0,0]
	s_setprio 0
	s_setprio 1
	v_mfma_scale_f32_16x16x128_f8f6f4 v[118:121], v[2:9], v[232:239], v[118:121], v188, v188 op_sel_hi:[0,0,0]
	v_mfma_scale_f32_16x16x128_f8f6f4 v[114:117], v[192:199], v[232:239], v[114:117], v188, v188 op_sel_hi:[0,0,0]
	v_mfma_scale_f32_16x16x128_f8f6f4 v[82:85], v[208:215], v[232:239], v[82:85], v188, v188 op_sel_hi:[0,0,0]
	v_mfma_scale_f32_16x16x128_f8f6f4 v[86:89], v[200:207], v[232:239], v[86:89], v188, v188 op_sel_hi:[0,0,0]
	v_mfma_scale_f32_16x16x128_f8f6f4 v[78:81], v[200:207], v[242:249], v[78:81], v188, v188 op_sel_hi:[0,0,0]
	v_mfma_scale_f32_16x16x128_f8f6f4 v[74:77], v[208:215], v[242:249], v[74:77], v188, v188 op_sel_hi:[0,0,0]
	v_mfma_scale_f32_16x16x128_f8f6f4 v[106:109], v[192:199], v[242:249], v[106:109], v188, v188 op_sel_hi:[0,0,0]
	v_mfma_scale_f32_16x16x128_f8f6f4 v[110:113], v[2:9], v[242:249], v[110:113], v188, v188 op_sel_hi:[0,0,0]
	s_setprio 0
	s_barrier
	s_mov_b32 m0, s9
	v_lshl_add_u64 v[176:177], s[44:45], 0, v[156:157]
	s_add_u32 s62, s44, 0x80000
	ds_read_b128 v[216:219], v190 offset:16384
	ds_read_b128 v[220:223], v190 offset:17408
	ds_read_b128 v[224:227], v190 offset:18432
	ds_read_b128 v[228:231], v190 offset:19456
	ds_read_b128 v[232:235], v190 offset:20480
	ds_read_b128 v[236:239], v190 offset:21504
	ds_read_b128 v[242:245], v190 offset:22528
	ds_read_b128 v[246:249], v190 offset:23552
	global_load_lds_dwordx4 v[176:177], off
	v_lshl_add_u64 v[182:183], s[44:45], 0, v[160:161]
	s_mov_b32 m0, s27
	s_addc_u32 s63, s45, 0
	global_load_lds_dwordx4 v[182:183], off
	v_lshl_add_u64 v[184:185], s[62:63], 0, v[156:157]
	s_mov_b32 m0, s33
	v_lshl_add_u64 v[186:187], s[48:49], 0, v[158:159]
	global_load_lds_dwordx4 v[184:185], off
	v_lshl_add_u64 v[184:185], s[62:63], 0, v[160:161]
	s_mov_b32 m0, s35
	s_nop 0
	global_load_lds_dwordx4 v[184:185], off
	v_lshl_add_u64 v[184:185], s[48:49], 0, v[154:155]
	s_mov_b32 m0, s8
	s_nop 0
	global_load_lds_dwordx4 v[184:185], off
	s_mov_b32 m0, s43
	s_nop 0
	global_load_lds_dwordx4 v[186:187], off
	s_waitcnt vmcnt(8)
	s_waitcnt lgkmcnt(0)
	s_barrier
	s_setprio 1
	s_waitcnt lgkmcnt(0)
	v_mfma_scale_f32_16x16x128_f8f6f4 v[70:73], v[2:9], v[216:223], v[70:73], v188, v188 op_sel_hi:[0,0,0]
	v_mfma_scale_f32_16x16x128_f8f6f4 v[66:69], v[192:199], v[216:223], v[66:69], v188, v188 op_sel_hi:[0,0,0]
	v_mfma_scale_f32_16x16x128_f8f6f4 v[34:37], v[208:215], v[216:223], v[34:37], v188, v188 op_sel_hi:[0,0,0]
	v_mfma_scale_f32_16x16x128_f8f6f4 v[38:41], v[200:207], v[216:223], v[38:41], v188, v188 op_sel_hi:[0,0,0]
	v_mfma_scale_f32_16x16x128_f8f6f4 v[30:33], v[200:207], v[224:231], v[30:33], v188, v188 op_sel_hi:[0,0,0]
	v_mfma_scale_f32_16x16x128_f8f6f4 v[26:29], v[208:215], v[224:231], v[26:29], v188, v188 op_sel_hi:[0,0,0]
	v_mfma_scale_f32_16x16x128_f8f6f4 v[58:61], v[192:199], v[224:231], v[58:61], v188, v188 op_sel_hi:[0,0,0]
	v_mfma_scale_f32_16x16x128_f8f6f4 v[62:65], v[2:9], v[224:231], v[62:65], v188, v188 op_sel_hi:[0,0,0]
	s_setprio 0
	s_setprio 1
	v_mfma_scale_f32_16x16x128_f8f6f4 v[54:57], v[2:9], v[232:239], v[54:57], v188, v188 op_sel_hi:[0,0,0]
	v_mfma_scale_f32_16x16x128_f8f6f4 v[50:53], v[192:199], v[232:239], v[50:53], v188, v188 op_sel_hi:[0,0,0]
	v_mfma_scale_f32_16x16x128_f8f6f4 v[18:21], v[208:215], v[232:239], v[18:21], v188, v188 op_sel_hi:[0,0,0]
	v_mfma_scale_f32_16x16x128_f8f6f4 v[22:25], v[200:207], v[232:239], v[22:25], v188, v188 op_sel_hi:[0,0,0]
	v_mfma_scale_f32_16x16x128_f8f6f4 v[14:17], v[200:207], v[242:249], v[14:17], v188, v188 op_sel_hi:[0,0,0]
	v_mfma_scale_f32_16x16x128_f8f6f4 v[10:13], v[208:215], v[242:249], v[10:13], v188, v188 op_sel_hi:[0,0,0]
	v_mfma_scale_f32_16x16x128_f8f6f4 v[42:45], v[192:199], v[242:249], v[42:45], v188, v188 op_sel_hi:[0,0,0]
	v_mfma_scale_f32_16x16x128_f8f6f4 v[46:49], v[2:9], v[242:249], v[46:49], v188, v188 op_sel_hi:[0,0,0]
	s_setprio 0
	s_barrier
	ds_read_b128 v[192:195], v189 offset:32768
	ds_read_b128 v[196:199], v189 offset:33792
	ds_read_b128 v[200:203], v189 offset:34816
	ds_read_b128 v[204:207], v189 offset:35840
	ds_read_b128 v[2:5], v189 offset:49152
	ds_read_b128 v[6:9], v189 offset:50176
	ds_read_b128 v[208:211], v189 offset:51200
	ds_read_b128 v[212:215], v189 offset:52224
	s_add_u32 s48, s48, 0x80000
	s_addc_u32 s49, s49, 0
	s_mov_b32 m0, s52
	v_lshl_add_u64 v[252:253], s[48:49], 0, v[154:155]
	ds_read_b128 v[216:219], v190 offset:32768
	ds_read_b128 v[220:223], v190 offset:33792
	ds_read_b128 v[224:227], v190 offset:34816
	ds_read_b128 v[228:231], v190 offset:35840
	ds_read_b128 v[232:235], v190 offset:36864
	ds_read_b128 v[236:239], v190 offset:37888
	ds_read_b128 v[242:245], v190 offset:38912
	ds_read_b128 v[246:249], v190 offset:39936
	global_load_lds_dwordx4 v[252:253], off
	v_lshl_add_u64 v[252:253], s[48:49], 0, v[158:159]
	s_mov_b32 m0, s53
	s_nop 0
	global_load_lds_dwordx4 v[252:253], off
	s_waitcnt vmcnt(8)
	s_waitcnt lgkmcnt(0)
	s_barrier
	s_setprio 1
	s_waitcnt lgkmcnt(0)
	v_mfma_scale_f32_16x16x128_f8f6f4 v[134:137], v[192:199], v[216:223], v[134:137], v188, v188 op_sel_hi:[0,0,0]
	v_mfma_scale_f32_16x16x128_f8f6f4 v[130:133], v[200:207], v[216:223], v[130:133], v188, v188 op_sel_hi:[0,0,0]
	v_mfma_scale_f32_16x16x128_f8f6f4 v[98:101], v[208:215], v[216:223], v[98:101], v188, v188 op_sel_hi:[0,0,0]
	v_mfma_scale_f32_16x16x128_f8f6f4 v[102:105], v[2:9], v[216:223], v[102:105], v188, v188 op_sel_hi:[0,0,0]
	v_mfma_scale_f32_16x16x128_f8f6f4 v[94:97], v[2:9], v[224:231], v[94:97], v188, v188 op_sel_hi:[0,0,0]
	v_mfma_scale_f32_16x16x128_f8f6f4 v[90:93], v[208:215], v[224:231], v[90:93], v188, v188 op_sel_hi:[0,0,0]
	v_mfma_scale_f32_16x16x128_f8f6f4 v[122:125], v[200:207], v[224:231], v[122:125], v188, v188 op_sel_hi:[0,0,0]
	v_mfma_scale_f32_16x16x128_f8f6f4 v[126:129], v[192:199], v[224:231], v[126:129], v188, v188 op_sel_hi:[0,0,0]
	s_setprio 0
	s_setprio 1
	v_mfma_scale_f32_16x16x128_f8f6f4 v[118:121], v[192:199], v[232:239], v[118:121], v188, v188 op_sel_hi:[0,0,0]
	v_mfma_scale_f32_16x16x128_f8f6f4 v[114:117], v[200:207], v[232:239], v[114:117], v188, v188 op_sel_hi:[0,0,0]
	v_mfma_scale_f32_16x16x128_f8f6f4 v[82:85], v[208:215], v[232:239], v[82:85], v188, v188 op_sel_hi:[0,0,0]
	v_mfma_scale_f32_16x16x128_f8f6f4 v[86:89], v[2:9], v[232:239], v[86:89], v188, v188 op_sel_hi:[0,0,0]
	v_mfma_scale_f32_16x16x128_f8f6f4 v[78:81], v[2:9], v[242:249], v[78:81], v188, v188 op_sel_hi:[0,0,0]
	v_mfma_scale_f32_16x16x128_f8f6f4 v[74:77], v[208:215], v[242:249], v[74:77], v188, v188 op_sel_hi:[0,0,0]
	v_mfma_scale_f32_16x16x128_f8f6f4 v[106:109], v[200:207], v[242:249], v[106:109], v188, v188 op_sel_hi:[0,0,0]
	v_mfma_scale_f32_16x16x128_f8f6f4 v[110:113], v[192:199], v[242:249], v[110:113], v188, v188 op_sel_hi:[0,0,0]
	s_setprio 0
	s_barrier
	s_mov_b32 m0, s70
	v_lshl_add_u64 v[176:177], v[176:177], 0, s[18:19]
	s_add_u32 s44, s44, 0x80080
	ds_read_b128 v[216:219], v190 offset:49152
	ds_read_b128 v[220:223], v190 offset:50176
	ds_read_b128 v[224:227], v190 offset:51200
	ds_read_b128 v[228:231], v190 offset:52224
	ds_read_b128 v[232:235], v190 offset:53248
	ds_read_b128 v[236:239], v190 offset:54272
	ds_read_b128 v[242:245], v190 offset:55296
	ds_read_b128 v[246:249], v190 offset:56320
	global_load_lds_dwordx4 v[176:177], off
	v_lshl_add_u64 v[176:177], v[182:183], 0, s[18:19]
	s_mov_b32 m0, s71
	s_addc_u32 s45, s45, 0
	global_load_lds_dwordx4 v[176:177], off
	v_lshl_add_u64 v[176:177], s[44:45], 0, v[156:157]
	s_mov_b32 m0, s74
	s_nop 0
	global_load_lds_dwordx4 v[176:177], off
	v_lshl_add_u64 v[176:177], s[44:45], 0, v[160:161]
	s_mov_b32 m0, s75
	s_nop 0
	global_load_lds_dwordx4 v[176:177], off
	v_lshl_add_u64 v[176:177], v[184:185], 0, s[18:19]
	s_mov_b32 m0, s72
	s_nop 0
	global_load_lds_dwordx4 v[176:177], off
	v_lshl_add_u64 v[176:177], v[186:187], 0, s[18:19]
	s_mov_b32 m0, s73
	s_nop 0
	global_load_lds_dwordx4 v[176:177], off
	s_waitcnt vmcnt(8)
	s_waitcnt lgkmcnt(0)
	s_barrier
	s_setprio 1
	s_waitcnt lgkmcnt(0)
	v_mfma_scale_f32_16x16x128_f8f6f4 v[70:73], v[192:199], v[216:223], v[70:73], v188, v188 op_sel_hi:[0,0,0]
	v_mfma_scale_f32_16x16x128_f8f6f4 v[66:69], v[200:207], v[216:223], v[66:69], v188, v188 op_sel_hi:[0,0,0]
	v_mfma_scale_f32_16x16x128_f8f6f4 v[34:37], v[208:215], v[216:223], v[34:37], v188, v188 op_sel_hi:[0,0,0]
	v_mfma_scale_f32_16x16x128_f8f6f4 v[38:41], v[2:9], v[216:223], v[38:41], v188, v188 op_sel_hi:[0,0,0]
	v_mfma_scale_f32_16x16x128_f8f6f4 v[30:33], v[2:9], v[224:231], v[30:33], v188, v188 op_sel_hi:[0,0,0]
	v_mfma_scale_f32_16x16x128_f8f6f4 v[26:29], v[208:215], v[224:231], v[26:29], v188, v188 op_sel_hi:[0,0,0]
	v_mfma_scale_f32_16x16x128_f8f6f4 v[58:61], v[200:207], v[224:231], v[58:61], v188, v188 op_sel_hi:[0,0,0]
	v_mfma_scale_f32_16x16x128_f8f6f4 v[62:65], v[192:199], v[224:231], v[62:65], v188, v188 op_sel_hi:[0,0,0]
	s_setprio 0
	s_setprio 1
	v_mfma_scale_f32_16x16x128_f8f6f4 v[54:57], v[192:199], v[232:239], v[54:57], v188, v188 op_sel_hi:[0,0,0]
	v_mfma_scale_f32_16x16x128_f8f6f4 v[50:53], v[200:207], v[232:239], v[50:53], v188, v188 op_sel_hi:[0,0,0]
	v_mfma_scale_f32_16x16x128_f8f6f4 v[18:21], v[208:215], v[232:239], v[18:21], v188, v188 op_sel_hi:[0,0,0]
	v_mfma_scale_f32_16x16x128_f8f6f4 v[22:25], v[2:9], v[232:239], v[22:25], v188, v188 op_sel_hi:[0,0,0]
	v_mfma_scale_f32_16x16x128_f8f6f4 v[14:17], v[2:9], v[242:249], v[14:17], v188, v188 op_sel_hi:[0,0,0]
	v_mfma_scale_f32_16x16x128_f8f6f4 v[10:13], v[208:215], v[242:249], v[10:13], v188, v188 op_sel_hi:[0,0,0]
	v_mfma_scale_f32_16x16x128_f8f6f4 v[42:45], v[200:207], v[242:249], v[42:45], v188, v188 op_sel_hi:[0,0,0]
	v_mfma_scale_f32_16x16x128_f8f6f4 v[46:49], v[192:199], v[242:249], v[46:49], v188, v188 op_sel_hi:[0,0,0]
	s_setprio 0
	s_barrier
	s_add_i32 s44, s51, 2
	s_add_u32 s46, s46, 0x100
	s_addc_u32 s47, s47, 0
	s_add_u32 s41, s41, 0x100
	s_addc_u32 s50, s50, 0
	s_cmp_ge_i32 s51, s86
	s_cbranch_scc1 .LBB0_796
	s_mov_b32 s51, s44
	s_cmp_eq_u32 s86, s51
	s_cselect_b64 s[44:45], -1, 0
	s_cmp_lg_u32 s86, s51
	s_cbranch_scc0 .LBB0_793
	s_branch .LBB0_794

.LBB0_946:
	s_ashr_i32 s37, s36, 31
	ds_read_b128 v[18:21], v192
	ds_read_b128 v[22:25], v192 offset:1024
	ds_read_b128 v[26:29], v192 offset:2048
	ds_read_b128 v[30:33], v192 offset:3072
	ds_read_b128 v[2:5], v192 offset:16384
	ds_read_b128 v[6:9], v192 offset:17408
	ds_read_b128 v[10:13], v192 offset:18432
	ds_read_b128 v[14:17], v192 offset:19456
	s_lshl_b64 s[38:39], s[36:37], 20
	s_add_u32 s38, s22, s38
	s_addc_u32 s39, s23, s39
	s_and_b64 s[40:41], s[2:3], exec
	s_cselect_b32 s37, s39, s47
	s_cselect_b32 s84, s38, s46
	s_ashr_i32 s27, s26, 31
	s_lshl_b64 s[40:41], s[26:27], 20
	s_add_u32 s40, s25, s40
	s_addc_u32 s41, s35, s41
	s_and_b64 s[48:49], s[2:3], exec
	s_cselect_b32 s27, s41, s45
	s_cselect_b32 s85, s40, s44
	s_add_u32 s48, s46, 0x80080
	s_addc_u32 s49, s47, 0
	s_mov_b32 m0, s80
	v_lshl_add_u64 v[218:219], s[48:49], 0, v[164:165]
	ds_read_b128 v[184:187], v193
	ds_read_b128 v[188:191], v193 offset:1024
	ds_read_b128 v[194:197], v193 offset:2048
	ds_read_b128 v[198:201], v193 offset:3072
	ds_read_b128 v[202:205], v193 offset:4096
	ds_read_b128 v[206:209], v193 offset:5120
	ds_read_b128 v[210:213], v193 offset:6144
	ds_read_b128 v[214:217], v193 offset:7168
	global_load_lds_dwordx4 v[218:219], off
	v_lshl_add_u64 v[218:219], s[48:49], 0, v[168:169]
	s_mov_b32 m0, s81
	s_nop 0
	global_load_lds_dwordx4 v[218:219], off
	s_waitcnt vmcnt(8)
	s_waitcnt lgkmcnt(0)
	s_barrier
	s_setprio 1
	s_waitcnt lgkmcnt(0)
	v_mfma_scale_f32_16x16x128_f8f6f4 v[158:161], v[18:25], v[184:191], 0, v181, v181 op_sel_hi:[0,0,0]
	v_mfma_scale_f32_16x16x128_f8f6f4 v[154:157], v[26:33], v[184:191], 0, v181, v181 op_sel_hi:[0,0,0]
	v_mfma_scale_f32_16x16x128_f8f6f4 v[122:125], v[10:17], v[184:191], 0, v181, v181 op_sel_hi:[0,0,0]
	v_mfma_scale_f32_16x16x128_f8f6f4 v[126:129], v[2:9], v[184:191], 0, v181, v181 op_sel_hi:[0,0,0]
	v_mfma_scale_f32_16x16x128_f8f6f4 v[118:121], v[2:9], v[194:201], 0, v181, v181 op_sel_hi:[0,0,0]
	v_mfma_scale_f32_16x16x128_f8f6f4 v[114:117], v[10:17], v[194:201], 0, v181, v181 op_sel_hi:[0,0,0]
	v_mfma_scale_f32_16x16x128_f8f6f4 v[146:149], v[26:33], v[194:201], 0, v181, v181 op_sel_hi:[0,0,0]
	v_mfma_scale_f32_16x16x128_f8f6f4 v[150:153], v[18:25], v[194:201], 0, v181, v181 op_sel_hi:[0,0,0]
	s_setprio 0
	s_setprio 1
	v_mfma_scale_f32_16x16x128_f8f6f4 v[142:145], v[18:25], v[202:209], 0, v181, v181 op_sel_hi:[0,0,0]
	v_mfma_scale_f32_16x16x128_f8f6f4 v[138:141], v[26:33], v[202:209], 0, v181, v181 op_sel_hi:[0,0,0]
	v_mfma_scale_f32_16x16x128_f8f6f4 v[106:109], v[10:17], v[202:209], 0, v181, v181 op_sel_hi:[0,0,0]
	v_mfma_scale_f32_16x16x128_f8f6f4 v[110:113], v[2:9], v[202:209], 0, v181, v181 op_sel_hi:[0,0,0]
	v_mfma_scale_f32_16x16x128_f8f6f4 v[102:105], v[2:9], v[210:217], 0, v181, v181 op_sel_hi:[0,0,0]
	v_mfma_scale_f32_16x16x128_f8f6f4 v[98:101], v[10:17], v[210:217], 0, v181, v181 op_sel_hi:[0,0,0]
	v_mfma_scale_f32_16x16x128_f8f6f4 v[130:133], v[26:33], v[210:217], 0, v181, v181 op_sel_hi:[0,0,0]
	v_mfma_scale_f32_16x16x128_f8f6f4 v[134:137], v[18:25], v[210:217], 0, v181, v181 op_sel_hi:[0,0,0]
	s_setprio 0
	s_barrier
	v_lshl_add_u64 v[184:185], s[44:45], 0, v[166:167]
	s_mov_b32 m0, s52
	v_lshl_add_u64 v[186:187], v[184:185], 0, s[14:15]
	ds_read_b128 v[194:197], v193 offset:16384
	ds_read_b128 v[198:201], v193 offset:17408
	ds_read_b128 v[202:205], v193 offset:18432
	ds_read_b128 v[206:209], v193 offset:19456
	ds_read_b128 v[210:213], v193 offset:20480
	ds_read_b128 v[214:217], v193 offset:21504
	ds_read_b128 v[218:221], v193 offset:22528
	ds_read_b128 v[222:225], v193 offset:23552
	global_load_lds_dwordx4 v[186:187], off
	v_lshl_add_u64 v[186:187], s[44:45], 0, v[170:171]
	s_add_u32 s48, s44, 0x80100
	v_lshl_add_u64 v[188:189], v[186:187], 0, s[14:15]
	s_mov_b32 m0, s53
	s_addc_u32 s49, s45, 0
	global_load_lds_dwordx4 v[188:189], off
	v_lshl_add_u64 v[188:189], s[48:49], 0, v[166:167]
	s_mov_b32 m0, s54
	s_nop 0
	global_load_lds_dwordx4 v[188:189], off
	v_lshl_add_u64 v[188:189], s[48:49], 0, v[170:171]
	s_mov_b32 m0, s55
	s_nop 0
	global_load_lds_dwordx4 v[188:189], off
	v_lshl_add_u64 v[188:189], s[46:47], 0, v[164:165]
	v_lshl_add_u64 v[190:191], v[188:189], 0, s[14:15]
	s_mov_b32 m0, s43
	s_nop 0
	global_load_lds_dwordx4 v[190:191], off
	v_lshl_add_u64 v[190:191], s[46:47], 0, v[168:169]
	v_lshl_add_u64 v[226:227], v[190:191], 0, s[14:15]
	s_mov_b32 m0, s61
	s_nop 0
	global_load_lds_dwordx4 v[226:227], off
	s_waitcnt vmcnt(8)
	s_waitcnt lgkmcnt(0)
	s_barrier
	s_setprio 1
	s_waitcnt lgkmcnt(0)
	v_mfma_scale_f32_16x16x128_f8f6f4 v[94:97], v[18:25], v[194:201], 0, v181, v181 op_sel_hi:[0,0,0]
	v_mfma_scale_f32_16x16x128_f8f6f4 v[90:93], v[26:33], v[194:201], 0, v181, v181 op_sel_hi:[0,0,0]
	v_mfma_scale_f32_16x16x128_f8f6f4 v[58:61], v[10:17], v[194:201], 0, v181, v181 op_sel_hi:[0,0,0]
	v_mfma_scale_f32_16x16x128_f8f6f4 v[62:65], v[2:9], v[194:201], 0, v181, v181 op_sel_hi:[0,0,0]
	v_mfma_scale_f32_16x16x128_f8f6f4 v[54:57], v[2:9], v[202:209], 0, v181, v181 op_sel_hi:[0,0,0]
	v_mfma_scale_f32_16x16x128_f8f6f4 v[50:53], v[10:17], v[202:209], 0, v181, v181 op_sel_hi:[0,0,0]
	v_mfma_scale_f32_16x16x128_f8f6f4 v[82:85], v[26:33], v[202:209], 0, v181, v181 op_sel_hi:[0,0,0]
	v_mfma_scale_f32_16x16x128_f8f6f4 v[86:89], v[18:25], v[202:209], 0, v181, v181 op_sel_hi:[0,0,0]
	s_setprio 0
	s_setprio 1
	v_mfma_scale_f32_16x16x128_f8f6f4 v[78:81], v[18:25], v[210:217], 0, v181, v181 op_sel_hi:[0,0,0]
	v_mfma_scale_f32_16x16x128_f8f6f4 v[74:77], v[26:33], v[210:217], 0, v181, v181 op_sel_hi:[0,0,0]
	v_mfma_scale_f32_16x16x128_f8f6f4 v[42:45], v[10:17], v[210:217], 0, v181, v181 op_sel_hi:[0,0,0]
	v_mfma_scale_f32_16x16x128_f8f6f4 v[46:49], v[2:9], v[210:217], 0, v181, v181 op_sel_hi:[0,0,0]
	v_mfma_scale_f32_16x16x128_f8f6f4 v[38:41], v[2:9], v[218:225], 0, v181, v181 op_sel_hi:[0,0,0]
	v_mfma_scale_f32_16x16x128_f8f6f4 v[34:37], v[10:17], v[218:225], 0, v181, v181 op_sel_hi:[0,0,0]
	v_mfma_scale_f32_16x16x128_f8f6f4 v[66:69], v[26:33], v[218:225], 0, v181, v181 op_sel_hi:[0,0,0]
	v_mfma_scale_f32_16x16x128_f8f6f4 v[70:73], v[18:25], v[218:225], 0, v181, v181 op_sel_hi:[0,0,0]
	s_setprio 0
	s_barrier
	ds_read_b128 v[18:21], v192 offset:32768
	ds_read_b128 v[22:25], v192 offset:33792
	ds_read_b128 v[26:29], v192 offset:34816
	ds_read_b128 v[30:33], v192 offset:35840
	ds_read_b128 v[2:5], v192 offset:49152
	ds_read_b128 v[6:9], v192 offset:50176
	ds_read_b128 v[10:13], v192 offset:51200
	ds_read_b128 v[14:17], v192 offset:52224
	s_add_u32 s48, s46, 0x80100
	s_addc_u32 s49, s47, 0
	s_mov_b32 m0, s68
	v_lshl_add_u64 v[226:227], s[48:49], 0, v[164:165]
	ds_read_b128 v[194:197], v193 offset:32768
	ds_read_b128 v[198:201], v193 offset:33792
	ds_read_b128 v[202:205], v193 offset:34816
	ds_read_b128 v[206:209], v193 offset:35840
	ds_read_b128 v[210:213], v193 offset:36864
	ds_read_b128 v[214:217], v193 offset:37888
	ds_read_b128 v[218:221], v193 offset:38912
	ds_read_b128 v[222:225], v193 offset:39936
	global_load_lds_dwordx4 v[226:227], off
	v_lshl_add_u64 v[226:227], s[48:49], 0, v[168:169]
	s_mov_b32 m0, s69
	s_nop 0
	global_load_lds_dwordx4 v[226:227], off
	s_waitcnt vmcnt(8)
	s_waitcnt lgkmcnt(0)
	s_barrier
	s_setprio 1
	s_waitcnt lgkmcnt(0)
	v_mfma_scale_f32_16x16x128_f8f6f4 v[158:161], v[18:25], v[194:201], v[158:161], v181, v181 op_sel_hi:[0,0,0]
	v_mfma_scale_f32_16x16x128_f8f6f4 v[154:157], v[26:33], v[194:201], v[154:157], v181, v181 op_sel_hi:[0,0,0]
	v_mfma_scale_f32_16x16x128_f8f6f4 v[122:125], v[10:17], v[194:201], v[122:125], v181, v181 op_sel_hi:[0,0,0]
	v_mfma_scale_f32_16x16x128_f8f6f4 v[126:129], v[2:9], v[194:201], v[126:129], v181, v181 op_sel_hi:[0,0,0]
	v_mfma_scale_f32_16x16x128_f8f6f4 v[118:121], v[2:9], v[202:209], v[118:121], v181, v181 op_sel_hi:[0,0,0]
	v_mfma_scale_f32_16x16x128_f8f6f4 v[114:117], v[10:17], v[202:209], v[114:117], v181, v181 op_sel_hi:[0,0,0]
	v_mfma_scale_f32_16x16x128_f8f6f4 v[146:149], v[26:33], v[202:209], v[146:149], v181, v181 op_sel_hi:[0,0,0]
	v_mfma_scale_f32_16x16x128_f8f6f4 v[150:153], v[18:25], v[202:209], v[150:153], v181, v181 op_sel_hi:[0,0,0]
	s_setprio 0
	s_setprio 1
	v_mfma_scale_f32_16x16x128_f8f6f4 v[142:145], v[18:25], v[210:217], v[142:145], v181, v181 op_sel_hi:[0,0,0]
	v_mfma_scale_f32_16x16x128_f8f6f4 v[138:141], v[26:33], v[210:217], v[138:141], v181, v181 op_sel_hi:[0,0,0]
	v_mfma_scale_f32_16x16x128_f8f6f4 v[106:109], v[10:17], v[210:217], v[106:109], v181, v181 op_sel_hi:[0,0,0]
	v_mfma_scale_f32_16x16x128_f8f6f4 v[110:113], v[2:9], v[210:217], v[110:113], v181, v181 op_sel_hi:[0,0,0]
	v_mfma_scale_f32_16x16x128_f8f6f4 v[102:105], v[2:9], v[218:225], v[102:105], v181, v181 op_sel_hi:[0,0,0]
	v_mfma_scale_f32_16x16x128_f8f6f4 v[98:101], v[10:17], v[218:225], v[98:101], v181, v181 op_sel_hi:[0,0,0]
	v_mfma_scale_f32_16x16x128_f8f6f4 v[130:133], v[26:33], v[218:225], v[130:133], v181, v181 op_sel_hi:[0,0,0]
	v_mfma_scale_f32_16x16x128_f8f6f4 v[134:137], v[18:25], v[218:225], v[134:137], v181, v181 op_sel_hi:[0,0,0]
	s_setprio 0
	s_barrier
	s_mov_b32 m0, s74
	v_lshl_add_u64 v[184:185], v[184:185], 0, s[18:19]
	s_add_u32 s48, s44, 0x80180
	ds_read_b128 v[194:197], v193 offset:49152
	ds_read_b128 v[198:201], v193 offset:50176
	ds_read_b128 v[202:205], v193 offset:51200
	ds_read_b128 v[206:209], v193 offset:52224
	ds_read_b128 v[210:213], v193 offset:53248
	ds_read_b128 v[214:217], v193 offset:54272
	ds_read_b128 v[218:221], v193 offset:55296
	ds_read_b128 v[222:225], v193 offset:56320
	global_load_lds_dwordx4 v[184:185], off
	v_lshl_add_u64 v[184:185], v[186:187], 0, s[18:19]
	s_mov_b32 m0, s75
	s_addc_u32 s49, s45, 0
	global_load_lds_dwordx4 v[184:185], off
	v_lshl_add_u64 v[184:185], s[48:49], 0, v[166:167]
	s_mov_b32 m0, s78
	s_nop 0
	global_load_lds_dwordx4 v[184:185], off
	v_lshl_add_u64 v[184:185], s[48:49], 0, v[170:171]
	s_mov_b32 m0, s79
	s_nop 0
	global_load_lds_dwordx4 v[184:185], off
	v_lshl_add_u64 v[184:185], v[188:189], 0, s[18:19]
	s_mov_b32 m0, s76
	s_nop 0
	global_load_lds_dwordx4 v[184:185], off
	v_lshl_add_u64 v[184:185], v[190:191], 0, s[18:19]
	s_mov_b32 m0, s77
	s_nop 0
	global_load_lds_dwordx4 v[184:185], off
	s_waitcnt vmcnt(8)
	s_waitcnt lgkmcnt(0)
	s_barrier
	s_setprio 1
	s_waitcnt lgkmcnt(0)
	v_mfma_scale_f32_16x16x128_f8f6f4 v[94:97], v[18:25], v[194:201], v[94:97], v181, v181 op_sel_hi:[0,0,0]
	v_mfma_scale_f32_16x16x128_f8f6f4 v[90:93], v[26:33], v[194:201], v[90:93], v181, v181 op_sel_hi:[0,0,0]
	v_mfma_scale_f32_16x16x128_f8f6f4 v[58:61], v[10:17], v[194:201], v[58:61], v181, v181 op_sel_hi:[0,0,0]
	v_mfma_scale_f32_16x16x128_f8f6f4 v[62:65], v[2:9], v[194:201], v[62:65], v181, v181 op_sel_hi:[0,0,0]
	v_mfma_scale_f32_16x16x128_f8f6f4 v[54:57], v[2:9], v[202:209], v[54:57], v181, v181 op_sel_hi:[0,0,0]
	v_mfma_scale_f32_16x16x128_f8f6f4 v[50:53], v[10:17], v[202:209], v[50:53], v181, v181 op_sel_hi:[0,0,0]
	v_mfma_scale_f32_16x16x128_f8f6f4 v[82:85], v[26:33], v[202:209], v[82:85], v181, v181 op_sel_hi:[0,0,0]
	v_mfma_scale_f32_16x16x128_f8f6f4 v[86:89], v[18:25], v[202:209], v[86:89], v181, v181 op_sel_hi:[0,0,0]
	s_setprio 0
	s_setprio 1
	v_mfma_scale_f32_16x16x128_f8f6f4 v[78:81], v[18:25], v[210:217], v[78:81], v181, v181 op_sel_hi:[0,0,0]
	v_mfma_scale_f32_16x16x128_f8f6f4 v[74:77], v[26:33], v[210:217], v[74:77], v181, v181 op_sel_hi:[0,0,0]
	v_mfma_scale_f32_16x16x128_f8f6f4 v[42:45], v[10:17], v[210:217], v[42:45], v181, v181 op_sel_hi:[0,0,0]
	v_mfma_scale_f32_16x16x128_f8f6f4 v[46:49], v[2:9], v[210:217], v[46:49], v181, v181 op_sel_hi:[0,0,0]
	v_mfma_scale_f32_16x16x128_f8f6f4 v[38:41], v[2:9], v[218:225], v[38:41], v181, v181 op_sel_hi:[0,0,0]
	v_mfma_scale_f32_16x16x128_f8f6f4 v[34:37], v[10:17], v[218:225], v[34:37], v181, v181 op_sel_hi:[0,0,0]
	v_mfma_scale_f32_16x16x128_f8f6f4 v[66:69], v[26:33], v[218:225], v[66:69], v181, v181 op_sel_hi:[0,0,0]
	v_mfma_scale_f32_16x16x128_f8f6f4 v[70:73], v[18:25], v[218:225], v[70:73], v181, v181 op_sel_hi:[0,0,0]
	s_setprio 0
	s_barrier
	s_add_u32 s46, s46, 0x80180
	s_addc_u32 s47, s47, 0
	s_add_u32 s62, s44, 0x200
	s_addc_u32 s63, s45, 0
	s_mov_b32 s86, 0
.LBB0_947:
	ds_read_b128 v[2:5], v192
	ds_read_b128 v[6:9], v192 offset:1024
	ds_read_b128 v[18:21], v192 offset:2048
	ds_read_b128 v[22:25], v192 offset:3072
	ds_read_b128 v[26:29], v192 offset:16384
	ds_read_b128 v[30:33], v192 offset:17408
	ds_read_b128 v[184:187], v192 offset:18432
	ds_read_b128 v[188:191], v192 offset:19456
	s_add_u32 s44, s46, 0xfff80080
	s_addc_u32 s45, s47, -1
	s_cmp_eq_u32 s86, 28
	s_cselect_b32 s49, s37, s45
	s_cselect_b32 s48, s84, s44
	s_cselect_b32 s45, s27, s63
	s_cselect_b32 s44, s85, s62
	s_mov_b32 m0, s80
	v_lshl_add_u64 v[218:219], s[46:47], 0, v[172:173]
	ds_read_b128 v[10:13], v193
	ds_read_b128 v[14:17], v193 offset:1024
	ds_read_b128 v[194:197], v193 offset:2048
	ds_read_b128 v[198:201], v193 offset:3072
	ds_read_b128 v[202:205], v193 offset:4096
	ds_read_b128 v[206:209], v193 offset:5120
	ds_read_b128 v[210:213], v193 offset:6144
	ds_read_b128 v[214:217], v193 offset:7168
	global_load_lds_dwordx4 v[218:219], off
	v_lshl_add_u64 v[218:219], s[46:47], 0, v[174:175]
	s_mov_b32 m0, s81
	s_nop 0
	global_load_lds_dwordx4 v[218:219], off
	s_waitcnt vmcnt(8)
	s_waitcnt lgkmcnt(0)
	s_barrier
	s_setprio 1
	s_waitcnt lgkmcnt(0)
	v_mfma_scale_f32_16x16x128_f8f6f4 v[158:161], v[2:9], v[10:17], v[158:161], v181, v181 op_sel_hi:[0,0,0]
	v_mfma_scale_f32_16x16x128_f8f6f4 v[154:157], v[18:25], v[10:17], v[154:157], v181, v181 op_sel_hi:[0,0,0]
	v_mfma_scale_f32_16x16x128_f8f6f4 v[122:125], v[184:191], v[10:17], v[122:125], v181, v181 op_sel_hi:[0,0,0]
	v_mfma_scale_f32_16x16x128_f8f6f4 v[126:129], v[26:33], v[10:17], v[126:129], v181, v181 op_sel_hi:[0,0,0]
	v_mfma_scale_f32_16x16x128_f8f6f4 v[118:121], v[26:33], v[194:201], v[118:121], v181, v181 op_sel_hi:[0,0,0]
	v_mfma_scale_f32_16x16x128_f8f6f4 v[114:117], v[184:191], v[194:201], v[114:117], v181, v181 op_sel_hi:[0,0,0]
	v_mfma_scale_f32_16x16x128_f8f6f4 v[146:149], v[18:25], v[194:201], v[146:149], v181, v181 op_sel_hi:[0,0,0]
	v_mfma_scale_f32_16x16x128_f8f6f4 v[150:153], v[2:9], v[194:201], v[150:153], v181, v181 op_sel_hi:[0,0,0]
	s_setprio 0
	s_setprio 1
	v_mfma_scale_f32_16x16x128_f8f6f4 v[142:145], v[2:9], v[202:209], v[142:145], v181, v181 op_sel_hi:[0,0,0]
	v_mfma_scale_f32_16x16x128_f8f6f4 v[138:141], v[18:25], v[202:209], v[138:141], v181, v181 op_sel_hi:[0,0,0]
	v_mfma_scale_f32_16x16x128_f8f6f4 v[106:109], v[184:191], v[202:209], v[106:109], v181, v181 op_sel_hi:[0,0,0]
	v_mfma_scale_f32_16x16x128_f8f6f4 v[110:113], v[26:33], v[202:209], v[110:113], v181, v181 op_sel_hi:[0,0,0]
	v_mfma_scale_f32_16x16x128_f8f6f4 v[102:105], v[26:33], v[210:217], v[102:105], v181, v181 op_sel_hi:[0,0,0]
	v_mfma_scale_f32_16x16x128_f8f6f4 v[98:101], v[184:191], v[210:217], v[98:101], v181, v181 op_sel_hi:[0,0,0]
	v_mfma_scale_f32_16x16x128_f8f6f4 v[130:133], v[18:25], v[210:217], v[130:133], v181, v181 op_sel_hi:[0,0,0]
	v_mfma_scale_f32_16x16x128_f8f6f4 v[134:137], v[2:9], v[210:217], v[134:137], v181, v181 op_sel_hi:[0,0,0]
	s_setprio 0
	s_barrier
	s_mov_b32 m0, s52
	v_lshl_add_u64 v[10:11], s[44:45], 0, v[166:167]
	s_add_u32 s88, s44, 0x80000
	ds_read_b128 v[194:197], v193 offset:16384
	ds_read_b128 v[198:201], v193 offset:17408
	ds_read_b128 v[202:205], v193 offset:18432
	ds_read_b128 v[206:209], v193 offset:19456
	ds_read_b128 v[210:213], v193 offset:20480
	ds_read_b128 v[214:217], v193 offset:21504
	ds_read_b128 v[218:221], v193 offset:22528
	ds_read_b128 v[222:225], v193 offset:23552
	global_load_lds_dwordx4 v[10:11], off
	v_lshl_add_u64 v[12:13], s[44:45], 0, v[170:171]
	s_mov_b32 m0, s53
	s_addc_u32 s89, s45, 0
	global_load_lds_dwordx4 v[12:13], off
	v_lshl_add_u64 v[14:15], s[88:89], 0, v[166:167]
	s_mov_b32 m0, s54
	v_lshl_add_u64 v[16:17], s[48:49], 0, v[168:169]
	global_load_lds_dwordx4 v[14:15], off
	v_lshl_add_u64 v[14:15], s[88:89], 0, v[170:171]
	s_mov_b32 m0, s55
	s_nop 0
	global_load_lds_dwordx4 v[14:15], off
	v_lshl_add_u64 v[14:15], s[48:49], 0, v[164:165]
	s_mov_b32 m0, s43
	s_nop 0
	global_load_lds_dwordx4 v[14:15], off
	s_mov_b32 m0, s61
	s_nop 0
	global_load_lds_dwordx4 v[16:17], off
	s_waitcnt vmcnt(8)
	s_waitcnt lgkmcnt(0)
	s_barrier
	s_setprio 1
	s_waitcnt lgkmcnt(0)
	v_mfma_scale_f32_16x16x128_f8f6f4 v[94:97], v[2:9], v[194:201], v[94:97], v181, v181 op_sel_hi:[0,0,0]
	v_mfma_scale_f32_16x16x128_f8f6f4 v[90:93], v[18:25], v[194:201], v[90:93], v181, v181 op_sel_hi:[0,0,0]
	v_mfma_scale_f32_16x16x128_f8f6f4 v[58:61], v[184:191], v[194:201], v[58:61], v181, v181 op_sel_hi:[0,0,0]
	v_mfma_scale_f32_16x16x128_f8f6f4 v[62:65], v[26:33], v[194:201], v[62:65], v181, v181 op_sel_hi:[0,0,0]
	v_mfma_scale_f32_16x16x128_f8f6f4 v[54:57], v[26:33], v[202:209], v[54:57], v181, v181 op_sel_hi:[0,0,0]
	v_mfma_scale_f32_16x16x128_f8f6f4 v[50:53], v[184:191], v[202:209], v[50:53], v181, v181 op_sel_hi:[0,0,0]
	v_mfma_scale_f32_16x16x128_f8f6f4 v[82:85], v[18:25], v[202:209], v[82:85], v181, v181 op_sel_hi:[0,0,0]
	v_mfma_scale_f32_16x16x128_f8f6f4 v[86:89], v[2:9], v[202:209], v[86:89], v181, v181 op_sel_hi:[0,0,0]
	s_setprio 0
	s_setprio 1
	v_mfma_scale_f32_16x16x128_f8f6f4 v[78:81], v[2:9], v[210:217], v[78:81], v181, v181 op_sel_hi:[0,0,0]
	v_mfma_scale_f32_16x16x128_f8f6f4 v[74:77], v[18:25], v[210:217], v[74:77], v181, v181 op_sel_hi:[0,0,0]
	v_mfma_scale_f32_16x16x128_f8f6f4 v[42:45], v[184:191], v[210:217], v[42:45], v181, v181 op_sel_hi:[0,0,0]
	v_mfma_scale_f32_16x16x128_f8f6f4 v[46:49], v[26:33], v[210:217], v[46:49], v181, v181 op_sel_hi:[0,0,0]
	v_mfma_scale_f32_16x16x128_f8f6f4 v[38:41], v[26:33], v[218:225], v[38:41], v181, v181 op_sel_hi:[0,0,0]
	v_mfma_scale_f32_16x16x128_f8f6f4 v[34:37], v[184:191], v[218:225], v[34:37], v181, v181 op_sel_hi:[0,0,0]
	v_mfma_scale_f32_16x16x128_f8f6f4 v[66:69], v[18:25], v[218:225], v[66:69], v181, v181 op_sel_hi:[0,0,0]
	v_mfma_scale_f32_16x16x128_f8f6f4 v[70:73], v[2:9], v[218:225], v[70:73], v181, v181 op_sel_hi:[0,0,0]
	s_setprio 0
	s_barrier
	ds_read_b128 v[18:21], v192 offset:32768
	ds_read_b128 v[22:25], v192 offset:33792
	ds_read_b128 v[26:29], v192 offset:34816
	ds_read_b128 v[30:33], v192 offset:35840
	ds_read_b128 v[2:5], v192 offset:49152
	ds_read_b128 v[6:9], v192 offset:50176
	ds_read_b128 v[184:187], v192 offset:51200
	ds_read_b128 v[188:191], v192 offset:52224
	s_add_u32 s48, s48, 0x80000
	s_addc_u32 s49, s49, 0
	s_mov_b32 m0, s68
	v_lshl_add_u64 v[226:227], s[48:49], 0, v[164:165]
	ds_read_b128 v[194:197], v193 offset:32768
	ds_read_b128 v[198:201], v193 offset:33792
	ds_read_b128 v[202:205], v193 offset:34816
	ds_read_b128 v[206:209], v193 offset:35840
	ds_read_b128 v[210:213], v193 offset:36864
	ds_read_b128 v[214:217], v193 offset:37888
	ds_read_b128 v[218:221], v193 offset:38912
	ds_read_b128 v[222:225], v193 offset:39936
	global_load_lds_dwordx4 v[226:227], off
	v_lshl_add_u64 v[226:227], s[48:49], 0, v[168:169]
	s_mov_b32 m0, s69
	s_nop 0
	global_load_lds_dwordx4 v[226:227], off
	s_waitcnt vmcnt(8)
	s_waitcnt lgkmcnt(0)
	s_barrier
	s_setprio 1
	s_waitcnt lgkmcnt(0)
	v_mfma_scale_f32_16x16x128_f8f6f4 v[158:161], v[18:25], v[194:201], v[158:161], v181, v181 op_sel_hi:[0,0,0]
	v_mfma_scale_f32_16x16x128_f8f6f4 v[154:157], v[26:33], v[194:201], v[154:157], v181, v181 op_sel_hi:[0,0,0]
	v_mfma_scale_f32_16x16x128_f8f6f4 v[122:125], v[184:191], v[194:201], v[122:125], v181, v181 op_sel_hi:[0,0,0]
	v_mfma_scale_f32_16x16x128_f8f6f4 v[126:129], v[2:9], v[194:201], v[126:129], v181, v181 op_sel_hi:[0,0,0]
	v_mfma_scale_f32_16x16x128_f8f6f4 v[118:121], v[2:9], v[202:209], v[118:121], v181, v181 op_sel_hi:[0,0,0]
	v_mfma_scale_f32_16x16x128_f8f6f4 v[114:117], v[184:191], v[202:209], v[114:117], v181, v181 op_sel_hi:[0,0,0]
	v_mfma_scale_f32_16x16x128_f8f6f4 v[146:149], v[26:33], v[202:209], v[146:149], v181, v181 op_sel_hi:[0,0,0]
	v_mfma_scale_f32_16x16x128_f8f6f4 v[150:153], v[18:25], v[202:209], v[150:153], v181, v181 op_sel_hi:[0,0,0]
	s_setprio 0
	s_setprio 1
	v_mfma_scale_f32_16x16x128_f8f6f4 v[142:145], v[18:25], v[210:217], v[142:145], v181, v181 op_sel_hi:[0,0,0]
	v_mfma_scale_f32_16x16x128_f8f6f4 v[138:141], v[26:33], v[210:217], v[138:141], v181, v181 op_sel_hi:[0,0,0]
	v_mfma_scale_f32_16x16x128_f8f6f4 v[106:109], v[184:191], v[210:217], v[106:109], v181, v181 op_sel_hi:[0,0,0]
	v_mfma_scale_f32_16x16x128_f8f6f4 v[110:113], v[2:9], v[210:217], v[110:113], v181, v181 op_sel_hi:[0,0,0]
	v_mfma_scale_f32_16x16x128_f8f6f4 v[102:105], v[2:9], v[218:225], v[102:105], v181, v181 op_sel_hi:[0,0,0]
	v_mfma_scale_f32_16x16x128_f8f6f4 v[98:101], v[184:191], v[218:225], v[98:101], v181, v181 op_sel_hi:[0,0,0]
	v_mfma_scale_f32_16x16x128_f8f6f4 v[130:133], v[26:33], v[218:225], v[130:133], v181, v181 op_sel_hi:[0,0,0]
	v_mfma_scale_f32_16x16x128_f8f6f4 v[134:137], v[18:25], v[218:225], v[134:137], v181, v181 op_sel_hi:[0,0,0]
	s_setprio 0
	s_barrier
	s_mov_b32 m0, s74
	v_lshl_add_u64 v[10:11], v[10:11], 0, s[4:5]
	s_add_u32 s44, s44, 0x80080
	ds_read_b128 v[194:197], v193 offset:49152
	ds_read_b128 v[198:201], v193 offset:50176
	ds_read_b128 v[202:205], v193 offset:51200
	ds_read_b128 v[206:209], v193 offset:52224
	ds_read_b128 v[210:213], v193 offset:53248
	ds_read_b128 v[214:217], v193 offset:54272
	ds_read_b128 v[218:221], v193 offset:55296
	ds_read_b128 v[222:225], v193 offset:56320
	global_load_lds_dwordx4 v[10:11], off
	v_lshl_add_u64 v[10:11], v[12:13], 0, s[4:5]
	s_mov_b32 m0, s75
	s_addc_u32 s45, s45, 0
	global_load_lds_dwordx4 v[10:11], off
	v_lshl_add_u64 v[10:11], s[44:45], 0, v[166:167]
	s_mov_b32 m0, s78
	s_nop 0
	global_load_lds_dwordx4 v[10:11], off
	v_lshl_add_u64 v[10:11], s[44:45], 0, v[170:171]
	s_mov_b32 m0, s79
	s_nop 0
	global_load_lds_dwordx4 v[10:11], off
	v_lshl_add_u64 v[10:11], v[14:15], 0, s[4:5]
	s_mov_b32 m0, s76
	s_nop 0
	global_load_lds_dwordx4 v[10:11], off
	v_lshl_add_u64 v[10:11], v[16:17], 0, s[4:5]
	s_mov_b32 m0, s77
	s_nop 0
	global_load_lds_dwordx4 v[10:11], off
	s_waitcnt vmcnt(8)
	s_waitcnt lgkmcnt(0)
	s_barrier
	s_setprio 1
	s_waitcnt lgkmcnt(0)
	v_mfma_scale_f32_16x16x128_f8f6f4 v[94:97], v[18:25], v[194:201], v[94:97], v181, v181 op_sel_hi:[0,0,0]
	v_mfma_scale_f32_16x16x128_f8f6f4 v[90:93], v[26:33], v[194:201], v[90:93], v181, v181 op_sel_hi:[0,0,0]
	v_mfma_scale_f32_16x16x128_f8f6f4 v[58:61], v[184:191], v[194:201], v[58:61], v181, v181 op_sel_hi:[0,0,0]
	v_mfma_scale_f32_16x16x128_f8f6f4 v[62:65], v[2:9], v[194:201], v[62:65], v181, v181 op_sel_hi:[0,0,0]
	v_mfma_scale_f32_16x16x128_f8f6f4 v[54:57], v[2:9], v[202:209], v[54:57], v181, v181 op_sel_hi:[0,0,0]
	v_mfma_scale_f32_16x16x128_f8f6f4 v[50:53], v[184:191], v[202:209], v[50:53], v181, v181 op_sel_hi:[0,0,0]
	v_mfma_scale_f32_16x16x128_f8f6f4 v[82:85], v[26:33], v[202:209], v[82:85], v181, v181 op_sel_hi:[0,0,0]
	v_mfma_scale_f32_16x16x128_f8f6f4 v[86:89], v[18:25], v[202:209], v[86:89], v181, v181 op_sel_hi:[0,0,0]
	s_setprio 0
	s_setprio 1
	v_mfma_scale_f32_16x16x128_f8f6f4 v[78:81], v[18:25], v[210:217], v[78:81], v181, v181 op_sel_hi:[0,0,0]
	v_mfma_scale_f32_16x16x128_f8f6f4 v[74:77], v[26:33], v[210:217], v[74:77], v181, v181 op_sel_hi:[0,0,0]
	v_mfma_scale_f32_16x16x128_f8f6f4 v[42:45], v[184:191], v[210:217], v[42:45], v181, v181 op_sel_hi:[0,0,0]
	v_mfma_scale_f32_16x16x128_f8f6f4 v[46:49], v[2:9], v[210:217], v[46:49], v181, v181 op_sel_hi:[0,0,0]
	v_mfma_scale_f32_16x16x128_f8f6f4 v[38:41], v[2:9], v[218:225], v[38:41], v181, v181 op_sel_hi:[0,0,0]
	v_mfma_scale_f32_16x16x128_f8f6f4 v[34:37], v[184:191], v[218:225], v[34:37], v181, v181 op_sel_hi:[0,0,0]
	v_mfma_scale_f32_16x16x128_f8f6f4 v[66:69], v[26:33], v[218:225], v[66:69], v181, v181 op_sel_hi:[0,0,0]
	v_mfma_scale_f32_16x16x128_f8f6f4 v[70:73], v[18:25], v[218:225], v[70:73], v181, v181 op_sel_hi:[0,0,0]
	s_setprio 0
	s_barrier
	s_add_i32 s86, s86, 2
	s_add_u32 s46, s46, 0x100
	s_addc_u32 s47, s47, 0
	s_add_u32 s62, s62, 0x100
	s_addc_u32 s63, s63, 0
	s_cmp_gt_u32 s86, 29
	s_cbranch_scc0 .LBB0_947
	s_and_b64 vcc, exec, s[6:7]
	s_cbranch_vccz .LBB0_950
	s_barrier

.LBB0_1031:
	ds_read_b128 v[2:5], v189
	ds_read_b128 v[6:9], v189 offset:1024
	ds_read_b128 v[192:195], v189 offset:2048
	ds_read_b128 v[196:199], v189 offset:3072
	ds_read_b128 v[200:203], v189 offset:16384
	ds_read_b128 v[204:207], v189 offset:17408
	ds_read_b128 v[208:211], v189 offset:18432
	ds_read_b128 v[212:215], v189 offset:19456
	s_add_u32 s25, s36, 0x100
	s_addc_u32 s83, s37, 0
	s_and_b64 s[40:41], s[38:39], exec
	s_cselect_b32 s41, s1, s83
	s_cselect_b32 s40, s0, s25
	s_add_u32 s25, s26, 0x100
	s_addc_u32 s83, s27, 0
	s_and_b64 s[38:39], s[38:39], exec
	s_cselect_b32 s39, s5, s83
	s_cselect_b32 s38, s4, s25
	s_add_u32 s84, s36, 0x158080
	s_addc_u32 s85, s37, 0
	s_add_i32 s25, s23, 0xc000
	v_lshl_add_u64 v[174:175], s[84:85], 0, v[154:155]
	s_mov_b32 m0, s25
	s_add_i32 s83, s23, 0xe000
	ds_read_b128 v[216:219], v190
	ds_read_b128 v[220:223], v190 offset:1024
	ds_read_b128 v[224:227], v190 offset:2048
	ds_read_b128 v[228:231], v190 offset:3072
	ds_read_b128 v[232:235], v190 offset:4096
	ds_read_b128 v[236:239], v190 offset:5120
	ds_read_b128 v[240:243], v190 offset:6144
	ds_read_b128 v[244:247], v190 offset:7168
	global_load_lds_dwordx4 v[174:175], off
	v_lshl_add_u64 v[174:175], s[84:85], 0, v[158:159]
	s_mov_b32 m0, s83
	s_nop 0
	global_load_lds_dwordx4 v[174:175], off
	s_waitcnt vmcnt(8)
	s_waitcnt lgkmcnt(0)
	s_barrier
	s_setprio 1
	s_waitcnt lgkmcnt(0)
	v_mfma_scale_f32_16x16x128_f8f6f4 v[134:137], v[2:9], v[216:223], 0, v188, v188 op_sel_hi:[0,0,0]
	v_mfma_scale_f32_16x16x128_f8f6f4 v[130:133], v[192:199], v[216:223], 0, v188, v188 op_sel_hi:[0,0,0]
	v_mfma_scale_f32_16x16x128_f8f6f4 v[98:101], v[208:215], v[216:223], 0, v188, v188 op_sel_hi:[0,0,0]
	v_mfma_scale_f32_16x16x128_f8f6f4 v[102:105], v[200:207], v[216:223], 0, v188, v188 op_sel_hi:[0,0,0]
	v_mfma_scale_f32_16x16x128_f8f6f4 v[94:97], v[200:207], v[224:231], 0, v188, v188 op_sel_hi:[0,0,0]
	v_mfma_scale_f32_16x16x128_f8f6f4 v[90:93], v[208:215], v[224:231], 0, v188, v188 op_sel_hi:[0,0,0]
	v_mfma_scale_f32_16x16x128_f8f6f4 v[122:125], v[192:199], v[224:231], 0, v188, v188 op_sel_hi:[0,0,0]
	v_mfma_scale_f32_16x16x128_f8f6f4 v[126:129], v[2:9], v[224:231], 0, v188, v188 op_sel_hi:[0,0,0]
	s_setprio 0
	s_setprio 1
	v_mfma_scale_f32_16x16x128_f8f6f4 v[118:121], v[2:9], v[232:239], 0, v188, v188 op_sel_hi:[0,0,0]
	v_mfma_scale_f32_16x16x128_f8f6f4 v[114:117], v[192:199], v[232:239], 0, v188, v188 op_sel_hi:[0,0,0]
	v_mfma_scale_f32_16x16x128_f8f6f4 v[82:85], v[208:215], v[232:239], 0, v188, v188 op_sel_hi:[0,0,0]
	v_mfma_scale_f32_16x16x128_f8f6f4 v[86:89], v[200:207], v[232:239], 0, v188, v188 op_sel_hi:[0,0,0]
	v_mfma_scale_f32_16x16x128_f8f6f4 v[78:81], v[200:207], v[240:247], 0, v188, v188 op_sel_hi:[0,0,0]
	v_mfma_scale_f32_16x16x128_f8f6f4 v[74:77], v[208:215], v[240:247], 0, v188, v188 op_sel_hi:[0,0,0]
	v_mfma_scale_f32_16x16x128_f8f6f4 v[106:109], v[192:199], v[240:247], 0, v188, v188 op_sel_hi:[0,0,0]
	v_mfma_scale_f32_16x16x128_f8f6f4 v[110:113], v[2:9], v[240:247], 0, v188, v188 op_sel_hi:[0,0,0]
	s_setprio 0
	s_barrier
	s_mov_b32 m0, s33
	v_lshl_add_u64 v[174:175], s[38:39], 0, v[156:157]
	s_add_u32 s84, s38, 0x158000
	ds_read_b128 v[216:219], v190 offset:16384
	ds_read_b128 v[220:223], v190 offset:17408
	ds_read_b128 v[224:227], v190 offset:18432
	ds_read_b128 v[228:231], v190 offset:19456
	ds_read_b128 v[232:235], v190 offset:20480
	ds_read_b128 v[236:239], v190 offset:21504
	ds_read_b128 v[240:243], v190 offset:22528
	ds_read_b128 v[244:247], v190 offset:23552
	global_load_lds_dwordx4 v[174:175], off
	v_lshl_add_u64 v[176:177], s[38:39], 0, v[160:161]
	s_mov_b32 m0, s35
	s_addc_u32 s85, s39, 0
	global_load_lds_dwordx4 v[176:177], off
	v_lshl_add_u64 v[182:183], s[84:85], 0, v[156:157]
	s_mov_b32 m0, s42
	v_lshl_add_u64 v[184:185], s[40:41], 0, v[158:159]
	global_load_lds_dwordx4 v[182:183], off
	v_lshl_add_u64 v[182:183], s[84:85], 0, v[160:161]
	s_mov_b32 m0, s43
	s_nop 0
	global_load_lds_dwordx4 v[182:183], off
	v_lshl_add_u64 v[182:183], s[40:41], 0, v[154:155]
	s_mov_b32 m0, s23
	s_nop 0
	global_load_lds_dwordx4 v[182:183], off
	s_mov_b32 m0, s44
	s_nop 0
	global_load_lds_dwordx4 v[184:185], off
	s_waitcnt vmcnt(8)
	s_waitcnt lgkmcnt(0)
	s_barrier
	s_setprio 1
	s_waitcnt lgkmcnt(0)
	v_mfma_scale_f32_16x16x128_f8f6f4 v[70:73], v[2:9], v[216:223], 0, v188, v188 op_sel_hi:[0,0,0]
	v_mfma_scale_f32_16x16x128_f8f6f4 v[66:69], v[192:199], v[216:223], 0, v188, v188 op_sel_hi:[0,0,0]
	v_mfma_scale_f32_16x16x128_f8f6f4 v[34:37], v[208:215], v[216:223], 0, v188, v188 op_sel_hi:[0,0,0]
	v_mfma_scale_f32_16x16x128_f8f6f4 v[38:41], v[200:207], v[216:223], 0, v188, v188 op_sel_hi:[0,0,0]
	v_mfma_scale_f32_16x16x128_f8f6f4 v[30:33], v[200:207], v[224:231], 0, v188, v188 op_sel_hi:[0,0,0]
	v_mfma_scale_f32_16x16x128_f8f6f4 v[26:29], v[208:215], v[224:231], 0, v188, v188 op_sel_hi:[0,0,0]
	v_mfma_scale_f32_16x16x128_f8f6f4 v[58:61], v[192:199], v[224:231], 0, v188, v188 op_sel_hi:[0,0,0]
	v_mfma_scale_f32_16x16x128_f8f6f4 v[62:65], v[2:9], v[224:231], 0, v188, v188 op_sel_hi:[0,0,0]
	s_setprio 0
	s_setprio 1
	v_mfma_scale_f32_16x16x128_f8f6f4 v[54:57], v[2:9], v[232:239], 0, v188, v188 op_sel_hi:[0,0,0]
	v_mfma_scale_f32_16x16x128_f8f6f4 v[50:53], v[192:199], v[232:239], 0, v188, v188 op_sel_hi:[0,0,0]
	v_mfma_scale_f32_16x16x128_f8f6f4 v[18:21], v[208:215], v[232:239], 0, v188, v188 op_sel_hi:[0,0,0]
	v_mfma_scale_f32_16x16x128_f8f6f4 v[22:25], v[200:207], v[232:239], 0, v188, v188 op_sel_hi:[0,0,0]
	v_mfma_scale_f32_16x16x128_f8f6f4 v[14:17], v[200:207], v[240:247], 0, v188, v188 op_sel_hi:[0,0,0]
	v_mfma_scale_f32_16x16x128_f8f6f4 v[10:13], v[208:215], v[240:247], 0, v188, v188 op_sel_hi:[0,0,0]
	v_mfma_scale_f32_16x16x128_f8f6f4 v[42:45], v[192:199], v[240:247], 0, v188, v188 op_sel_hi:[0,0,0]
	v_mfma_scale_f32_16x16x128_f8f6f4 v[46:49], v[2:9], v[240:247], 0, v188, v188 op_sel_hi:[0,0,0]
	s_setprio 0
	s_barrier
	ds_read_b128 v[2:5], v189 offset:32768
	ds_read_b128 v[6:9], v189 offset:33792
	ds_read_b128 v[192:195], v189 offset:34816
	ds_read_b128 v[196:199], v189 offset:35840
	ds_read_b128 v[200:203], v189 offset:49152
	ds_read_b128 v[204:207], v189 offset:50176
	ds_read_b128 v[208:211], v189 offset:51200
	ds_read_b128 v[212:215], v189 offset:52224
	s_add_u32 s40, s40, 0x158000
	s_addc_u32 s41, s41, 0
	s_mov_b32 m0, s45
	v_lshl_add_u64 v[186:187], s[40:41], 0, v[154:155]
	ds_read_b128 v[216:219], v190 offset:32768
	ds_read_b128 v[220:223], v190 offset:33792
	ds_read_b128 v[224:227], v190 offset:34816
	ds_read_b128 v[228:231], v190 offset:35840
	ds_read_b128 v[232:235], v190 offset:36864
	ds_read_b128 v[236:239], v190 offset:37888
	ds_read_b128 v[240:243], v190 offset:38912
	ds_read_b128 v[244:247], v190 offset:39936
	global_load_lds_dwordx4 v[186:187], off
	v_lshl_add_u64 v[186:187], s[40:41], 0, v[158:159]
	s_mov_b32 m0, s46
	s_nop 0
	global_load_lds_dwordx4 v[186:187], off
	s_waitcnt vmcnt(8)
	s_waitcnt lgkmcnt(0)
	s_barrier
	s_setprio 1
	s_waitcnt lgkmcnt(0)
	v_mfma_scale_f32_16x16x128_f8f6f4 v[134:137], v[2:9], v[216:223], v[134:137], v188, v188 op_sel_hi:[0,0,0]
	v_mfma_scale_f32_16x16x128_f8f6f4 v[130:133], v[192:199], v[216:223], v[130:133], v188, v188 op_sel_hi:[0,0,0]
	v_mfma_scale_f32_16x16x128_f8f6f4 v[98:101], v[208:215], v[216:223], v[98:101], v188, v188 op_sel_hi:[0,0,0]
	v_mfma_scale_f32_16x16x128_f8f6f4 v[102:105], v[200:207], v[216:223], v[102:105], v188, v188 op_sel_hi:[0,0,0]
	v_mfma_scale_f32_16x16x128_f8f6f4 v[94:97], v[200:207], v[224:231], v[94:97], v188, v188 op_sel_hi:[0,0,0]
	v_mfma_scale_f32_16x16x128_f8f6f4 v[90:93], v[208:215], v[224:231], v[90:93], v188, v188 op_sel_hi:[0,0,0]
	v_mfma_scale_f32_16x16x128_f8f6f4 v[122:125], v[192:199], v[224:231], v[122:125], v188, v188 op_sel_hi:[0,0,0]
	v_mfma_scale_f32_16x16x128_f8f6f4 v[126:129], v[2:9], v[224:231], v[126:129], v188, v188 op_sel_hi:[0,0,0]
	s_setprio 0
	s_setprio 1
	v_mfma_scale_f32_16x16x128_f8f6f4 v[118:121], v[2:9], v[232:239], v[118:121], v188, v188 op_sel_hi:[0,0,0]
	v_mfma_scale_f32_16x16x128_f8f6f4 v[114:117], v[192:199], v[232:239], v[114:117], v188, v188 op_sel_hi:[0,0,0]
	v_mfma_scale_f32_16x16x128_f8f6f4 v[82:85], v[208:215], v[232:239], v[82:85], v188, v188 op_sel_hi:[0,0,0]
	v_mfma_scale_f32_16x16x128_f8f6f4 v[86:89], v[200:207], v[232:239], v[86:89], v188, v188 op_sel_hi:[0,0,0]
	v_mfma_scale_f32_16x16x128_f8f6f4 v[78:81], v[200:207], v[240:247], v[78:81], v188, v188 op_sel_hi:[0,0,0]
	v_mfma_scale_f32_16x16x128_f8f6f4 v[74:77], v[208:215], v[240:247], v[74:77], v188, v188 op_sel_hi:[0,0,0]
	v_mfma_scale_f32_16x16x128_f8f6f4 v[106:109], v[192:199], v[240:247], v[106:109], v188, v188 op_sel_hi:[0,0,0]
	v_mfma_scale_f32_16x16x128_f8f6f4 v[110:113], v[2:9], v[240:247], v[110:113], v188, v188 op_sel_hi:[0,0,0]
	s_setprio 0
	s_barrier
	s_mov_b32 m0, s52
	v_lshl_add_u64 v[174:175], v[174:175], 0, s[14:15]
	s_add_u32 s38, s38, 0x158080
	ds_read_b128 v[216:219], v190 offset:49152
	ds_read_b128 v[220:223], v190 offset:50176
	ds_read_b128 v[224:227], v190 offset:51200
	ds_read_b128 v[228:231], v190 offset:52224
	ds_read_b128 v[232:235], v190 offset:53248
	ds_read_b128 v[236:239], v190 offset:54272
	ds_read_b128 v[240:243], v190 offset:55296
	ds_read_b128 v[244:247], v190 offset:56320
	global_load_lds_dwordx4 v[174:175], off
	v_lshl_add_u64 v[174:175], v[176:177], 0, s[14:15]
	s_mov_b32 m0, s53
	s_addc_u32 s39, s39, 0
	global_load_lds_dwordx4 v[174:175], off
	v_lshl_add_u64 v[174:175], s[38:39], 0, v[156:157]
	s_mov_b32 m0, s56
	s_nop 0
	global_load_lds_dwordx4 v[174:175], off
	v_lshl_add_u64 v[174:175], s[38:39], 0, v[160:161]
	s_mov_b32 m0, s57
	s_nop 0
	global_load_lds_dwordx4 v[174:175], off
	v_lshl_add_u64 v[174:175], v[182:183], 0, s[14:15]
	s_mov_b32 m0, s54
	s_nop 0
	global_load_lds_dwordx4 v[174:175], off
	v_lshl_add_u64 v[174:175], v[184:185], 0, s[14:15]
	s_mov_b32 m0, s55
	s_nop 0
	global_load_lds_dwordx4 v[174:175], off
	s_waitcnt vmcnt(8)
	s_waitcnt lgkmcnt(0)
	s_barrier
	s_setprio 1
	s_waitcnt lgkmcnt(0)
	v_mfma_scale_f32_16x16x128_f8f6f4 v[70:73], v[2:9], v[216:223], v[70:73], v188, v188 op_sel_hi:[0,0,0]
	v_mfma_scale_f32_16x16x128_f8f6f4 v[66:69], v[192:199], v[216:223], v[66:69], v188, v188 op_sel_hi:[0,0,0]
	v_mfma_scale_f32_16x16x128_f8f6f4 v[34:37], v[208:215], v[216:223], v[34:37], v188, v188 op_sel_hi:[0,0,0]
	v_mfma_scale_f32_16x16x128_f8f6f4 v[38:41], v[200:207], v[216:223], v[38:41], v188, v188 op_sel_hi:[0,0,0]
	v_mfma_scale_f32_16x16x128_f8f6f4 v[30:33], v[200:207], v[224:231], v[30:33], v188, v188 op_sel_hi:[0,0,0]
	v_mfma_scale_f32_16x16x128_f8f6f4 v[26:29], v[208:215], v[224:231], v[26:29], v188, v188 op_sel_hi:[0,0,0]
	v_mfma_scale_f32_16x16x128_f8f6f4 v[58:61], v[192:199], v[224:231], v[58:61], v188, v188 op_sel_hi:[0,0,0]
	v_mfma_scale_f32_16x16x128_f8f6f4 v[62:65], v[2:9], v[224:231], v[62:65], v188, v188 op_sel_hi:[0,0,0]
	s_setprio 0
	s_setprio 1
	v_mfma_scale_f32_16x16x128_f8f6f4 v[54:57], v[2:9], v[232:239], v[54:57], v188, v188 op_sel_hi:[0,0,0]
	v_mfma_scale_f32_16x16x128_f8f6f4 v[50:53], v[192:199], v[232:239], v[50:53], v188, v188 op_sel_hi:[0,0,0]
	v_mfma_scale_f32_16x16x128_f8f6f4 v[18:21], v[208:215], v[232:239], v[18:21], v188, v188 op_sel_hi:[0,0,0]
	v_mfma_scale_f32_16x16x128_f8f6f4 v[22:25], v[200:207], v[232:239], v[22:25], v188, v188 op_sel_hi:[0,0,0]
	v_mfma_scale_f32_16x16x128_f8f6f4 v[14:17], v[200:207], v[240:247], v[14:17], v188, v188 op_sel_hi:[0,0,0]
	v_mfma_scale_f32_16x16x128_f8f6f4 v[10:13], v[208:215], v[240:247], v[10:13], v188, v188 op_sel_hi:[0,0,0]
	v_mfma_scale_f32_16x16x128_f8f6f4 v[42:45], v[192:199], v[240:247], v[42:45], v188, v188 op_sel_hi:[0,0,0]
	v_mfma_scale_f32_16x16x128_f8f6f4 v[46:49], v[2:9], v[240:247], v[46:49], v188, v188 op_sel_hi:[0,0,0]
	s_setprio 0
	s_barrier
	s_cmp_lt_u32 s82, 3
	s_cbranch_scc1 .LBB0_1036
	s_add_u32 s38, s48, s63
	s_addc_u32 s39, s49, s62
	s_add_u32 s36, s36, 0x158180
	s_addc_u32 s37, s37, 0
	s_add_u32 s40, s26, 0x200
	v_lshl_add_u64 v[174:175], v[172:173], 2, s[38:39]
	s_addc_u32 s41, s27, 0
	s_mov_b32 s84, 4
	s_cmp_eq_u32 s82, s84
	s_cselect_b64 s[26:27], -1, 0
	s_cmp_lg_u32 s82, s84
	s_cbranch_scc1 .LBB0_1034

.LBB0_1034:
	ds_read_b128 v[2:5], v189
	ds_read_b128 v[6:9], v189 offset:1024
	ds_read_b128 v[192:195], v189 offset:2048
	ds_read_b128 v[196:199], v189 offset:3072
	ds_read_b128 v[200:203], v189 offset:16384
	ds_read_b128 v[204:207], v189 offset:17408
	ds_read_b128 v[208:211], v189 offset:18432
	ds_read_b128 v[212:215], v189 offset:19456
	s_add_u32 s38, s36, 0xffea8080
	s_addc_u32 s39, s37, -1
	s_and_b64 s[26:27], s[26:27], exec
	s_cselect_b32 s26, s4, s40
	s_cselect_b32 s39, s1, s39
	s_cselect_b32 s38, s0, s38
	s_cselect_b32 s27, s5, s41
	s_mov_b32 m0, s25
	v_lshl_add_u64 v[176:177], s[36:37], 0, v[162:163]
	ds_read_b128 v[216:219], v190
	ds_read_b128 v[220:223], v190 offset:1024
	ds_read_b128 v[224:227], v190 offset:2048
	ds_read_b128 v[228:231], v190 offset:3072
	ds_read_b128 v[232:235], v190 offset:4096
	ds_read_b128 v[236:239], v190 offset:5120
	ds_read_b128 v[240:243], v190 offset:6144
	ds_read_b128 v[244:247], v190 offset:7168
	global_load_lds_dwordx4 v[176:177], off
	v_lshl_add_u64 v[176:177], s[36:37], 0, v[164:165]
	s_mov_b32 m0, s83
	s_nop 0
	global_load_lds_dwordx4 v[176:177], off
	s_waitcnt vmcnt(8)
	s_waitcnt lgkmcnt(0)
	s_barrier
	s_setprio 1
	s_waitcnt lgkmcnt(0)
	v_mfma_scale_f32_16x16x128_f8f6f4 v[134:137], v[2:9], v[216:223], v[134:137], v188, v188 op_sel_hi:[0,0,0]
	v_mfma_scale_f32_16x16x128_f8f6f4 v[130:133], v[192:199], v[216:223], v[130:133], v188, v188 op_sel_hi:[0,0,0]
	v_mfma_scale_f32_16x16x128_f8f6f4 v[98:101], v[208:215], v[216:223], v[98:101], v188, v188 op_sel_hi:[0,0,0]
	v_mfma_scale_f32_16x16x128_f8f6f4 v[102:105], v[200:207], v[216:223], v[102:105], v188, v188 op_sel_hi:[0,0,0]
	v_mfma_scale_f32_16x16x128_f8f6f4 v[94:97], v[200:207], v[224:231], v[94:97], v188, v188 op_sel_hi:[0,0,0]
	v_mfma_scale_f32_16x16x128_f8f6f4 v[90:93], v[208:215], v[224:231], v[90:93], v188, v188 op_sel_hi:[0,0,0]
	v_mfma_scale_f32_16x16x128_f8f6f4 v[122:125], v[192:199], v[224:231], v[122:125], v188, v188 op_sel_hi:[0,0,0]
	v_mfma_scale_f32_16x16x128_f8f6f4 v[126:129], v[2:9], v[224:231], v[126:129], v188, v188 op_sel_hi:[0,0,0]
	s_setprio 0
	s_setprio 1
	v_mfma_scale_f32_16x16x128_f8f6f4 v[118:121], v[2:9], v[232:239], v[118:121], v188, v188 op_sel_hi:[0,0,0]
	v_mfma_scale_f32_16x16x128_f8f6f4 v[114:117], v[192:199], v[232:239], v[114:117], v188, v188 op_sel_hi:[0,0,0]
	v_mfma_scale_f32_16x16x128_f8f6f4 v[82:85], v[208:215], v[232:239], v[82:85], v188, v188 op_sel_hi:[0,0,0]
	v_mfma_scale_f32_16x16x128_f8f6f4 v[86:89], v[200:207], v[232:239], v[86:89], v188, v188 op_sel_hi:[0,0,0]
	v_mfma_scale_f32_16x16x128_f8f6f4 v[78:81], v[200:207], v[240:247], v[78:81], v188, v188 op_sel_hi:[0,0,0]
	v_mfma_scale_f32_16x16x128_f8f6f4 v[74:77], v[208:215], v[240:247], v[74:77], v188, v188 op_sel_hi:[0,0,0]
	v_mfma_scale_f32_16x16x128_f8f6f4 v[106:109], v[192:199], v[240:247], v[106:109], v188, v188 op_sel_hi:[0,0,0]
	v_mfma_scale_f32_16x16x128_f8f6f4 v[110:113], v[2:9], v[240:247], v[110:113], v188, v188 op_sel_hi:[0,0,0]
	s_setprio 0
	s_barrier
	s_mov_b32 m0, s33
	v_lshl_add_u64 v[176:177], s[26:27], 0, v[156:157]
	s_add_u32 s62, s26, 0x158000
	ds_read_b128 v[216:219], v190 offset:16384
	ds_read_b128 v[220:223], v190 offset:17408
	ds_read_b128 v[224:227], v190 offset:18432
	ds_read_b128 v[228:231], v190 offset:19456
	ds_read_b128 v[232:235], v190 offset:20480
	ds_read_b128 v[236:239], v190 offset:21504
	ds_read_b128 v[240:243], v190 offset:22528
	ds_read_b128 v[244:247], v190 offset:23552
	global_load_lds_dwordx4 v[176:177], off
	v_lshl_add_u64 v[182:183], s[26:27], 0, v[160:161]
	s_mov_b32 m0, s35
	s_addc_u32 s63, s27, 0
	global_load_lds_dwordx4 v[182:183], off
	v_lshl_add_u64 v[184:185], s[62:63], 0, v[156:157]
	s_mov_b32 m0, s42
	v_lshl_add_u64 v[186:187], s[38:39], 0, v[158:159]
	global_load_lds_dwordx4 v[184:185], off
	v_lshl_add_u64 v[184:185], s[62:63], 0, v[160:161]
	s_mov_b32 m0, s43
	s_nop 0
	global_load_lds_dwordx4 v[184:185], off
	v_lshl_add_u64 v[184:185], s[38:39], 0, v[154:155]
	s_mov_b32 m0, s23
	s_nop 0
	global_load_lds_dwordx4 v[184:185], off
	s_mov_b32 m0, s44
	s_nop 0
	global_load_lds_dwordx4 v[186:187], off
	s_waitcnt vmcnt(8)
	s_waitcnt lgkmcnt(0)
	s_barrier
	s_setprio 1
	s_waitcnt lgkmcnt(0)
	v_mfma_scale_f32_16x16x128_f8f6f4 v[70:73], v[2:9], v[216:223], v[70:73], v188, v188 op_sel_hi:[0,0,0]
	v_mfma_scale_f32_16x16x128_f8f6f4 v[66:69], v[192:199], v[216:223], v[66:69], v188, v188 op_sel_hi:[0,0,0]
	v_mfma_scale_f32_16x16x128_f8f6f4 v[34:37], v[208:215], v[216:223], v[34:37], v188, v188 op_sel_hi:[0,0,0]
	v_mfma_scale_f32_16x16x128_f8f6f4 v[38:41], v[200:207], v[216:223], v[38:41], v188, v188 op_sel_hi:[0,0,0]
	v_mfma_scale_f32_16x16x128_f8f6f4 v[30:33], v[200:207], v[224:231], v[30:33], v188, v188 op_sel_hi:[0,0,0]
	v_mfma_scale_f32_16x16x128_f8f6f4 v[26:29], v[208:215], v[224:231], v[26:29], v188, v188 op_sel_hi:[0,0,0]
	v_mfma_scale_f32_16x16x128_f8f6f4 v[58:61], v[192:199], v[224:231], v[58:61], v188, v188 op_sel_hi:[0,0,0]
	v_mfma_scale_f32_16x16x128_f8f6f4 v[62:65], v[2:9], v[224:231], v[62:65], v188, v188 op_sel_hi:[0,0,0]
	s_setprio 0
	s_setprio 1
	v_mfma_scale_f32_16x16x128_f8f6f4 v[54:57], v[2:9], v[232:239], v[54:57], v188, v188 op_sel_hi:[0,0,0]
	v_mfma_scale_f32_16x16x128_f8f6f4 v[50:53], v[192:199], v[232:239], v[50:53], v188, v188 op_sel_hi:[0,0,0]
	v_mfma_scale_f32_16x16x128_f8f6f4 v[18:21], v[208:215], v[232:239], v[18:21], v188, v188 op_sel_hi:[0,0,0]
	v_mfma_scale_f32_16x16x128_f8f6f4 v[22:25], v[200:207], v[232:239], v[22:25], v188, v188 op_sel_hi:[0,0,0]
	v_mfma_scale_f32_16x16x128_f8f6f4 v[14:17], v[200:207], v[240:247], v[14:17], v188, v188 op_sel_hi:[0,0,0]
	v_mfma_scale_f32_16x16x128_f8f6f4 v[10:13], v[208:215], v[240:247], v[10:13], v188, v188 op_sel_hi:[0,0,0]
	v_mfma_scale_f32_16x16x128_f8f6f4 v[42:45], v[192:199], v[240:247], v[42:45], v188, v188 op_sel_hi:[0,0,0]
	v_mfma_scale_f32_16x16x128_f8f6f4 v[46:49], v[2:9], v[240:247], v[46:49], v188, v188 op_sel_hi:[0,0,0]
	s_setprio 0
	s_barrier
	ds_read_b128 v[192:195], v189 offset:32768
	ds_read_b128 v[196:199], v189 offset:33792
	ds_read_b128 v[200:203], v189 offset:34816
	ds_read_b128 v[204:207], v189 offset:35840
	ds_read_b128 v[2:5], v189 offset:49152
	ds_read_b128 v[6:9], v189 offset:50176
	ds_read_b128 v[208:211], v189 offset:51200
	ds_read_b128 v[212:215], v189 offset:52224
	s_add_u32 s38, s38, 0x158000
	s_addc_u32 s39, s39, 0
	s_mov_b32 m0, s45
	v_lshl_add_u64 v[248:249], s[38:39], 0, v[154:155]
	ds_read_b128 v[216:219], v190 offset:32768
	ds_read_b128 v[220:223], v190 offset:33792
	ds_read_b128 v[224:227], v190 offset:34816
	ds_read_b128 v[228:231], v190 offset:35840
	ds_read_b128 v[232:235], v190 offset:36864
	ds_read_b128 v[236:239], v190 offset:37888
	ds_read_b128 v[240:243], v190 offset:38912
	ds_read_b128 v[244:247], v190 offset:39936
	global_load_lds_dwordx4 v[248:249], off
	v_lshl_add_u64 v[248:249], s[38:39], 0, v[158:159]
	s_mov_b32 m0, s46
	s_nop 0
	global_load_lds_dwordx4 v[248:249], off
	s_waitcnt vmcnt(8)
	s_waitcnt lgkmcnt(0)
	s_barrier
	s_setprio 1
	s_waitcnt lgkmcnt(0)
	v_mfma_scale_f32_16x16x128_f8f6f4 v[134:137], v[192:199], v[216:223], v[134:137], v188, v188 op_sel_hi:[0,0,0]
	v_mfma_scale_f32_16x16x128_f8f6f4 v[130:133], v[200:207], v[216:223], v[130:133], v188, v188 op_sel_hi:[0,0,0]
	v_mfma_scale_f32_16x16x128_f8f6f4 v[98:101], v[208:215], v[216:223], v[98:101], v188, v188 op_sel_hi:[0,0,0]
	v_mfma_scale_f32_16x16x128_f8f6f4 v[102:105], v[2:9], v[216:223], v[102:105], v188, v188 op_sel_hi:[0,0,0]
	v_mfma_scale_f32_16x16x128_f8f6f4 v[94:97], v[2:9], v[224:231], v[94:97], v188, v188 op_sel_hi:[0,0,0]
	v_mfma_scale_f32_16x16x128_f8f6f4 v[90:93], v[208:215], v[224:231], v[90:93], v188, v188 op_sel_hi:[0,0,0]
	v_mfma_scale_f32_16x16x128_f8f6f4 v[122:125], v[200:207], v[224:231], v[122:125], v188, v188 op_sel_hi:[0,0,0]
	v_mfma_scale_f32_16x16x128_f8f6f4 v[126:129], v[192:199], v[224:231], v[126:129], v188, v188 op_sel_hi:[0,0,0]
	s_setprio 0
	s_setprio 1
	v_mfma_scale_f32_16x16x128_f8f6f4 v[118:121], v[192:199], v[232:239], v[118:121], v188, v188 op_sel_hi:[0,0,0]
	v_mfma_scale_f32_16x16x128_f8f6f4 v[114:117], v[200:207], v[232:239], v[114:117], v188, v188 op_sel_hi:[0,0,0]
	v_mfma_scale_f32_16x16x128_f8f6f4 v[82:85], v[208:215], v[232:239], v[82:85], v188, v188 op_sel_hi:[0,0,0]
	v_mfma_scale_f32_16x16x128_f8f6f4 v[86:89], v[2:9], v[232:239], v[86:89], v188, v188 op_sel_hi:[0,0,0]
	v_mfma_scale_f32_16x16x128_f8f6f4 v[78:81], v[2:9], v[240:247], v[78:81], v188, v188 op_sel_hi:[0,0,0]
	v_mfma_scale_f32_16x16x128_f8f6f4 v[74:77], v[208:215], v[240:247], v[74:77], v188, v188 op_sel_hi:[0,0,0]
	v_mfma_scale_f32_16x16x128_f8f6f4 v[106:109], v[200:207], v[240:247], v[106:109], v188, v188 op_sel_hi:[0,0,0]
	v_mfma_scale_f32_16x16x128_f8f6f4 v[110:113], v[192:199], v[240:247], v[110:113], v188, v188 op_sel_hi:[0,0,0]
	s_setprio 0
	s_barrier
	s_mov_b32 m0, s52
	v_lshl_add_u64 v[176:177], v[176:177], 0, s[14:15]
	s_add_u32 s26, s26, 0x158080
	ds_read_b128 v[216:219], v190 offset:49152
	ds_read_b128 v[220:223], v190 offset:50176
	ds_read_b128 v[224:227], v190 offset:51200
	ds_read_b128 v[228:231], v190 offset:52224
	ds_read_b128 v[232:235], v190 offset:53248
	ds_read_b128 v[236:239], v190 offset:54272
	ds_read_b128 v[240:243], v190 offset:55296
	ds_read_b128 v[244:247], v190 offset:56320
	global_load_lds_dwordx4 v[176:177], off
	v_lshl_add_u64 v[176:177], v[182:183], 0, s[14:15]
	s_mov_b32 m0, s53
	s_addc_u32 s27, s27, 0
	global_load_lds_dwordx4 v[176:177], off
	v_lshl_add_u64 v[176:177], s[26:27], 0, v[156:157]
	s_mov_b32 m0, s56
	s_nop 0
	global_load_lds_dwordx4 v[176:177], off
	v_lshl_add_u64 v[176:177], s[26:27], 0, v[160:161]
	s_mov_b32 m0, s57
	s_nop 0
	global_load_lds_dwordx4 v[176:177], off
	v_lshl_add_u64 v[176:177], v[184:185], 0, s[14:15]
	s_mov_b32 m0, s54
	s_nop 0
	global_load_lds_dwordx4 v[176:177], off
	v_lshl_add_u64 v[176:177], v[186:187], 0, s[14:15]
	s_mov_b32 m0, s55
	s_nop 0
	global_load_lds_dwordx4 v[176:177], off
	s_waitcnt vmcnt(8)
	s_waitcnt lgkmcnt(0)
	s_barrier
	s_setprio 1
	s_waitcnt lgkmcnt(0)
	v_mfma_scale_f32_16x16x128_f8f6f4 v[70:73], v[192:199], v[216:223], v[70:73], v188, v188 op_sel_hi:[0,0,0]
	v_mfma_scale_f32_16x16x128_f8f6f4 v[66:69], v[200:207], v[216:223], v[66:69], v188, v188 op_sel_hi:[0,0,0]
	v_mfma_scale_f32_16x16x128_f8f6f4 v[34:37], v[208:215], v[216:223], v[34:37], v188, v188 op_sel_hi:[0,0,0]
	v_mfma_scale_f32_16x16x128_f8f6f4 v[38:41], v[2:9], v[216:223], v[38:41], v188, v188 op_sel_hi:[0,0,0]
	v_mfma_scale_f32_16x16x128_f8f6f4 v[30:33], v[2:9], v[224:231], v[30:33], v188, v188 op_sel_hi:[0,0,0]
	v_mfma_scale_f32_16x16x128_f8f6f4 v[26:29], v[208:215], v[224:231], v[26:29], v188, v188 op_sel_hi:[0,0,0]
	v_mfma_scale_f32_16x16x128_f8f6f4 v[58:61], v[200:207], v[224:231], v[58:61], v188, v188 op_sel_hi:[0,0,0]
	v_mfma_scale_f32_16x16x128_f8f6f4 v[62:65], v[192:199], v[224:231], v[62:65], v188, v188 op_sel_hi:[0,0,0]
	s_setprio 0
	s_setprio 1
	v_mfma_scale_f32_16x16x128_f8f6f4 v[54:57], v[192:199], v[232:239], v[54:57], v188, v188 op_sel_hi:[0,0,0]
	v_mfma_scale_f32_16x16x128_f8f6f4 v[50:53], v[200:207], v[232:239], v[50:53], v188, v188 op_sel_hi:[0,0,0]
	v_mfma_scale_f32_16x16x128_f8f6f4 v[18:21], v[208:215], v[232:239], v[18:21], v188, v188 op_sel_hi:[0,0,0]
	v_mfma_scale_f32_16x16x128_f8f6f4 v[22:25], v[2:9], v[232:239], v[22:25], v188, v188 op_sel_hi:[0,0,0]
	v_mfma_scale_f32_16x16x128_f8f6f4 v[14:17], v[2:9], v[240:247], v[14:17], v188, v188 op_sel_hi:[0,0,0]
	v_mfma_scale_f32_16x16x128_f8f6f4 v[10:13], v[208:215], v[240:247], v[10:13], v188, v188 op_sel_hi:[0,0,0]
	v_mfma_scale_f32_16x16x128_f8f6f4 v[42:45], v[200:207], v[240:247], v[42:45], v188, v188 op_sel_hi:[0,0,0]
	v_mfma_scale_f32_16x16x128_f8f6f4 v[46:49], v[192:199], v[240:247], v[46:49], v188, v188 op_sel_hi:[0,0,0]
	s_setprio 0
	s_barrier
	s_add_i32 s26, s84, 2
	s_add_u32 s36, s36, 0x100
	s_addc_u32 s37, s37, 0
	s_add_u32 s40, s40, 0x100
	s_addc_u32 s41, s41, 0
	s_cmp_ge_i32 s84, s82
	s_cbranch_scc1 .LBB0_1036
	s_mov_b32 s84, s26
	s_cmp_eq_u32 s82, s84
	s_cselect_b64 s[26:27], -1, 0
	s_cmp_lg_u32 s82, s84
	s_cbranch_scc0 .LBB0_1033
	s_branch .LBB0_1034
